# K-loops: the two s_nop 15 between the fragment reads and their lgkmcnt wait removed (all six generated loops)
# baseline (speedup 1.0000x reference)
.LBB0_165:
	s_add_u32 s16, s14, 0xfff80080
	s_addc_u32 s17, s15, -1
	s_cmp_eq_u32 s64, 28
	s_cselect_b32 s19, s1, s17
	s_cselect_b32 s18, s4, s16
	s_cselect_b32 s17, s11, s21
	s_cselect_b32 s16, s13, s20
	s_and_b64 vcc, exec, s[36:37]
	s_cbranch_vccz .Lk64_trail_p1
	s_sub_u32 vcc_lo, s20, 0x80
	s_subb_u32 vcc_hi, s21, 0
	s_add_i32 m0, s23, 0x18000
	s_nop 0
	global_load_lds_dwordx4 v130, vcc
	s_add_i32 m0, s23, 0x1a000
	s_nop 0
	global_load_lds_dwordx4 v134, vcc
	s_add_u32 vcc_lo, vcc_lo, 0x20000
	s_addc_u32 vcc_hi, vcc_hi, 0
	s_add_i32 m0, s23, 0x19000
	s_nop 0
	global_load_lds_dwordx4 v130, vcc
	s_add_i32 m0, s23, 0x1b000
	s_nop 0
	global_load_lds_dwordx4 v134, vcc
	s_add_u32 vcc_lo, vcc_lo, 0x60000
	s_addc_u32 vcc_hi, vcc_hi, 0
	s_add_i32 m0, s23, 0x1c000
	s_nop 0
	global_load_lds_dwordx4 v130, vcc
	s_add_i32 m0, s23, 0x1e000
	s_nop 0
	global_load_lds_dwordx4 v134, vcc
	s_add_u32 vcc_lo, vcc_lo, 0x20000
	s_addc_u32 vcc_hi, vcc_hi, 0
	s_add_i32 m0, s23, 0x1d000
	s_nop 0
	global_load_lds_dwordx4 v130, vcc
	s_add_i32 m0, s23, 0x1f000
	s_nop 0
	global_load_lds_dwordx4 v134, vcc
	ds_read_b128 v[148:151], v168 offset:0
	ds_read_b128 v[152:155], v168 offset:1024
	ds_read_b128 v[156:159], v168 offset:2048
	ds_read_b128 v[172:175], v168 offset:3072
	ds_read_b128 v[176:179], v169 offset:0
	ds_read_b128 v[180:183], v169 offset:1024
	ds_read_b128 v[184:187], v169 offset:2048
	ds_read_b128 v[188:191], v169 offset:3072
	ds_read_b128 v[192:195], v170 offset:0
	ds_read_b128 v[196:199], v170 offset:1024
	ds_read_b128 v[200:203], v170 offset:2048
	ds_read_b128 v[204:207], v170 offset:3072
	ds_read_b128 v[208:211], v170 offset:4096
	ds_read_b128 v[212:215], v170 offset:5120
	ds_read_b128 v[216:219], v170 offset:6144
	ds_read_b128 v[220:223], v170 offset:7168
	ds_read_b128 v[142:145], v170 offset:16384
	ds_read_b128 v[224:227], v170 offset:17408
	ds_read_b128 v[228:231], v170 offset:18432
	ds_read_b128 v[232:235], v170 offset:19456
	ds_read_b128 v[236:239], v170 offset:20480
	ds_read_b128 v[240:243], v170 offset:21504
	ds_read_b128 v[244:247], v170 offset:22528
	ds_read_b128 v[248:251], v170 offset:23552
	s_waitcnt lgkmcnt(0)
	s_barrier
	s_setprio 1
	v_mfma_f32_16x16x32_bf16 v[124:127], v[148:151], v[192:195], v[124:127]
	v_mfma_f32_16x16x32_bf16 v[120:123], v[156:159], v[192:195], v[120:123]
	v_mfma_f32_16x16x32_bf16 v[116:119], v[148:151], v[200:203], v[116:119]
	v_mfma_f32_16x16x32_bf16 v[112:115], v[156:159], v[200:203], v[112:115]
	v_mfma_f32_16x16x32_bf16 v[100:103], v[148:151], v[208:211], v[100:103]
	v_mfma_f32_16x16x32_bf16 v[96:99], v[156:159], v[208:211], v[96:99]
	v_mfma_f32_16x16x32_bf16 v[84:87], v[148:151], v[216:219], v[84:87]
	v_mfma_f32_16x16x32_bf16 v[80:83], v[156:159], v[216:219], v[80:83]
	v_mfma_f32_16x16x32_bf16 v[124:127], v[152:155], v[196:199], v[124:127]
	v_mfma_f32_16x16x32_bf16 v[120:123], v[172:175], v[196:199], v[120:123]
	v_mfma_f32_16x16x32_bf16 v[116:119], v[152:155], v[204:207], v[116:119]
	v_mfma_f32_16x16x32_bf16 v[112:115], v[172:175], v[204:207], v[112:115]
	v_mfma_f32_16x16x32_bf16 v[100:103], v[152:155], v[212:215], v[100:103]
	v_mfma_f32_16x16x32_bf16 v[96:99], v[172:175], v[212:215], v[96:99]
	v_mfma_f32_16x16x32_bf16 v[84:87], v[152:155], v[220:223], v[84:87]
	v_mfma_f32_16x16x32_bf16 v[80:83], v[172:175], v[220:223], v[80:83]
	s_setprio 0
	s_setprio 1
	v_mfma_f32_16x16x32_bf16 v[108:111], v[176:179], v[192:195], v[108:111]
	v_mfma_f32_16x16x32_bf16 v[104:107], v[184:187], v[192:195], v[104:107]
	v_mfma_f32_16x16x32_bf16 v[92:95], v[176:179], v[200:203], v[92:95]
	v_mfma_f32_16x16x32_bf16 v[88:91], v[184:187], v[200:203], v[88:91]
	v_mfma_f32_16x16x32_bf16 v[76:79], v[176:179], v[208:211], v[76:79]
	v_mfma_f32_16x16x32_bf16 v[72:75], v[184:187], v[208:211], v[72:75]
	v_mfma_f32_16x16x32_bf16 v[68:71], v[176:179], v[216:219], v[68:71]
	v_mfma_f32_16x16x32_bf16 v[64:67], v[184:187], v[216:219], v[64:67]
	v_mfma_f32_16x16x32_bf16 v[108:111], v[180:183], v[196:199], v[108:111]
	v_mfma_f32_16x16x32_bf16 v[104:107], v[188:191], v[196:199], v[104:107]
	v_mfma_f32_16x16x32_bf16 v[92:95], v[180:183], v[204:207], v[92:95]
	v_mfma_f32_16x16x32_bf16 v[88:91], v[188:191], v[204:207], v[88:91]
	v_mfma_f32_16x16x32_bf16 v[76:79], v[180:183], v[212:215], v[76:79]
	v_mfma_f32_16x16x32_bf16 v[72:75], v[188:191], v[212:215], v[72:75]
	v_mfma_f32_16x16x32_bf16 v[68:71], v[180:183], v[220:223], v[68:71]
	v_mfma_f32_16x16x32_bf16 v[64:67], v[188:191], v[220:223], v[64:67]
	s_setprio 0
	s_setprio 1
	v_mfma_f32_16x16x32_bf16 v[60:63], v[148:151], v[142:145], v[60:63]
	v_mfma_f32_16x16x32_bf16 v[56:59], v[156:159], v[142:145], v[56:59]
	v_mfma_f32_16x16x32_bf16 v[52:55], v[148:151], v[228:231], v[52:55]
	v_mfma_f32_16x16x32_bf16 v[48:51], v[156:159], v[228:231], v[48:51]
	v_mfma_f32_16x16x32_bf16 v[36:39], v[148:151], v[236:239], v[36:39]
	v_mfma_f32_16x16x32_bf16 v[32:35], v[156:159], v[236:239], v[32:35]
	v_mfma_f32_16x16x32_bf16 v[20:23], v[148:151], v[244:247], v[20:23]
	v_mfma_f32_16x16x32_bf16 v[16:19], v[156:159], v[244:247], v[16:19]
	v_mfma_f32_16x16x32_bf16 v[60:63], v[152:155], v[224:227], v[60:63]
	v_mfma_f32_16x16x32_bf16 v[56:59], v[172:175], v[224:227], v[56:59]
	v_mfma_f32_16x16x32_bf16 v[52:55], v[152:155], v[232:235], v[52:55]
	v_mfma_f32_16x16x32_bf16 v[48:51], v[172:175], v[232:235], v[48:51]
	v_mfma_f32_16x16x32_bf16 v[36:39], v[152:155], v[240:243], v[36:39]
	v_mfma_f32_16x16x32_bf16 v[32:35], v[172:175], v[240:243], v[32:35]
	v_mfma_f32_16x16x32_bf16 v[20:23], v[152:155], v[248:251], v[20:23]
	v_mfma_f32_16x16x32_bf16 v[16:19], v[172:175], v[248:251], v[16:19]
	s_setprio 0
	s_setprio 1
	v_mfma_f32_16x16x32_bf16 v[44:47], v[176:179], v[142:145], v[44:47]
	v_mfma_f32_16x16x32_bf16 v[40:43], v[184:187], v[142:145], v[40:43]
	v_mfma_f32_16x16x32_bf16 v[28:31], v[176:179], v[228:231], v[28:31]
	v_mfma_f32_16x16x32_bf16 v[24:27], v[184:187], v[228:231], v[24:27]
	v_mfma_f32_16x16x32_bf16 v[12:15], v[176:179], v[236:239], v[12:15]
	v_mfma_f32_16x16x32_bf16 v[8:11], v[184:187], v[236:239], v[8:11]
	v_mfma_f32_16x16x32_bf16 v[4:7], v[176:179], v[244:247], v[4:7]
	v_mfma_f32_16x16x32_bf16 v[0:3], v[184:187], v[244:247], v[0:3]
	v_mfma_f32_16x16x32_bf16 v[44:47], v[180:183], v[224:227], v[44:47]
	v_mfma_f32_16x16x32_bf16 v[40:43], v[188:191], v[224:227], v[40:43]
	v_mfma_f32_16x16x32_bf16 v[28:31], v[180:183], v[232:235], v[28:31]
	v_mfma_f32_16x16x32_bf16 v[24:27], v[188:191], v[232:235], v[24:27]
	v_mfma_f32_16x16x32_bf16 v[12:15], v[180:183], v[240:243], v[12:15]
	v_mfma_f32_16x16x32_bf16 v[8:11], v[188:191], v[240:243], v[8:11]
	v_mfma_f32_16x16x32_bf16 v[4:7], v[180:183], v[248:251], v[4:7]
	v_mfma_f32_16x16x32_bf16 v[0:3], v[188:191], v[248:251], v[0:3]
	s_setprio 0
	s_waitcnt vmcnt(0)
	s_barrier
	s_add_u32 vcc_lo, s16, 0x0
	s_addc_u32 vcc_hi, s17, 0
	s_add_i32 m0, s23, 0x10000
	s_nop 0
	global_load_lds_dwordx4 v130, vcc
	s_add_i32 m0, s23, 0x12000
	s_nop 0
	global_load_lds_dwordx4 v134, vcc
	s_add_u32 vcc_lo, vcc_lo, 0x20000
	s_addc_u32 vcc_hi, vcc_hi, 0
	s_add_i32 m0, s23, 0x11000
	s_nop 0
	global_load_lds_dwordx4 v130, vcc
	s_add_i32 m0, s23, 0x13000
	s_nop 0
	global_load_lds_dwordx4 v134, vcc
	s_add_u32 vcc_lo, vcc_lo, 0x60000
	s_addc_u32 vcc_hi, vcc_hi, 0
	s_add_i32 m0, s23, 0x14000
	s_nop 0
	global_load_lds_dwordx4 v130, vcc
	s_add_i32 m0, s23, 0x16000
	s_nop 0
	global_load_lds_dwordx4 v134, vcc
	s_add_u32 vcc_lo, vcc_lo, 0x20000
	s_addc_u32 vcc_hi, vcc_hi, 0
	s_add_i32 m0, s23, 0x15000
	s_nop 0
	global_load_lds_dwordx4 v130, vcc
	s_add_i32 m0, s23, 0x17000
	s_nop 0
	global_load_lds_dwordx4 v134, vcc
	ds_read_b128 v[148:151], v168 offset:32768
	ds_read_b128 v[152:155], v168 offset:33792
	ds_read_b128 v[156:159], v168 offset:34816
	ds_read_b128 v[172:175], v168 offset:35840
	ds_read_b128 v[176:179], v169 offset:32768
	ds_read_b128 v[180:183], v169 offset:33792
	ds_read_b128 v[184:187], v169 offset:34816
	ds_read_b128 v[188:191], v169 offset:35840
	ds_read_b128 v[192:195], v170 offset:32768
	ds_read_b128 v[196:199], v170 offset:33792
	ds_read_b128 v[200:203], v170 offset:34816
	ds_read_b128 v[204:207], v170 offset:35840
	ds_read_b128 v[208:211], v170 offset:36864
	ds_read_b128 v[212:215], v170 offset:37888
	ds_read_b128 v[216:219], v170 offset:38912
	ds_read_b128 v[220:223], v170 offset:39936
	ds_read_b128 v[142:145], v170 offset:49152
	ds_read_b128 v[224:227], v170 offset:50176
	ds_read_b128 v[228:231], v170 offset:51200
	ds_read_b128 v[232:235], v170 offset:52224
	ds_read_b128 v[236:239], v170 offset:53248
	ds_read_b128 v[240:243], v170 offset:54272
	ds_read_b128 v[244:247], v170 offset:55296
	ds_read_b128 v[248:251], v170 offset:56320
	s_waitcnt lgkmcnt(0)
	s_barrier
	s_setprio 1
	v_mfma_f32_16x16x32_bf16 v[124:127], v[148:151], v[192:195], v[124:127]
	v_mfma_f32_16x16x32_bf16 v[120:123], v[156:159], v[192:195], v[120:123]
	v_mfma_f32_16x16x32_bf16 v[116:119], v[148:151], v[200:203], v[116:119]
	v_mfma_f32_16x16x32_bf16 v[112:115], v[156:159], v[200:203], v[112:115]
	v_mfma_f32_16x16x32_bf16 v[100:103], v[148:151], v[208:211], v[100:103]
	v_mfma_f32_16x16x32_bf16 v[96:99], v[156:159], v[208:211], v[96:99]
	v_mfma_f32_16x16x32_bf16 v[84:87], v[148:151], v[216:219], v[84:87]
	v_mfma_f32_16x16x32_bf16 v[80:83], v[156:159], v[216:219], v[80:83]
	v_mfma_f32_16x16x32_bf16 v[124:127], v[152:155], v[196:199], v[124:127]
	v_mfma_f32_16x16x32_bf16 v[120:123], v[172:175], v[196:199], v[120:123]
	v_mfma_f32_16x16x32_bf16 v[116:119], v[152:155], v[204:207], v[116:119]
	v_mfma_f32_16x16x32_bf16 v[112:115], v[172:175], v[204:207], v[112:115]
	v_mfma_f32_16x16x32_bf16 v[100:103], v[152:155], v[212:215], v[100:103]
	v_mfma_f32_16x16x32_bf16 v[96:99], v[172:175], v[212:215], v[96:99]
	v_mfma_f32_16x16x32_bf16 v[84:87], v[152:155], v[220:223], v[84:87]
	v_mfma_f32_16x16x32_bf16 v[80:83], v[172:175], v[220:223], v[80:83]
	s_setprio 0
	s_setprio 1
	v_mfma_f32_16x16x32_bf16 v[108:111], v[176:179], v[192:195], v[108:111]
	v_mfma_f32_16x16x32_bf16 v[104:107], v[184:187], v[192:195], v[104:107]
	v_mfma_f32_16x16x32_bf16 v[92:95], v[176:179], v[200:203], v[92:95]
	v_mfma_f32_16x16x32_bf16 v[88:91], v[184:187], v[200:203], v[88:91]
	v_mfma_f32_16x16x32_bf16 v[76:79], v[176:179], v[208:211], v[76:79]
	v_mfma_f32_16x16x32_bf16 v[72:75], v[184:187], v[208:211], v[72:75]
	v_mfma_f32_16x16x32_bf16 v[68:71], v[176:179], v[216:219], v[68:71]
	v_mfma_f32_16x16x32_bf16 v[64:67], v[184:187], v[216:219], v[64:67]
	v_mfma_f32_16x16x32_bf16 v[108:111], v[180:183], v[196:199], v[108:111]
	v_mfma_f32_16x16x32_bf16 v[104:107], v[188:191], v[196:199], v[104:107]
	v_mfma_f32_16x16x32_bf16 v[92:95], v[180:183], v[204:207], v[92:95]
	v_mfma_f32_16x16x32_bf16 v[88:91], v[188:191], v[204:207], v[88:91]
	v_mfma_f32_16x16x32_bf16 v[76:79], v[180:183], v[212:215], v[76:79]
	v_mfma_f32_16x16x32_bf16 v[72:75], v[188:191], v[212:215], v[72:75]
	v_mfma_f32_16x16x32_bf16 v[68:71], v[180:183], v[220:223], v[68:71]
	v_mfma_f32_16x16x32_bf16 v[64:67], v[188:191], v[220:223], v[64:67]
	s_setprio 0
	s_setprio 1
	v_mfma_f32_16x16x32_bf16 v[60:63], v[148:151], v[142:145], v[60:63]
	v_mfma_f32_16x16x32_bf16 v[56:59], v[156:159], v[142:145], v[56:59]
	v_mfma_f32_16x16x32_bf16 v[52:55], v[148:151], v[228:231], v[52:55]
	v_mfma_f32_16x16x32_bf16 v[48:51], v[156:159], v[228:231], v[48:51]
	v_mfma_f32_16x16x32_bf16 v[36:39], v[148:151], v[236:239], v[36:39]
	v_mfma_f32_16x16x32_bf16 v[32:35], v[156:159], v[236:239], v[32:35]
	v_mfma_f32_16x16x32_bf16 v[20:23], v[148:151], v[244:247], v[20:23]
	v_mfma_f32_16x16x32_bf16 v[16:19], v[156:159], v[244:247], v[16:19]
	v_mfma_f32_16x16x32_bf16 v[60:63], v[152:155], v[224:227], v[60:63]
	v_mfma_f32_16x16x32_bf16 v[56:59], v[172:175], v[224:227], v[56:59]
	v_mfma_f32_16x16x32_bf16 v[52:55], v[152:155], v[232:235], v[52:55]
	v_mfma_f32_16x16x32_bf16 v[48:51], v[172:175], v[232:235], v[48:51]
	v_mfma_f32_16x16x32_bf16 v[36:39], v[152:155], v[240:243], v[36:39]
	v_mfma_f32_16x16x32_bf16 v[32:35], v[172:175], v[240:243], v[32:35]
	v_mfma_f32_16x16x32_bf16 v[20:23], v[152:155], v[248:251], v[20:23]
	v_mfma_f32_16x16x32_bf16 v[16:19], v[172:175], v[248:251], v[16:19]
	s_setprio 0
	s_setprio 1
	v_mfma_f32_16x16x32_bf16 v[44:47], v[176:179], v[142:145], v[44:47]
	v_mfma_f32_16x16x32_bf16 v[40:43], v[184:187], v[142:145], v[40:43]
	v_mfma_f32_16x16x32_bf16 v[28:31], v[176:179], v[228:231], v[28:31]
	v_mfma_f32_16x16x32_bf16 v[24:27], v[184:187], v[228:231], v[24:27]
	v_mfma_f32_16x16x32_bf16 v[12:15], v[176:179], v[236:239], v[12:15]
	v_mfma_f32_16x16x32_bf16 v[8:11], v[184:187], v[236:239], v[8:11]
	v_mfma_f32_16x16x32_bf16 v[4:7], v[176:179], v[244:247], v[4:7]
	v_mfma_f32_16x16x32_bf16 v[0:3], v[184:187], v[244:247], v[0:3]
	v_mfma_f32_16x16x32_bf16 v[44:47], v[180:183], v[224:227], v[44:47]
	v_mfma_f32_16x16x32_bf16 v[40:43], v[188:191], v[224:227], v[40:43]
	v_mfma_f32_16x16x32_bf16 v[28:31], v[180:183], v[232:235], v[28:31]
	v_mfma_f32_16x16x32_bf16 v[24:27], v[188:191], v[232:235], v[24:27]
	v_mfma_f32_16x16x32_bf16 v[12:15], v[180:183], v[240:243], v[12:15]
	v_mfma_f32_16x16x32_bf16 v[8:11], v[188:191], v[240:243], v[8:11]
	v_mfma_f32_16x16x32_bf16 v[4:7], v[180:183], v[248:251], v[4:7]
	v_mfma_f32_16x16x32_bf16 v[0:3], v[188:191], v[248:251], v[0:3]
	s_setprio 0
	s_waitcnt vmcnt(0)
	s_barrier
	s_add_i32 s64, s64, 2
	s_add_u32 s14, s14, 0x100
	s_addc_u32 s15, s15, 0
	s_add_u32 s20, s20, 0x100
	s_addc_u32 s21, s21, 0
	s_cmp_gt_u32 s64, 29
	s_cbranch_scc0 .LBB0_165
	s_branch .Lk64_done_p1
.Lk64_trail_p1:
	s_sub_u32 vcc_lo, s14, 0x80000
	s_subb_u32 vcc_hi, s15, 0
	s_add_i32 m0, s23, 0xa000
	s_nop 0
	global_load_lds_dwordx4 v132, vcc
	s_add_u32 vcc_lo, vcc_lo, 0x20000
	s_addc_u32 vcc_hi, vcc_hi, 0
	s_add_i32 m0, s23, 0x9000
	s_nop 0
	global_load_lds_dwordx4 v128, vcc
	s_add_u32 vcc_lo, vcc_lo, 0x60000
	s_addc_u32 vcc_hi, vcc_hi, 0
	s_add_i32 m0, s23, 0xe000
	s_nop 0
	global_load_lds_dwordx4 v132, vcc
	s_add_u32 vcc_lo, vcc_lo, 0x20000
	s_addc_u32 vcc_hi, vcc_hi, 0
	s_add_i32 m0, s23, 0xd000
	s_nop 0
	global_load_lds_dwordx4 v128, vcc
	s_add_u32 vcc_lo, s18, 0x0
	s_addc_u32 vcc_hi, s19, 0
	s_mov_b32 m0, s23
	s_nop 0
	global_load_lds_dwordx4 v128, vcc
	s_sub_u32 vcc_lo, vcc_lo, 0x20000
	s_subb_u32 vcc_hi, vcc_hi, 0
	s_sub_i32 m0, s23, 0x1000
	s_nop 0
	global_load_lds_dwordx4 v128, vcc
	s_add_u32 vcc_lo, vcc_lo, 0xa0000
	s_addc_u32 vcc_hi, vcc_hi, 0
	s_add_i32 m0, s23, 0x4000
	s_nop 0
	global_load_lds_dwordx4 v128, vcc
	s_sub_u32 vcc_lo, vcc_lo, 0x20000
	s_subb_u32 vcc_hi, vcc_hi, 0
	s_add_i32 m0, s23, 0x3000
	s_nop 0
	global_load_lds_dwordx4 v128, vcc
	ds_read_b128 v[148:151], v168 offset:0
	ds_read_b128 v[152:155], v168 offset:1024
	ds_read_b128 v[156:159], v168 offset:2048
	ds_read_b128 v[172:175], v168 offset:3072
	ds_read_b128 v[176:179], v169 offset:0
	ds_read_b128 v[180:183], v169 offset:1024
	ds_read_b128 v[184:187], v169 offset:2048
	ds_read_b128 v[188:191], v169 offset:3072
	ds_read_b128 v[192:195], v170 offset:0
	ds_read_b128 v[196:199], v170 offset:1024
	ds_read_b128 v[200:203], v170 offset:2048
	ds_read_b128 v[204:207], v170 offset:3072
	ds_read_b128 v[208:211], v170 offset:4096
	ds_read_b128 v[212:215], v170 offset:5120
	ds_read_b128 v[216:219], v170 offset:6144
	ds_read_b128 v[220:223], v170 offset:7168
	ds_read_b128 v[142:145], v170 offset:16384
	ds_read_b128 v[224:227], v170 offset:17408
	ds_read_b128 v[228:231], v170 offset:18432
	ds_read_b128 v[232:235], v170 offset:19456
	ds_read_b128 v[236:239], v170 offset:20480
	ds_read_b128 v[240:243], v170 offset:21504
	ds_read_b128 v[244:247], v170 offset:22528
	ds_read_b128 v[248:251], v170 offset:23552
	s_waitcnt lgkmcnt(0)
	s_barrier
	s_setprio 1
	v_mfma_f32_16x16x32_bf16 v[124:127], v[148:151], v[192:195], v[124:127]
	v_mfma_f32_16x16x32_bf16 v[120:123], v[156:159], v[192:195], v[120:123]
	v_mfma_f32_16x16x32_bf16 v[116:119], v[148:151], v[200:203], v[116:119]
	v_mfma_f32_16x16x32_bf16 v[112:115], v[156:159], v[200:203], v[112:115]
	v_mfma_f32_16x16x32_bf16 v[100:103], v[148:151], v[208:211], v[100:103]
	v_mfma_f32_16x16x32_bf16 v[96:99], v[156:159], v[208:211], v[96:99]
	v_mfma_f32_16x16x32_bf16 v[84:87], v[148:151], v[216:219], v[84:87]
	v_mfma_f32_16x16x32_bf16 v[80:83], v[156:159], v[216:219], v[80:83]
	v_mfma_f32_16x16x32_bf16 v[124:127], v[152:155], v[196:199], v[124:127]
	v_mfma_f32_16x16x32_bf16 v[120:123], v[172:175], v[196:199], v[120:123]
	v_mfma_f32_16x16x32_bf16 v[116:119], v[152:155], v[204:207], v[116:119]
	v_mfma_f32_16x16x32_bf16 v[112:115], v[172:175], v[204:207], v[112:115]
	v_mfma_f32_16x16x32_bf16 v[100:103], v[152:155], v[212:215], v[100:103]
	v_mfma_f32_16x16x32_bf16 v[96:99], v[172:175], v[212:215], v[96:99]
	v_mfma_f32_16x16x32_bf16 v[84:87], v[152:155], v[220:223], v[84:87]
	v_mfma_f32_16x16x32_bf16 v[80:83], v[172:175], v[220:223], v[80:83]
	s_setprio 0
	s_setprio 1
	v_mfma_f32_16x16x32_bf16 v[108:111], v[176:179], v[192:195], v[108:111]
	v_mfma_f32_16x16x32_bf16 v[104:107], v[184:187], v[192:195], v[104:107]
	v_mfma_f32_16x16x32_bf16 v[92:95], v[176:179], v[200:203], v[92:95]
	v_mfma_f32_16x16x32_bf16 v[88:91], v[184:187], v[200:203], v[88:91]
	v_mfma_f32_16x16x32_bf16 v[76:79], v[176:179], v[208:211], v[76:79]
	v_mfma_f32_16x16x32_bf16 v[72:75], v[184:187], v[208:211], v[72:75]
	v_mfma_f32_16x16x32_bf16 v[68:71], v[176:179], v[216:219], v[68:71]
	v_mfma_f32_16x16x32_bf16 v[64:67], v[184:187], v[216:219], v[64:67]
	v_mfma_f32_16x16x32_bf16 v[108:111], v[180:183], v[196:199], v[108:111]
	v_mfma_f32_16x16x32_bf16 v[104:107], v[188:191], v[196:199], v[104:107]
	v_mfma_f32_16x16x32_bf16 v[92:95], v[180:183], v[204:207], v[92:95]
	v_mfma_f32_16x16x32_bf16 v[88:91], v[188:191], v[204:207], v[88:91]
	v_mfma_f32_16x16x32_bf16 v[76:79], v[180:183], v[212:215], v[76:79]
	v_mfma_f32_16x16x32_bf16 v[72:75], v[188:191], v[212:215], v[72:75]
	v_mfma_f32_16x16x32_bf16 v[68:71], v[180:183], v[220:223], v[68:71]
	v_mfma_f32_16x16x32_bf16 v[64:67], v[188:191], v[220:223], v[64:67]
	s_setprio 0
	s_setprio 1
	v_mfma_f32_16x16x32_bf16 v[60:63], v[148:151], v[142:145], v[60:63]
	v_mfma_f32_16x16x32_bf16 v[56:59], v[156:159], v[142:145], v[56:59]
	v_mfma_f32_16x16x32_bf16 v[52:55], v[148:151], v[228:231], v[52:55]
	v_mfma_f32_16x16x32_bf16 v[48:51], v[156:159], v[228:231], v[48:51]
	v_mfma_f32_16x16x32_bf16 v[36:39], v[148:151], v[236:239], v[36:39]
	v_mfma_f32_16x16x32_bf16 v[32:35], v[156:159], v[236:239], v[32:35]
	v_mfma_f32_16x16x32_bf16 v[20:23], v[148:151], v[244:247], v[20:23]
	v_mfma_f32_16x16x32_bf16 v[16:19], v[156:159], v[244:247], v[16:19]
	v_mfma_f32_16x16x32_bf16 v[60:63], v[152:155], v[224:227], v[60:63]
	v_mfma_f32_16x16x32_bf16 v[56:59], v[172:175], v[224:227], v[56:59]
	v_mfma_f32_16x16x32_bf16 v[52:55], v[152:155], v[232:235], v[52:55]
	v_mfma_f32_16x16x32_bf16 v[48:51], v[172:175], v[232:235], v[48:51]
	v_mfma_f32_16x16x32_bf16 v[36:39], v[152:155], v[240:243], v[36:39]
	v_mfma_f32_16x16x32_bf16 v[32:35], v[172:175], v[240:243], v[32:35]
	v_mfma_f32_16x16x32_bf16 v[20:23], v[152:155], v[248:251], v[20:23]
	v_mfma_f32_16x16x32_bf16 v[16:19], v[172:175], v[248:251], v[16:19]
	s_setprio 0
	s_setprio 1
	v_mfma_f32_16x16x32_bf16 v[44:47], v[176:179], v[142:145], v[44:47]
	v_mfma_f32_16x16x32_bf16 v[40:43], v[184:187], v[142:145], v[40:43]
	v_mfma_f32_16x16x32_bf16 v[28:31], v[176:179], v[228:231], v[28:31]
	v_mfma_f32_16x16x32_bf16 v[24:27], v[184:187], v[228:231], v[24:27]
	v_mfma_f32_16x16x32_bf16 v[12:15], v[176:179], v[236:239], v[12:15]
	v_mfma_f32_16x16x32_bf16 v[8:11], v[184:187], v[236:239], v[8:11]
	v_mfma_f32_16x16x32_bf16 v[4:7], v[176:179], v[244:247], v[4:7]
	v_mfma_f32_16x16x32_bf16 v[0:3], v[184:187], v[244:247], v[0:3]
	v_mfma_f32_16x16x32_bf16 v[44:47], v[180:183], v[224:227], v[44:47]
	v_mfma_f32_16x16x32_bf16 v[40:43], v[188:191], v[224:227], v[40:43]
	v_mfma_f32_16x16x32_bf16 v[28:31], v[180:183], v[232:235], v[28:31]
	v_mfma_f32_16x16x32_bf16 v[24:27], v[188:191], v[232:235], v[24:27]
	v_mfma_f32_16x16x32_bf16 v[12:15], v[180:183], v[240:243], v[12:15]
	v_mfma_f32_16x16x32_bf16 v[8:11], v[188:191], v[240:243], v[8:11]
	v_mfma_f32_16x16x32_bf16 v[4:7], v[180:183], v[248:251], v[4:7]
	v_mfma_f32_16x16x32_bf16 v[0:3], v[188:191], v[248:251], v[0:3]
	s_setprio 0
	s_waitcnt vmcnt(0)
	s_barrier
	s_add_u32 vcc_lo, s18, 0x0
	s_addc_u32 vcc_hi, s19, 0
	s_add_i32 m0, s23, 0x2000
	s_nop 0
	global_load_lds_dwordx4 v132, vcc
	s_add_u32 vcc_lo, vcc_lo, 0x20000
	s_addc_u32 vcc_hi, vcc_hi, 0
	s_add_i32 m0, s23, 0x1000
	s_nop 0
	global_load_lds_dwordx4 v128, vcc
	s_add_u32 vcc_lo, vcc_lo, 0x60000
	s_addc_u32 vcc_hi, vcc_hi, 0
	s_add_i32 m0, s23, 0x6000
	s_nop 0
	global_load_lds_dwordx4 v132, vcc
	s_add_u32 vcc_lo, vcc_lo, 0x20000
	s_addc_u32 vcc_hi, vcc_hi, 0
	s_add_i32 m0, s23, 0x5000
	s_nop 0
	global_load_lds_dwordx4 v128, vcc
	s_add_u32 vcc_lo, s18, 0x80
	s_addc_u32 vcc_hi, s19, 0
	s_add_i32 m0, s23, 0x8000
	s_nop 0
	global_load_lds_dwordx4 v128, vcc
	s_sub_u32 vcc_lo, vcc_lo, 0x20000
	s_subb_u32 vcc_hi, vcc_hi, 0
	s_add_i32 m0, s23, 0x7000
	s_nop 0
	global_load_lds_dwordx4 v128, vcc
	s_add_u32 vcc_lo, vcc_lo, 0xa0000
	s_addc_u32 vcc_hi, vcc_hi, 0
	s_add_i32 m0, s23, 0xc000
	s_nop 0
	global_load_lds_dwordx4 v128, vcc
	s_sub_u32 vcc_lo, vcc_lo, 0x20000
	s_subb_u32 vcc_hi, vcc_hi, 0
	s_add_i32 m0, s23, 0xb000
	s_nop 0
	global_load_lds_dwordx4 v128, vcc
	ds_read_b128 v[148:151], v168 offset:32768
	ds_read_b128 v[152:155], v168 offset:33792
	ds_read_b128 v[156:159], v168 offset:34816
	ds_read_b128 v[172:175], v168 offset:35840
	ds_read_b128 v[176:179], v169 offset:32768
	ds_read_b128 v[180:183], v169 offset:33792
	ds_read_b128 v[184:187], v169 offset:34816
	ds_read_b128 v[188:191], v169 offset:35840
	ds_read_b128 v[192:195], v170 offset:32768
	ds_read_b128 v[196:199], v170 offset:33792
	ds_read_b128 v[200:203], v170 offset:34816
	ds_read_b128 v[204:207], v170 offset:35840
	ds_read_b128 v[208:211], v170 offset:36864
	ds_read_b128 v[212:215], v170 offset:37888
	ds_read_b128 v[216:219], v170 offset:38912
	ds_read_b128 v[220:223], v170 offset:39936
	ds_read_b128 v[142:145], v170 offset:49152
	ds_read_b128 v[224:227], v170 offset:50176
	ds_read_b128 v[228:231], v170 offset:51200
	ds_read_b128 v[232:235], v170 offset:52224
	ds_read_b128 v[236:239], v170 offset:53248
	ds_read_b128 v[240:243], v170 offset:54272
	ds_read_b128 v[244:247], v170 offset:55296
	ds_read_b128 v[248:251], v170 offset:56320
	s_waitcnt lgkmcnt(0)
	s_barrier
	s_setprio 1
	v_mfma_f32_16x16x32_bf16 v[124:127], v[148:151], v[192:195], v[124:127]
	v_mfma_f32_16x16x32_bf16 v[120:123], v[156:159], v[192:195], v[120:123]
	v_mfma_f32_16x16x32_bf16 v[116:119], v[148:151], v[200:203], v[116:119]
	v_mfma_f32_16x16x32_bf16 v[112:115], v[156:159], v[200:203], v[112:115]
	v_mfma_f32_16x16x32_bf16 v[100:103], v[148:151], v[208:211], v[100:103]
	v_mfma_f32_16x16x32_bf16 v[96:99], v[156:159], v[208:211], v[96:99]
	v_mfma_f32_16x16x32_bf16 v[84:87], v[148:151], v[216:219], v[84:87]
	v_mfma_f32_16x16x32_bf16 v[80:83], v[156:159], v[216:219], v[80:83]
	v_mfma_f32_16x16x32_bf16 v[124:127], v[152:155], v[196:199], v[124:127]
	v_mfma_f32_16x16x32_bf16 v[120:123], v[172:175], v[196:199], v[120:123]
	v_mfma_f32_16x16x32_bf16 v[116:119], v[152:155], v[204:207], v[116:119]
	v_mfma_f32_16x16x32_bf16 v[112:115], v[172:175], v[204:207], v[112:115]
	v_mfma_f32_16x16x32_bf16 v[100:103], v[152:155], v[212:215], v[100:103]
	v_mfma_f32_16x16x32_bf16 v[96:99], v[172:175], v[212:215], v[96:99]
	v_mfma_f32_16x16x32_bf16 v[84:87], v[152:155], v[220:223], v[84:87]
	v_mfma_f32_16x16x32_bf16 v[80:83], v[172:175], v[220:223], v[80:83]
	s_setprio 0
	s_setprio 1
	v_mfma_f32_16x16x32_bf16 v[108:111], v[176:179], v[192:195], v[108:111]
	v_mfma_f32_16x16x32_bf16 v[104:107], v[184:187], v[192:195], v[104:107]
	v_mfma_f32_16x16x32_bf16 v[92:95], v[176:179], v[200:203], v[92:95]
	v_mfma_f32_16x16x32_bf16 v[88:91], v[184:187], v[200:203], v[88:91]
	v_mfma_f32_16x16x32_bf16 v[76:79], v[176:179], v[208:211], v[76:79]
	v_mfma_f32_16x16x32_bf16 v[72:75], v[184:187], v[208:211], v[72:75]
	v_mfma_f32_16x16x32_bf16 v[68:71], v[176:179], v[216:219], v[68:71]
	v_mfma_f32_16x16x32_bf16 v[64:67], v[184:187], v[216:219], v[64:67]
	v_mfma_f32_16x16x32_bf16 v[108:111], v[180:183], v[196:199], v[108:111]
	v_mfma_f32_16x16x32_bf16 v[104:107], v[188:191], v[196:199], v[104:107]
	v_mfma_f32_16x16x32_bf16 v[92:95], v[180:183], v[204:207], v[92:95]
	v_mfma_f32_16x16x32_bf16 v[88:91], v[188:191], v[204:207], v[88:91]
	v_mfma_f32_16x16x32_bf16 v[76:79], v[180:183], v[212:215], v[76:79]
	v_mfma_f32_16x16x32_bf16 v[72:75], v[188:191], v[212:215], v[72:75]
	v_mfma_f32_16x16x32_bf16 v[68:71], v[180:183], v[220:223], v[68:71]
	v_mfma_f32_16x16x32_bf16 v[64:67], v[188:191], v[220:223], v[64:67]
	s_setprio 0
	s_setprio 1
	v_mfma_f32_16x16x32_bf16 v[60:63], v[148:151], v[142:145], v[60:63]
	v_mfma_f32_16x16x32_bf16 v[56:59], v[156:159], v[142:145], v[56:59]
	v_mfma_f32_16x16x32_bf16 v[52:55], v[148:151], v[228:231], v[52:55]
	v_mfma_f32_16x16x32_bf16 v[48:51], v[156:159], v[228:231], v[48:51]
	v_mfma_f32_16x16x32_bf16 v[36:39], v[148:151], v[236:239], v[36:39]
	v_mfma_f32_16x16x32_bf16 v[32:35], v[156:159], v[236:239], v[32:35]
	v_mfma_f32_16x16x32_bf16 v[20:23], v[148:151], v[244:247], v[20:23]
	v_mfma_f32_16x16x32_bf16 v[16:19], v[156:159], v[244:247], v[16:19]
	v_mfma_f32_16x16x32_bf16 v[60:63], v[152:155], v[224:227], v[60:63]
	v_mfma_f32_16x16x32_bf16 v[56:59], v[172:175], v[224:227], v[56:59]
	v_mfma_f32_16x16x32_bf16 v[52:55], v[152:155], v[232:235], v[52:55]
	v_mfma_f32_16x16x32_bf16 v[48:51], v[172:175], v[232:235], v[48:51]
	v_mfma_f32_16x16x32_bf16 v[36:39], v[152:155], v[240:243], v[36:39]
	v_mfma_f32_16x16x32_bf16 v[32:35], v[172:175], v[240:243], v[32:35]
	v_mfma_f32_16x16x32_bf16 v[20:23], v[152:155], v[248:251], v[20:23]
	v_mfma_f32_16x16x32_bf16 v[16:19], v[172:175], v[248:251], v[16:19]
	s_setprio 0
	s_setprio 1
	v_mfma_f32_16x16x32_bf16 v[44:47], v[176:179], v[142:145], v[44:47]
	v_mfma_f32_16x16x32_bf16 v[40:43], v[184:187], v[142:145], v[40:43]
	v_mfma_f32_16x16x32_bf16 v[28:31], v[176:179], v[228:231], v[28:31]
	v_mfma_f32_16x16x32_bf16 v[24:27], v[184:187], v[228:231], v[24:27]
	v_mfma_f32_16x16x32_bf16 v[12:15], v[176:179], v[236:239], v[12:15]
	v_mfma_f32_16x16x32_bf16 v[8:11], v[184:187], v[236:239], v[8:11]
	v_mfma_f32_16x16x32_bf16 v[4:7], v[176:179], v[244:247], v[4:7]
	v_mfma_f32_16x16x32_bf16 v[0:3], v[184:187], v[244:247], v[0:3]
	v_mfma_f32_16x16x32_bf16 v[44:47], v[180:183], v[224:227], v[44:47]
	v_mfma_f32_16x16x32_bf16 v[40:43], v[188:191], v[224:227], v[40:43]
	v_mfma_f32_16x16x32_bf16 v[28:31], v[180:183], v[232:235], v[28:31]
	v_mfma_f32_16x16x32_bf16 v[24:27], v[188:191], v[232:235], v[24:27]
	v_mfma_f32_16x16x32_bf16 v[12:15], v[180:183], v[240:243], v[12:15]
	v_mfma_f32_16x16x32_bf16 v[8:11], v[188:191], v[240:243], v[8:11]
	v_mfma_f32_16x16x32_bf16 v[4:7], v[180:183], v[248:251], v[4:7]
	v_mfma_f32_16x16x32_bf16 v[0:3], v[188:191], v[248:251], v[0:3]
	s_setprio 0
	s_waitcnt vmcnt(0)
	s_barrier
	s_add_i32 s64, s64, 2
	s_add_u32 s14, s14, 0x100
	s_addc_u32 s15, s15, 0
	s_add_u32 s20, s20, 0x100
	s_addc_u32 s21, s21, 0
	s_cmp_gt_u32 s64, 29
	s_cbranch_scc0 .LBB0_165

.LBB0_613:
	s_add_u32 s24, s22, 0xfffc0080
	s_addc_u32 s25, s23, -1
	s_cmp_eq_u32 s49, 12
	s_cselect_b32 s27, s13, s25
	s_cselect_b32 s26, s41, s24
	s_cselect_b32 s25, s11, s48
	s_cselect_b32 s24, s46, s47
	s_and_b64 vcc, exec, s[6:7]
	s_cbranch_vccz .Lk64_trail_glu
	s_sub_u32 vcc_lo, s47, 0x80
	s_subb_u32 vcc_hi, s48, 0
	s_add_i32 m0, s28, 0x18000
	s_nop 0
	global_load_lds_dwordx4 v132, vcc
	s_add_i32 m0, s28, 0x1a000
	s_nop 0
	global_load_lds_dwordx4 v128, vcc
	s_add_u32 vcc_lo, vcc_lo, 0x10000
	s_addc_u32 vcc_hi, vcc_hi, 0
	s_add_i32 m0, s28, 0x19000
	s_nop 0
	global_load_lds_dwordx4 v132, vcc
	s_add_i32 m0, s28, 0x1b000
	s_nop 0
	global_load_lds_dwordx4 v128, vcc
	s_add_u32 vcc_lo, vcc_lo, 0x30000
	s_addc_u32 vcc_hi, vcc_hi, 0
	s_add_i32 m0, s28, 0x1c000
	s_nop 0
	global_load_lds_dwordx4 v132, vcc
	s_add_i32 m0, s28, 0x1e000
	s_nop 0
	global_load_lds_dwordx4 v128, vcc
	s_add_u32 vcc_lo, vcc_lo, 0x10000
	s_addc_u32 vcc_hi, vcc_hi, 0
	s_add_i32 m0, s28, 0x1d000
	s_nop 0
	global_load_lds_dwordx4 v132, vcc
	s_add_i32 m0, s28, 0x1f000
	s_nop 0
	global_load_lds_dwordx4 v128, vcc
	ds_read_b128 v[144:147], v151 offset:0
	ds_read_b128 v[154:157], v151 offset:1024
	ds_read_b128 v[158:161], v151 offset:2048
	ds_read_b128 v[162:165], v151 offset:3072
	ds_read_b128 v[166:169], v152 offset:0
	ds_read_b128 v[170:173], v152 offset:1024
	ds_read_b128 v[174:177], v152 offset:2048
	ds_read_b128 v[178:181], v152 offset:3072
	ds_read_b128 v[182:185], v153 offset:0
	ds_read_b128 v[186:189], v153 offset:1024
	ds_read_b128 v[190:193], v153 offset:2048
	ds_read_b128 v[194:197], v153 offset:3072
	ds_read_b128 v[198:201], v153 offset:4096
	ds_read_b128 v[202:205], v153 offset:5120
	ds_read_b128 v[206:209], v153 offset:6144
	ds_read_b128 v[210:213], v153 offset:7168
	ds_read_b128 v[220:223], v153 offset:16384
	ds_read_b128 v[224:227], v153 offset:17408
	ds_read_b128 v[228:231], v153 offset:18432
	ds_read_b128 v[232:235], v153 offset:19456
	ds_read_b128 v[236:239], v153 offset:20480
	ds_read_b128 v[240:243], v153 offset:21504
	ds_read_b128 v[244:247], v153 offset:22528
	ds_read_b128 v[248:251], v153 offset:23552
	s_waitcnt lgkmcnt(0)
	s_barrier
	s_setprio 1
	v_mfma_f32_16x16x32_bf16 v[124:127], v[144:147], v[182:185], v[124:127]
	v_mfma_f32_16x16x32_bf16 v[120:123], v[158:161], v[182:185], v[120:123]
	v_mfma_f32_16x16x32_bf16 v[108:111], v[144:147], v[190:193], v[108:111]
	v_mfma_f32_16x16x32_bf16 v[104:107], v[158:161], v[190:193], v[104:107]
	v_mfma_f32_16x16x32_bf16 v[92:95], v[144:147], v[198:201], v[92:95]
	v_mfma_f32_16x16x32_bf16 v[88:91], v[158:161], v[198:201], v[88:91]
	v_mfma_f32_16x16x32_bf16 v[76:79], v[144:147], v[206:209], v[76:79]
	v_mfma_f32_16x16x32_bf16 v[72:75], v[158:161], v[206:209], v[72:75]
	v_mfma_f32_16x16x32_bf16 v[124:127], v[154:157], v[186:189], v[124:127]
	v_mfma_f32_16x16x32_bf16 v[120:123], v[162:165], v[186:189], v[120:123]
	v_mfma_f32_16x16x32_bf16 v[108:111], v[154:157], v[194:197], v[108:111]
	v_mfma_f32_16x16x32_bf16 v[104:107], v[162:165], v[194:197], v[104:107]
	v_mfma_f32_16x16x32_bf16 v[92:95], v[154:157], v[202:205], v[92:95]
	v_mfma_f32_16x16x32_bf16 v[88:91], v[162:165], v[202:205], v[88:91]
	v_mfma_f32_16x16x32_bf16 v[76:79], v[154:157], v[210:213], v[76:79]
	v_mfma_f32_16x16x32_bf16 v[72:75], v[162:165], v[210:213], v[72:75]
	s_setprio 0
	s_setprio 1
	v_mfma_f32_16x16x32_bf16 v[116:119], v[166:169], v[182:185], v[116:119]
	v_mfma_f32_16x16x32_bf16 v[112:115], v[174:177], v[182:185], v[112:115]
	v_mfma_f32_16x16x32_bf16 v[100:103], v[166:169], v[190:193], v[100:103]
	v_mfma_f32_16x16x32_bf16 v[96:99], v[174:177], v[190:193], v[96:99]
	v_mfma_f32_16x16x32_bf16 v[84:87], v[166:169], v[198:201], v[84:87]
	v_mfma_f32_16x16x32_bf16 v[80:83], v[174:177], v[198:201], v[80:83]
	v_mfma_f32_16x16x32_bf16 v[68:71], v[166:169], v[206:209], v[68:71]
	v_mfma_f32_16x16x32_bf16 v[64:67], v[174:177], v[206:209], v[64:67]
	v_mfma_f32_16x16x32_bf16 v[116:119], v[170:173], v[186:189], v[116:119]
	v_mfma_f32_16x16x32_bf16 v[112:115], v[178:181], v[186:189], v[112:115]
	v_mfma_f32_16x16x32_bf16 v[100:103], v[170:173], v[194:197], v[100:103]
	v_mfma_f32_16x16x32_bf16 v[96:99], v[178:181], v[194:197], v[96:99]
	v_mfma_f32_16x16x32_bf16 v[84:87], v[170:173], v[202:205], v[84:87]
	v_mfma_f32_16x16x32_bf16 v[80:83], v[178:181], v[202:205], v[80:83]
	v_mfma_f32_16x16x32_bf16 v[68:71], v[170:173], v[210:213], v[68:71]
	v_mfma_f32_16x16x32_bf16 v[64:67], v[178:181], v[210:213], v[64:67]
	s_setprio 0
	s_setprio 1
	v_mfma_f32_16x16x32_bf16 v[60:63], v[144:147], v[220:223], v[60:63]
	v_mfma_f32_16x16x32_bf16 v[56:59], v[158:161], v[220:223], v[56:59]
	v_mfma_f32_16x16x32_bf16 v[44:47], v[144:147], v[228:231], v[44:47]
	v_mfma_f32_16x16x32_bf16 v[40:43], v[158:161], v[228:231], v[40:43]
	v_mfma_f32_16x16x32_bf16 v[28:31], v[144:147], v[236:239], v[28:31]
	v_mfma_f32_16x16x32_bf16 v[24:27], v[158:161], v[236:239], v[24:27]
	v_mfma_f32_16x16x32_bf16 v[12:15], v[144:147], v[244:247], v[12:15]
	v_mfma_f32_16x16x32_bf16 v[8:11], v[158:161], v[244:247], v[8:11]
	v_mfma_f32_16x16x32_bf16 v[60:63], v[154:157], v[224:227], v[60:63]
	v_mfma_f32_16x16x32_bf16 v[56:59], v[162:165], v[224:227], v[56:59]
	v_mfma_f32_16x16x32_bf16 v[44:47], v[154:157], v[232:235], v[44:47]
	v_mfma_f32_16x16x32_bf16 v[40:43], v[162:165], v[232:235], v[40:43]
	v_mfma_f32_16x16x32_bf16 v[28:31], v[154:157], v[240:243], v[28:31]
	v_mfma_f32_16x16x32_bf16 v[24:27], v[162:165], v[240:243], v[24:27]
	v_mfma_f32_16x16x32_bf16 v[12:15], v[154:157], v[248:251], v[12:15]
	v_mfma_f32_16x16x32_bf16 v[8:11], v[162:165], v[248:251], v[8:11]
	s_setprio 0
	s_setprio 1
	v_mfma_f32_16x16x32_bf16 v[52:55], v[166:169], v[220:223], v[52:55]
	v_mfma_f32_16x16x32_bf16 v[48:51], v[174:177], v[220:223], v[48:51]
	v_mfma_f32_16x16x32_bf16 v[36:39], v[166:169], v[228:231], v[36:39]
	v_mfma_f32_16x16x32_bf16 v[32:35], v[174:177], v[228:231], v[32:35]
	v_mfma_f32_16x16x32_bf16 v[20:23], v[166:169], v[236:239], v[20:23]
	v_mfma_f32_16x16x32_bf16 v[16:19], v[174:177], v[236:239], v[16:19]
	v_mfma_f32_16x16x32_bf16 v[4:7], v[166:169], v[244:247], v[4:7]
	v_mfma_f32_16x16x32_bf16 v[0:3], v[174:177], v[244:247], v[0:3]
	v_mfma_f32_16x16x32_bf16 v[52:55], v[170:173], v[224:227], v[52:55]
	v_mfma_f32_16x16x32_bf16 v[48:51], v[178:181], v[224:227], v[48:51]
	v_mfma_f32_16x16x32_bf16 v[36:39], v[170:173], v[232:235], v[36:39]
	v_mfma_f32_16x16x32_bf16 v[32:35], v[178:181], v[232:235], v[32:35]
	v_mfma_f32_16x16x32_bf16 v[20:23], v[170:173], v[240:243], v[20:23]
	v_mfma_f32_16x16x32_bf16 v[16:19], v[178:181], v[240:243], v[16:19]
	v_mfma_f32_16x16x32_bf16 v[4:7], v[170:173], v[248:251], v[4:7]
	v_mfma_f32_16x16x32_bf16 v[0:3], v[178:181], v[248:251], v[0:3]
	s_setprio 0
	s_waitcnt vmcnt(0)
	s_barrier
	s_add_u32 vcc_lo, s24, 0x0
	s_addc_u32 vcc_hi, s25, 0
	s_add_i32 m0, s28, 0x10000
	s_nop 0
	global_load_lds_dwordx4 v132, vcc
	s_add_i32 m0, s28, 0x12000
	s_nop 0
	global_load_lds_dwordx4 v128, vcc
	s_add_u32 vcc_lo, vcc_lo, 0x10000
	s_addc_u32 vcc_hi, vcc_hi, 0
	s_add_i32 m0, s28, 0x11000
	s_nop 0
	global_load_lds_dwordx4 v132, vcc
	s_add_i32 m0, s28, 0x13000
	s_nop 0
	global_load_lds_dwordx4 v128, vcc
	s_add_u32 vcc_lo, vcc_lo, 0x30000
	s_addc_u32 vcc_hi, vcc_hi, 0
	s_add_i32 m0, s28, 0x14000
	s_nop 0
	global_load_lds_dwordx4 v132, vcc
	s_add_i32 m0, s28, 0x16000
	s_nop 0
	global_load_lds_dwordx4 v128, vcc
	s_add_u32 vcc_lo, vcc_lo, 0x10000
	s_addc_u32 vcc_hi, vcc_hi, 0
	s_add_i32 m0, s28, 0x15000
	s_nop 0
	global_load_lds_dwordx4 v132, vcc
	s_add_i32 m0, s28, 0x17000
	s_nop 0
	global_load_lds_dwordx4 v128, vcc
	ds_read_b128 v[144:147], v151 offset:32768
	ds_read_b128 v[154:157], v151 offset:33792
	ds_read_b128 v[158:161], v151 offset:34816
	ds_read_b128 v[162:165], v151 offset:35840
	ds_read_b128 v[166:169], v152 offset:32768
	ds_read_b128 v[170:173], v152 offset:33792
	ds_read_b128 v[174:177], v152 offset:34816
	ds_read_b128 v[178:181], v152 offset:35840
	ds_read_b128 v[182:185], v153 offset:32768
	ds_read_b128 v[186:189], v153 offset:33792
	ds_read_b128 v[190:193], v153 offset:34816
	ds_read_b128 v[194:197], v153 offset:35840
	ds_read_b128 v[198:201], v153 offset:36864
	ds_read_b128 v[202:205], v153 offset:37888
	ds_read_b128 v[206:209], v153 offset:38912
	ds_read_b128 v[210:213], v153 offset:39936
	ds_read_b128 v[220:223], v153 offset:49152
	ds_read_b128 v[224:227], v153 offset:50176
	ds_read_b128 v[228:231], v153 offset:51200
	ds_read_b128 v[232:235], v153 offset:52224
	ds_read_b128 v[236:239], v153 offset:53248
	ds_read_b128 v[240:243], v153 offset:54272
	ds_read_b128 v[244:247], v153 offset:55296
	ds_read_b128 v[248:251], v153 offset:56320
	s_waitcnt lgkmcnt(0)
	s_barrier
	s_setprio 1
	v_mfma_f32_16x16x32_bf16 v[124:127], v[144:147], v[182:185], v[124:127]
	v_mfma_f32_16x16x32_bf16 v[120:123], v[158:161], v[182:185], v[120:123]
	v_mfma_f32_16x16x32_bf16 v[108:111], v[144:147], v[190:193], v[108:111]
	v_mfma_f32_16x16x32_bf16 v[104:107], v[158:161], v[190:193], v[104:107]
	v_mfma_f32_16x16x32_bf16 v[92:95], v[144:147], v[198:201], v[92:95]
	v_mfma_f32_16x16x32_bf16 v[88:91], v[158:161], v[198:201], v[88:91]
	v_mfma_f32_16x16x32_bf16 v[76:79], v[144:147], v[206:209], v[76:79]
	v_mfma_f32_16x16x32_bf16 v[72:75], v[158:161], v[206:209], v[72:75]
	v_mfma_f32_16x16x32_bf16 v[124:127], v[154:157], v[186:189], v[124:127]
	v_mfma_f32_16x16x32_bf16 v[120:123], v[162:165], v[186:189], v[120:123]
	v_mfma_f32_16x16x32_bf16 v[108:111], v[154:157], v[194:197], v[108:111]
	v_mfma_f32_16x16x32_bf16 v[104:107], v[162:165], v[194:197], v[104:107]
	v_mfma_f32_16x16x32_bf16 v[92:95], v[154:157], v[202:205], v[92:95]
	v_mfma_f32_16x16x32_bf16 v[88:91], v[162:165], v[202:205], v[88:91]
	v_mfma_f32_16x16x32_bf16 v[76:79], v[154:157], v[210:213], v[76:79]
	v_mfma_f32_16x16x32_bf16 v[72:75], v[162:165], v[210:213], v[72:75]
	s_setprio 0
	s_setprio 1
	v_mfma_f32_16x16x32_bf16 v[116:119], v[166:169], v[182:185], v[116:119]
	v_mfma_f32_16x16x32_bf16 v[112:115], v[174:177], v[182:185], v[112:115]
	v_mfma_f32_16x16x32_bf16 v[100:103], v[166:169], v[190:193], v[100:103]
	v_mfma_f32_16x16x32_bf16 v[96:99], v[174:177], v[190:193], v[96:99]
	v_mfma_f32_16x16x32_bf16 v[84:87], v[166:169], v[198:201], v[84:87]
	v_mfma_f32_16x16x32_bf16 v[80:83], v[174:177], v[198:201], v[80:83]
	v_mfma_f32_16x16x32_bf16 v[68:71], v[166:169], v[206:209], v[68:71]
	v_mfma_f32_16x16x32_bf16 v[64:67], v[174:177], v[206:209], v[64:67]
	v_mfma_f32_16x16x32_bf16 v[116:119], v[170:173], v[186:189], v[116:119]
	v_mfma_f32_16x16x32_bf16 v[112:115], v[178:181], v[186:189], v[112:115]
	v_mfma_f32_16x16x32_bf16 v[100:103], v[170:173], v[194:197], v[100:103]
	v_mfma_f32_16x16x32_bf16 v[96:99], v[178:181], v[194:197], v[96:99]
	v_mfma_f32_16x16x32_bf16 v[84:87], v[170:173], v[202:205], v[84:87]
	v_mfma_f32_16x16x32_bf16 v[80:83], v[178:181], v[202:205], v[80:83]
	v_mfma_f32_16x16x32_bf16 v[68:71], v[170:173], v[210:213], v[68:71]
	v_mfma_f32_16x16x32_bf16 v[64:67], v[178:181], v[210:213], v[64:67]
	s_setprio 0
	s_setprio 1
	v_mfma_f32_16x16x32_bf16 v[60:63], v[144:147], v[220:223], v[60:63]
	v_mfma_f32_16x16x32_bf16 v[56:59], v[158:161], v[220:223], v[56:59]
	v_mfma_f32_16x16x32_bf16 v[44:47], v[144:147], v[228:231], v[44:47]
	v_mfma_f32_16x16x32_bf16 v[40:43], v[158:161], v[228:231], v[40:43]
	v_mfma_f32_16x16x32_bf16 v[28:31], v[144:147], v[236:239], v[28:31]
	v_mfma_f32_16x16x32_bf16 v[24:27], v[158:161], v[236:239], v[24:27]
	v_mfma_f32_16x16x32_bf16 v[12:15], v[144:147], v[244:247], v[12:15]
	v_mfma_f32_16x16x32_bf16 v[8:11], v[158:161], v[244:247], v[8:11]
	v_mfma_f32_16x16x32_bf16 v[60:63], v[154:157], v[224:227], v[60:63]
	v_mfma_f32_16x16x32_bf16 v[56:59], v[162:165], v[224:227], v[56:59]
	v_mfma_f32_16x16x32_bf16 v[44:47], v[154:157], v[232:235], v[44:47]
	v_mfma_f32_16x16x32_bf16 v[40:43], v[162:165], v[232:235], v[40:43]
	v_mfma_f32_16x16x32_bf16 v[28:31], v[154:157], v[240:243], v[28:31]
	v_mfma_f32_16x16x32_bf16 v[24:27], v[162:165], v[240:243], v[24:27]
	v_mfma_f32_16x16x32_bf16 v[12:15], v[154:157], v[248:251], v[12:15]
	v_mfma_f32_16x16x32_bf16 v[8:11], v[162:165], v[248:251], v[8:11]
	s_setprio 0
	s_setprio 1
	v_mfma_f32_16x16x32_bf16 v[52:55], v[166:169], v[220:223], v[52:55]
	v_mfma_f32_16x16x32_bf16 v[48:51], v[174:177], v[220:223], v[48:51]
	v_mfma_f32_16x16x32_bf16 v[36:39], v[166:169], v[228:231], v[36:39]
	v_mfma_f32_16x16x32_bf16 v[32:35], v[174:177], v[228:231], v[32:35]
	v_mfma_f32_16x16x32_bf16 v[20:23], v[166:169], v[236:239], v[20:23]
	v_mfma_f32_16x16x32_bf16 v[16:19], v[174:177], v[236:239], v[16:19]
	v_mfma_f32_16x16x32_bf16 v[4:7], v[166:169], v[244:247], v[4:7]
	v_mfma_f32_16x16x32_bf16 v[0:3], v[174:177], v[244:247], v[0:3]
	v_mfma_f32_16x16x32_bf16 v[52:55], v[170:173], v[224:227], v[52:55]
	v_mfma_f32_16x16x32_bf16 v[48:51], v[178:181], v[224:227], v[48:51]
	v_mfma_f32_16x16x32_bf16 v[36:39], v[170:173], v[232:235], v[36:39]
	v_mfma_f32_16x16x32_bf16 v[32:35], v[178:181], v[232:235], v[32:35]
	v_mfma_f32_16x16x32_bf16 v[20:23], v[170:173], v[240:243], v[20:23]
	v_mfma_f32_16x16x32_bf16 v[16:19], v[178:181], v[240:243], v[16:19]
	v_mfma_f32_16x16x32_bf16 v[4:7], v[170:173], v[248:251], v[4:7]
	v_mfma_f32_16x16x32_bf16 v[0:3], v[178:181], v[248:251], v[0:3]
	s_setprio 0
	s_waitcnt vmcnt(0)
	s_barrier
	s_add_i32 s49, s49, 2
	s_add_u32 s22, s22, 0x100
	s_addc_u32 s23, s23, 0
	s_add_u32 s47, s47, 0x100
	s_addc_u32 s48, s48, 0
	s_cmp_gt_u32 s49, 13
	s_cbranch_scc0 .LBB0_613
	s_branch .Lk64_done_glu
.Lk64_trail_glu:
	s_sub_u32 vcc_lo, s22, 0x40000
	s_subb_u32 vcc_hi, s23, 0
	s_add_i32 m0, s28, 0xa000
	s_nop 0
	global_load_lds_dwordx4 v130, vcc
	s_add_u32 vcc_lo, vcc_lo, 0x10000
	s_addc_u32 vcc_hi, vcc_hi, 0
	s_add_i32 m0, s28, 0x9000
	s_nop 0
	global_load_lds_dwordx4 v134, vcc
	s_add_u32 vcc_lo, vcc_lo, 0x30000
	s_addc_u32 vcc_hi, vcc_hi, 0
	s_add_i32 m0, s28, 0xe000
	s_nop 0
	global_load_lds_dwordx4 v130, vcc
	s_add_u32 vcc_lo, vcc_lo, 0x10000
	s_addc_u32 vcc_hi, vcc_hi, 0
	s_add_i32 m0, s28, 0xd000
	s_nop 0
	global_load_lds_dwordx4 v134, vcc
	s_add_u32 vcc_lo, s26, 0x0
	s_addc_u32 vcc_hi, s27, 0
	s_mov_b32 m0, s28
	s_nop 0
	global_load_lds_dwordx4 v134, vcc
	s_sub_u32 vcc_lo, vcc_lo, 0x10000
	s_subb_u32 vcc_hi, vcc_hi, 0
	s_sub_i32 m0, s28, 0x1000
	s_nop 0
	global_load_lds_dwordx4 v134, vcc
	s_add_u32 vcc_lo, vcc_lo, 0x50000
	s_addc_u32 vcc_hi, vcc_hi, 0
	s_add_i32 m0, s28, 0x4000
	s_nop 0
	global_load_lds_dwordx4 v134, vcc
	s_sub_u32 vcc_lo, vcc_lo, 0x10000
	s_subb_u32 vcc_hi, vcc_hi, 0
	s_add_i32 m0, s28, 0x3000
	s_nop 0
	global_load_lds_dwordx4 v134, vcc
	ds_read_b128 v[144:147], v151 offset:0
	ds_read_b128 v[154:157], v151 offset:1024
	ds_read_b128 v[158:161], v151 offset:2048
	ds_read_b128 v[162:165], v151 offset:3072
	ds_read_b128 v[166:169], v152 offset:0
	ds_read_b128 v[170:173], v152 offset:1024
	ds_read_b128 v[174:177], v152 offset:2048
	ds_read_b128 v[178:181], v152 offset:3072
	ds_read_b128 v[182:185], v153 offset:0
	ds_read_b128 v[186:189], v153 offset:1024
	ds_read_b128 v[190:193], v153 offset:2048
	ds_read_b128 v[194:197], v153 offset:3072
	ds_read_b128 v[198:201], v153 offset:4096
	ds_read_b128 v[202:205], v153 offset:5120
	ds_read_b128 v[206:209], v153 offset:6144
	ds_read_b128 v[210:213], v153 offset:7168
	ds_read_b128 v[220:223], v153 offset:16384
	ds_read_b128 v[224:227], v153 offset:17408
	ds_read_b128 v[228:231], v153 offset:18432
	ds_read_b128 v[232:235], v153 offset:19456
	ds_read_b128 v[236:239], v153 offset:20480
	ds_read_b128 v[240:243], v153 offset:21504
	ds_read_b128 v[244:247], v153 offset:22528
	ds_read_b128 v[248:251], v153 offset:23552
	s_waitcnt lgkmcnt(0)
	s_barrier
	s_setprio 1
	v_mfma_f32_16x16x32_bf16 v[124:127], v[144:147], v[182:185], v[124:127]
	v_mfma_f32_16x16x32_bf16 v[120:123], v[158:161], v[182:185], v[120:123]
	v_mfma_f32_16x16x32_bf16 v[108:111], v[144:147], v[190:193], v[108:111]
	v_mfma_f32_16x16x32_bf16 v[104:107], v[158:161], v[190:193], v[104:107]
	v_mfma_f32_16x16x32_bf16 v[92:95], v[144:147], v[198:201], v[92:95]
	v_mfma_f32_16x16x32_bf16 v[88:91], v[158:161], v[198:201], v[88:91]
	v_mfma_f32_16x16x32_bf16 v[76:79], v[144:147], v[206:209], v[76:79]
	v_mfma_f32_16x16x32_bf16 v[72:75], v[158:161], v[206:209], v[72:75]
	v_mfma_f32_16x16x32_bf16 v[124:127], v[154:157], v[186:189], v[124:127]
	v_mfma_f32_16x16x32_bf16 v[120:123], v[162:165], v[186:189], v[120:123]
	v_mfma_f32_16x16x32_bf16 v[108:111], v[154:157], v[194:197], v[108:111]
	v_mfma_f32_16x16x32_bf16 v[104:107], v[162:165], v[194:197], v[104:107]
	v_mfma_f32_16x16x32_bf16 v[92:95], v[154:157], v[202:205], v[92:95]
	v_mfma_f32_16x16x32_bf16 v[88:91], v[162:165], v[202:205], v[88:91]
	v_mfma_f32_16x16x32_bf16 v[76:79], v[154:157], v[210:213], v[76:79]
	v_mfma_f32_16x16x32_bf16 v[72:75], v[162:165], v[210:213], v[72:75]
	s_setprio 0
	s_setprio 1
	v_mfma_f32_16x16x32_bf16 v[116:119], v[166:169], v[182:185], v[116:119]
	v_mfma_f32_16x16x32_bf16 v[112:115], v[174:177], v[182:185], v[112:115]
	v_mfma_f32_16x16x32_bf16 v[100:103], v[166:169], v[190:193], v[100:103]
	v_mfma_f32_16x16x32_bf16 v[96:99], v[174:177], v[190:193], v[96:99]
	v_mfma_f32_16x16x32_bf16 v[84:87], v[166:169], v[198:201], v[84:87]
	v_mfma_f32_16x16x32_bf16 v[80:83], v[174:177], v[198:201], v[80:83]
	v_mfma_f32_16x16x32_bf16 v[68:71], v[166:169], v[206:209], v[68:71]
	v_mfma_f32_16x16x32_bf16 v[64:67], v[174:177], v[206:209], v[64:67]
	v_mfma_f32_16x16x32_bf16 v[116:119], v[170:173], v[186:189], v[116:119]
	v_mfma_f32_16x16x32_bf16 v[112:115], v[178:181], v[186:189], v[112:115]
	v_mfma_f32_16x16x32_bf16 v[100:103], v[170:173], v[194:197], v[100:103]
	v_mfma_f32_16x16x32_bf16 v[96:99], v[178:181], v[194:197], v[96:99]
	v_mfma_f32_16x16x32_bf16 v[84:87], v[170:173], v[202:205], v[84:87]
	v_mfma_f32_16x16x32_bf16 v[80:83], v[178:181], v[202:205], v[80:83]
	v_mfma_f32_16x16x32_bf16 v[68:71], v[170:173], v[210:213], v[68:71]
	v_mfma_f32_16x16x32_bf16 v[64:67], v[178:181], v[210:213], v[64:67]
	s_setprio 0
	s_setprio 1
	v_mfma_f32_16x16x32_bf16 v[60:63], v[144:147], v[220:223], v[60:63]
	v_mfma_f32_16x16x32_bf16 v[56:59], v[158:161], v[220:223], v[56:59]
	v_mfma_f32_16x16x32_bf16 v[44:47], v[144:147], v[228:231], v[44:47]
	v_mfma_f32_16x16x32_bf16 v[40:43], v[158:161], v[228:231], v[40:43]
	v_mfma_f32_16x16x32_bf16 v[28:31], v[144:147], v[236:239], v[28:31]
	v_mfma_f32_16x16x32_bf16 v[24:27], v[158:161], v[236:239], v[24:27]
	v_mfma_f32_16x16x32_bf16 v[12:15], v[144:147], v[244:247], v[12:15]
	v_mfma_f32_16x16x32_bf16 v[8:11], v[158:161], v[244:247], v[8:11]
	v_mfma_f32_16x16x32_bf16 v[60:63], v[154:157], v[224:227], v[60:63]
	v_mfma_f32_16x16x32_bf16 v[56:59], v[162:165], v[224:227], v[56:59]
	v_mfma_f32_16x16x32_bf16 v[44:47], v[154:157], v[232:235], v[44:47]
	v_mfma_f32_16x16x32_bf16 v[40:43], v[162:165], v[232:235], v[40:43]
	v_mfma_f32_16x16x32_bf16 v[28:31], v[154:157], v[240:243], v[28:31]
	v_mfma_f32_16x16x32_bf16 v[24:27], v[162:165], v[240:243], v[24:27]
	v_mfma_f32_16x16x32_bf16 v[12:15], v[154:157], v[248:251], v[12:15]
	v_mfma_f32_16x16x32_bf16 v[8:11], v[162:165], v[248:251], v[8:11]
	s_setprio 0
	s_setprio 1
	v_mfma_f32_16x16x32_bf16 v[52:55], v[166:169], v[220:223], v[52:55]
	v_mfma_f32_16x16x32_bf16 v[48:51], v[174:177], v[220:223], v[48:51]
	v_mfma_f32_16x16x32_bf16 v[36:39], v[166:169], v[228:231], v[36:39]
	v_mfma_f32_16x16x32_bf16 v[32:35], v[174:177], v[228:231], v[32:35]
	v_mfma_f32_16x16x32_bf16 v[20:23], v[166:169], v[236:239], v[20:23]
	v_mfma_f32_16x16x32_bf16 v[16:19], v[174:177], v[236:239], v[16:19]
	v_mfma_f32_16x16x32_bf16 v[4:7], v[166:169], v[244:247], v[4:7]
	v_mfma_f32_16x16x32_bf16 v[0:3], v[174:177], v[244:247], v[0:3]
	v_mfma_f32_16x16x32_bf16 v[52:55], v[170:173], v[224:227], v[52:55]
	v_mfma_f32_16x16x32_bf16 v[48:51], v[178:181], v[224:227], v[48:51]
	v_mfma_f32_16x16x32_bf16 v[36:39], v[170:173], v[232:235], v[36:39]
	v_mfma_f32_16x16x32_bf16 v[32:35], v[178:181], v[232:235], v[32:35]
	v_mfma_f32_16x16x32_bf16 v[20:23], v[170:173], v[240:243], v[20:23]
	v_mfma_f32_16x16x32_bf16 v[16:19], v[178:181], v[240:243], v[16:19]
	v_mfma_f32_16x16x32_bf16 v[4:7], v[170:173], v[248:251], v[4:7]
	v_mfma_f32_16x16x32_bf16 v[0:3], v[178:181], v[248:251], v[0:3]
	s_setprio 0
	s_waitcnt vmcnt(0)
	s_barrier
	s_add_u32 vcc_lo, s26, 0x0
	s_addc_u32 vcc_hi, s27, 0
	s_add_i32 m0, s28, 0x2000
	s_nop 0
	global_load_lds_dwordx4 v130, vcc
	s_add_u32 vcc_lo, vcc_lo, 0x10000
	s_addc_u32 vcc_hi, vcc_hi, 0
	s_add_i32 m0, s28, 0x1000
	s_nop 0
	global_load_lds_dwordx4 v134, vcc
	s_add_u32 vcc_lo, vcc_lo, 0x30000
	s_addc_u32 vcc_hi, vcc_hi, 0
	s_add_i32 m0, s28, 0x6000
	s_nop 0
	global_load_lds_dwordx4 v130, vcc
	s_add_u32 vcc_lo, vcc_lo, 0x10000
	s_addc_u32 vcc_hi, vcc_hi, 0
	s_add_i32 m0, s28, 0x5000
	s_nop 0
	global_load_lds_dwordx4 v134, vcc
	s_add_u32 vcc_lo, s26, 0x80
	s_addc_u32 vcc_hi, s27, 0
	s_add_i32 m0, s28, 0x8000
	s_nop 0
	global_load_lds_dwordx4 v134, vcc
	s_sub_u32 vcc_lo, vcc_lo, 0x10000
	s_subb_u32 vcc_hi, vcc_hi, 0
	s_add_i32 m0, s28, 0x7000
	s_nop 0
	global_load_lds_dwordx4 v134, vcc
	s_add_u32 vcc_lo, vcc_lo, 0x50000
	s_addc_u32 vcc_hi, vcc_hi, 0
	s_add_i32 m0, s28, 0xc000
	s_nop 0
	global_load_lds_dwordx4 v134, vcc
	s_sub_u32 vcc_lo, vcc_lo, 0x10000
	s_subb_u32 vcc_hi, vcc_hi, 0
	s_add_i32 m0, s28, 0xb000
	s_nop 0
	global_load_lds_dwordx4 v134, vcc
	ds_read_b128 v[144:147], v151 offset:32768
	ds_read_b128 v[154:157], v151 offset:33792
	ds_read_b128 v[158:161], v151 offset:34816
	ds_read_b128 v[162:165], v151 offset:35840
	ds_read_b128 v[166:169], v152 offset:32768
	ds_read_b128 v[170:173], v152 offset:33792
	ds_read_b128 v[174:177], v152 offset:34816
	ds_read_b128 v[178:181], v152 offset:35840
	ds_read_b128 v[182:185], v153 offset:32768
	ds_read_b128 v[186:189], v153 offset:33792
	ds_read_b128 v[190:193], v153 offset:34816
	ds_read_b128 v[194:197], v153 offset:35840
	ds_read_b128 v[198:201], v153 offset:36864
	ds_read_b128 v[202:205], v153 offset:37888
	ds_read_b128 v[206:209], v153 offset:38912
	ds_read_b128 v[210:213], v153 offset:39936
	ds_read_b128 v[220:223], v153 offset:49152
	ds_read_b128 v[224:227], v153 offset:50176
	ds_read_b128 v[228:231], v153 offset:51200
	ds_read_b128 v[232:235], v153 offset:52224
	ds_read_b128 v[236:239], v153 offset:53248
	ds_read_b128 v[240:243], v153 offset:54272
	ds_read_b128 v[244:247], v153 offset:55296
	ds_read_b128 v[248:251], v153 offset:56320
	s_waitcnt lgkmcnt(0)
	s_barrier
	s_setprio 1
	v_mfma_f32_16x16x32_bf16 v[124:127], v[144:147], v[182:185], v[124:127]
	v_mfma_f32_16x16x32_bf16 v[120:123], v[158:161], v[182:185], v[120:123]
	v_mfma_f32_16x16x32_bf16 v[108:111], v[144:147], v[190:193], v[108:111]
	v_mfma_f32_16x16x32_bf16 v[104:107], v[158:161], v[190:193], v[104:107]
	v_mfma_f32_16x16x32_bf16 v[92:95], v[144:147], v[198:201], v[92:95]
	v_mfma_f32_16x16x32_bf16 v[88:91], v[158:161], v[198:201], v[88:91]
	v_mfma_f32_16x16x32_bf16 v[76:79], v[144:147], v[206:209], v[76:79]
	v_mfma_f32_16x16x32_bf16 v[72:75], v[158:161], v[206:209], v[72:75]
	v_mfma_f32_16x16x32_bf16 v[124:127], v[154:157], v[186:189], v[124:127]
	v_mfma_f32_16x16x32_bf16 v[120:123], v[162:165], v[186:189], v[120:123]
	v_mfma_f32_16x16x32_bf16 v[108:111], v[154:157], v[194:197], v[108:111]
	v_mfma_f32_16x16x32_bf16 v[104:107], v[162:165], v[194:197], v[104:107]
	v_mfma_f32_16x16x32_bf16 v[92:95], v[154:157], v[202:205], v[92:95]
	v_mfma_f32_16x16x32_bf16 v[88:91], v[162:165], v[202:205], v[88:91]
	v_mfma_f32_16x16x32_bf16 v[76:79], v[154:157], v[210:213], v[76:79]
	v_mfma_f32_16x16x32_bf16 v[72:75], v[162:165], v[210:213], v[72:75]
	s_setprio 0
	s_setprio 1
	v_mfma_f32_16x16x32_bf16 v[116:119], v[166:169], v[182:185], v[116:119]
	v_mfma_f32_16x16x32_bf16 v[112:115], v[174:177], v[182:185], v[112:115]
	v_mfma_f32_16x16x32_bf16 v[100:103], v[166:169], v[190:193], v[100:103]
	v_mfma_f32_16x16x32_bf16 v[96:99], v[174:177], v[190:193], v[96:99]
	v_mfma_f32_16x16x32_bf16 v[84:87], v[166:169], v[198:201], v[84:87]
	v_mfma_f32_16x16x32_bf16 v[80:83], v[174:177], v[198:201], v[80:83]
	v_mfma_f32_16x16x32_bf16 v[68:71], v[166:169], v[206:209], v[68:71]
	v_mfma_f32_16x16x32_bf16 v[64:67], v[174:177], v[206:209], v[64:67]
	v_mfma_f32_16x16x32_bf16 v[116:119], v[170:173], v[186:189], v[116:119]
	v_mfma_f32_16x16x32_bf16 v[112:115], v[178:181], v[186:189], v[112:115]
	v_mfma_f32_16x16x32_bf16 v[100:103], v[170:173], v[194:197], v[100:103]
	v_mfma_f32_16x16x32_bf16 v[96:99], v[178:181], v[194:197], v[96:99]
	v_mfma_f32_16x16x32_bf16 v[84:87], v[170:173], v[202:205], v[84:87]
	v_mfma_f32_16x16x32_bf16 v[80:83], v[178:181], v[202:205], v[80:83]
	v_mfma_f32_16x16x32_bf16 v[68:71], v[170:173], v[210:213], v[68:71]
	v_mfma_f32_16x16x32_bf16 v[64:67], v[178:181], v[210:213], v[64:67]
	s_setprio 0
	s_setprio 1
	v_mfma_f32_16x16x32_bf16 v[60:63], v[144:147], v[220:223], v[60:63]
	v_mfma_f32_16x16x32_bf16 v[56:59], v[158:161], v[220:223], v[56:59]
	v_mfma_f32_16x16x32_bf16 v[44:47], v[144:147], v[228:231], v[44:47]
	v_mfma_f32_16x16x32_bf16 v[40:43], v[158:161], v[228:231], v[40:43]
	v_mfma_f32_16x16x32_bf16 v[28:31], v[144:147], v[236:239], v[28:31]
	v_mfma_f32_16x16x32_bf16 v[24:27], v[158:161], v[236:239], v[24:27]
	v_mfma_f32_16x16x32_bf16 v[12:15], v[144:147], v[244:247], v[12:15]
	v_mfma_f32_16x16x32_bf16 v[8:11], v[158:161], v[244:247], v[8:11]
	v_mfma_f32_16x16x32_bf16 v[60:63], v[154:157], v[224:227], v[60:63]
	v_mfma_f32_16x16x32_bf16 v[56:59], v[162:165], v[224:227], v[56:59]
	v_mfma_f32_16x16x32_bf16 v[44:47], v[154:157], v[232:235], v[44:47]
	v_mfma_f32_16x16x32_bf16 v[40:43], v[162:165], v[232:235], v[40:43]
	v_mfma_f32_16x16x32_bf16 v[28:31], v[154:157], v[240:243], v[28:31]
	v_mfma_f32_16x16x32_bf16 v[24:27], v[162:165], v[240:243], v[24:27]
	v_mfma_f32_16x16x32_bf16 v[12:15], v[154:157], v[248:251], v[12:15]
	v_mfma_f32_16x16x32_bf16 v[8:11], v[162:165], v[248:251], v[8:11]
	s_setprio 0
	s_setprio 1
	v_mfma_f32_16x16x32_bf16 v[52:55], v[166:169], v[220:223], v[52:55]
	v_mfma_f32_16x16x32_bf16 v[48:51], v[174:177], v[220:223], v[48:51]
	v_mfma_f32_16x16x32_bf16 v[36:39], v[166:169], v[228:231], v[36:39]
	v_mfma_f32_16x16x32_bf16 v[32:35], v[174:177], v[228:231], v[32:35]
	v_mfma_f32_16x16x32_bf16 v[20:23], v[166:169], v[236:239], v[20:23]
	v_mfma_f32_16x16x32_bf16 v[16:19], v[174:177], v[236:239], v[16:19]
	v_mfma_f32_16x16x32_bf16 v[4:7], v[166:169], v[244:247], v[4:7]
	v_mfma_f32_16x16x32_bf16 v[0:3], v[174:177], v[244:247], v[0:3]
	v_mfma_f32_16x16x32_bf16 v[52:55], v[170:173], v[224:227], v[52:55]
	v_mfma_f32_16x16x32_bf16 v[48:51], v[178:181], v[224:227], v[48:51]
	v_mfma_f32_16x16x32_bf16 v[36:39], v[170:173], v[232:235], v[36:39]
	v_mfma_f32_16x16x32_bf16 v[32:35], v[178:181], v[232:235], v[32:35]
	v_mfma_f32_16x16x32_bf16 v[20:23], v[170:173], v[240:243], v[20:23]
	v_mfma_f32_16x16x32_bf16 v[16:19], v[178:181], v[240:243], v[16:19]
	v_mfma_f32_16x16x32_bf16 v[4:7], v[170:173], v[248:251], v[4:7]
	v_mfma_f32_16x16x32_bf16 v[0:3], v[178:181], v[248:251], v[0:3]
	s_setprio 0
	s_waitcnt vmcnt(0)
	s_barrier
	s_add_i32 s49, s49, 2
	s_add_u32 s22, s22, 0x100
	s_addc_u32 s23, s23, 0
	s_add_u32 s47, s47, 0x100
	s_addc_u32 s48, s48, 0
	s_cmp_gt_u32 s49, 13
	s_cbranch_scc0 .LBB0_613

.LBB0_686:
	s_add_u32 s30, s12, 0xfffc0080
	s_addc_u32 s31, s13, -1
	s_cmp_eq_u32 s56, 12
	s_cselect_b32 s35, s25, s31
	s_cselect_b32 s34, s49, s30
	s_cselect_b32 s31, s23, s55
	s_cselect_b32 s30, s51, s54
	s_and_b64 vcc, exec, s[4:5]
	s_cbranch_vccz .Lk64_trail_p4
	s_sub_u32 vcc_lo, s54, 0x80
	s_subb_u32 vcc_hi, s55, 0
	s_add_i32 m0, s36, 0x18000
	s_nop 0
	global_load_lds_dwordx4 v132, vcc
	s_add_i32 m0, s36, 0x1a000
	s_nop 0
	global_load_lds_dwordx4 v128, vcc
	s_add_u32 vcc_lo, vcc_lo, 0x10000
	s_addc_u32 vcc_hi, vcc_hi, 0
	s_add_i32 m0, s36, 0x19000
	s_nop 0
	global_load_lds_dwordx4 v132, vcc
	s_add_i32 m0, s36, 0x1b000
	s_nop 0
	global_load_lds_dwordx4 v128, vcc
	s_add_u32 vcc_lo, vcc_lo, 0x30000
	s_addc_u32 vcc_hi, vcc_hi, 0
	s_add_i32 m0, s36, 0x1c000
	s_nop 0
	global_load_lds_dwordx4 v132, vcc
	s_add_i32 m0, s36, 0x1e000
	s_nop 0
	global_load_lds_dwordx4 v128, vcc
	s_add_u32 vcc_lo, vcc_lo, 0x10000
	s_addc_u32 vcc_hi, vcc_hi, 0
	s_add_i32 m0, s36, 0x1d000
	s_nop 0
	global_load_lds_dwordx4 v132, vcc
	s_add_i32 m0, s36, 0x1f000
	s_nop 0
	global_load_lds_dwordx4 v128, vcc
	ds_read_b128 v[144:147], v151 offset:0
	ds_read_b128 v[154:157], v151 offset:1024
	ds_read_b128 v[158:161], v151 offset:2048
	ds_read_b128 v[162:165], v151 offset:3072
	ds_read_b128 v[166:169], v152 offset:0
	ds_read_b128 v[170:173], v152 offset:1024
	ds_read_b128 v[174:177], v152 offset:2048
	ds_read_b128 v[178:181], v152 offset:3072
	ds_read_b128 v[182:185], v153 offset:0
	ds_read_b128 v[186:189], v153 offset:1024
	ds_read_b128 v[190:193], v153 offset:2048
	ds_read_b128 v[194:197], v153 offset:3072
	ds_read_b128 v[198:201], v153 offset:4096
	ds_read_b128 v[202:205], v153 offset:5120
	ds_read_b128 v[206:209], v153 offset:6144
	ds_read_b128 v[210:213], v153 offset:7168
	ds_read_b128 v[220:223], v153 offset:16384
	ds_read_b128 v[224:227], v153 offset:17408
	ds_read_b128 v[228:231], v153 offset:18432
	ds_read_b128 v[232:235], v153 offset:19456
	ds_read_b128 v[236:239], v153 offset:20480
	ds_read_b128 v[240:243], v153 offset:21504
	ds_read_b128 v[244:247], v153 offset:22528
	ds_read_b128 v[248:251], v153 offset:23552
	s_waitcnt lgkmcnt(0)
	s_barrier
	s_setprio 1
	v_mfma_f32_16x16x32_bf16 v[124:127], v[144:147], v[182:185], v[124:127]
	v_mfma_f32_16x16x32_bf16 v[120:123], v[158:161], v[182:185], v[120:123]
	v_mfma_f32_16x16x32_bf16 v[108:111], v[144:147], v[190:193], v[108:111]
	v_mfma_f32_16x16x32_bf16 v[104:107], v[158:161], v[190:193], v[104:107]
	v_mfma_f32_16x16x32_bf16 v[92:95], v[144:147], v[198:201], v[92:95]
	v_mfma_f32_16x16x32_bf16 v[88:91], v[158:161], v[198:201], v[88:91]
	v_mfma_f32_16x16x32_bf16 v[76:79], v[144:147], v[206:209], v[76:79]
	v_mfma_f32_16x16x32_bf16 v[72:75], v[158:161], v[206:209], v[72:75]
	v_mfma_f32_16x16x32_bf16 v[124:127], v[154:157], v[186:189], v[124:127]
	v_mfma_f32_16x16x32_bf16 v[120:123], v[162:165], v[186:189], v[120:123]
	v_mfma_f32_16x16x32_bf16 v[108:111], v[154:157], v[194:197], v[108:111]
	v_mfma_f32_16x16x32_bf16 v[104:107], v[162:165], v[194:197], v[104:107]
	v_mfma_f32_16x16x32_bf16 v[92:95], v[154:157], v[202:205], v[92:95]
	v_mfma_f32_16x16x32_bf16 v[88:91], v[162:165], v[202:205], v[88:91]
	v_mfma_f32_16x16x32_bf16 v[76:79], v[154:157], v[210:213], v[76:79]
	v_mfma_f32_16x16x32_bf16 v[72:75], v[162:165], v[210:213], v[72:75]
	s_setprio 0
	s_setprio 1
	v_mfma_f32_16x16x32_bf16 v[116:119], v[166:169], v[182:185], v[116:119]
	v_mfma_f32_16x16x32_bf16 v[112:115], v[174:177], v[182:185], v[112:115]
	v_mfma_f32_16x16x32_bf16 v[100:103], v[166:169], v[190:193], v[100:103]
	v_mfma_f32_16x16x32_bf16 v[96:99], v[174:177], v[190:193], v[96:99]
	v_mfma_f32_16x16x32_bf16 v[84:87], v[166:169], v[198:201], v[84:87]
	v_mfma_f32_16x16x32_bf16 v[80:83], v[174:177], v[198:201], v[80:83]
	v_mfma_f32_16x16x32_bf16 v[68:71], v[166:169], v[206:209], v[68:71]
	v_mfma_f32_16x16x32_bf16 v[64:67], v[174:177], v[206:209], v[64:67]
	v_mfma_f32_16x16x32_bf16 v[116:119], v[170:173], v[186:189], v[116:119]
	v_mfma_f32_16x16x32_bf16 v[112:115], v[178:181], v[186:189], v[112:115]
	v_mfma_f32_16x16x32_bf16 v[100:103], v[170:173], v[194:197], v[100:103]
	v_mfma_f32_16x16x32_bf16 v[96:99], v[178:181], v[194:197], v[96:99]
	v_mfma_f32_16x16x32_bf16 v[84:87], v[170:173], v[202:205], v[84:87]
	v_mfma_f32_16x16x32_bf16 v[80:83], v[178:181], v[202:205], v[80:83]
	v_mfma_f32_16x16x32_bf16 v[68:71], v[170:173], v[210:213], v[68:71]
	v_mfma_f32_16x16x32_bf16 v[64:67], v[178:181], v[210:213], v[64:67]
	s_setprio 0
	s_setprio 1
	v_mfma_f32_16x16x32_bf16 v[60:63], v[144:147], v[220:223], v[60:63]
	v_mfma_f32_16x16x32_bf16 v[56:59], v[158:161], v[220:223], v[56:59]
	v_mfma_f32_16x16x32_bf16 v[44:47], v[144:147], v[228:231], v[44:47]
	v_mfma_f32_16x16x32_bf16 v[40:43], v[158:161], v[228:231], v[40:43]
	v_mfma_f32_16x16x32_bf16 v[28:31], v[144:147], v[236:239], v[28:31]
	v_mfma_f32_16x16x32_bf16 v[24:27], v[158:161], v[236:239], v[24:27]
	v_mfma_f32_16x16x32_bf16 v[12:15], v[144:147], v[244:247], v[12:15]
	v_mfma_f32_16x16x32_bf16 v[8:11], v[158:161], v[244:247], v[8:11]
	v_mfma_f32_16x16x32_bf16 v[60:63], v[154:157], v[224:227], v[60:63]
	v_mfma_f32_16x16x32_bf16 v[56:59], v[162:165], v[224:227], v[56:59]
	v_mfma_f32_16x16x32_bf16 v[44:47], v[154:157], v[232:235], v[44:47]
	v_mfma_f32_16x16x32_bf16 v[40:43], v[162:165], v[232:235], v[40:43]
	v_mfma_f32_16x16x32_bf16 v[28:31], v[154:157], v[240:243], v[28:31]
	v_mfma_f32_16x16x32_bf16 v[24:27], v[162:165], v[240:243], v[24:27]
	v_mfma_f32_16x16x32_bf16 v[12:15], v[154:157], v[248:251], v[12:15]
	v_mfma_f32_16x16x32_bf16 v[8:11], v[162:165], v[248:251], v[8:11]
	s_setprio 0
	s_setprio 1
	v_mfma_f32_16x16x32_bf16 v[52:55], v[166:169], v[220:223], v[52:55]
	v_mfma_f32_16x16x32_bf16 v[48:51], v[174:177], v[220:223], v[48:51]
	v_mfma_f32_16x16x32_bf16 v[36:39], v[166:169], v[228:231], v[36:39]
	v_mfma_f32_16x16x32_bf16 v[32:35], v[174:177], v[228:231], v[32:35]
	v_mfma_f32_16x16x32_bf16 v[20:23], v[166:169], v[236:239], v[20:23]
	v_mfma_f32_16x16x32_bf16 v[16:19], v[174:177], v[236:239], v[16:19]
	v_mfma_f32_16x16x32_bf16 v[4:7], v[166:169], v[244:247], v[4:7]
	v_mfma_f32_16x16x32_bf16 v[0:3], v[174:177], v[244:247], v[0:3]
	v_mfma_f32_16x16x32_bf16 v[52:55], v[170:173], v[224:227], v[52:55]
	v_mfma_f32_16x16x32_bf16 v[48:51], v[178:181], v[224:227], v[48:51]
	v_mfma_f32_16x16x32_bf16 v[36:39], v[170:173], v[232:235], v[36:39]
	v_mfma_f32_16x16x32_bf16 v[32:35], v[178:181], v[232:235], v[32:35]
	v_mfma_f32_16x16x32_bf16 v[20:23], v[170:173], v[240:243], v[20:23]
	v_mfma_f32_16x16x32_bf16 v[16:19], v[178:181], v[240:243], v[16:19]
	v_mfma_f32_16x16x32_bf16 v[4:7], v[170:173], v[248:251], v[4:7]
	v_mfma_f32_16x16x32_bf16 v[0:3], v[178:181], v[248:251], v[0:3]
	s_setprio 0
	s_waitcnt vmcnt(0)
	s_barrier
	s_add_u32 vcc_lo, s30, 0x0
	s_addc_u32 vcc_hi, s31, 0
	s_add_i32 m0, s36, 0x10000
	s_nop 0
	global_load_lds_dwordx4 v132, vcc
	s_add_i32 m0, s36, 0x12000
	s_nop 0
	global_load_lds_dwordx4 v128, vcc
	s_add_u32 vcc_lo, vcc_lo, 0x10000
	s_addc_u32 vcc_hi, vcc_hi, 0
	s_add_i32 m0, s36, 0x11000
	s_nop 0
	global_load_lds_dwordx4 v132, vcc
	s_add_i32 m0, s36, 0x13000
	s_nop 0
	global_load_lds_dwordx4 v128, vcc
	s_add_u32 vcc_lo, vcc_lo, 0x30000
	s_addc_u32 vcc_hi, vcc_hi, 0
	s_add_i32 m0, s36, 0x14000
	s_nop 0
	global_load_lds_dwordx4 v132, vcc
	s_add_i32 m0, s36, 0x16000
	s_nop 0
	global_load_lds_dwordx4 v128, vcc
	s_add_u32 vcc_lo, vcc_lo, 0x10000
	s_addc_u32 vcc_hi, vcc_hi, 0
	s_add_i32 m0, s36, 0x15000
	s_nop 0
	global_load_lds_dwordx4 v132, vcc
	s_add_i32 m0, s36, 0x17000
	s_nop 0
	global_load_lds_dwordx4 v128, vcc
	ds_read_b128 v[144:147], v151 offset:32768
	ds_read_b128 v[154:157], v151 offset:33792
	ds_read_b128 v[158:161], v151 offset:34816
	ds_read_b128 v[162:165], v151 offset:35840
	ds_read_b128 v[166:169], v152 offset:32768
	ds_read_b128 v[170:173], v152 offset:33792
	ds_read_b128 v[174:177], v152 offset:34816
	ds_read_b128 v[178:181], v152 offset:35840
	ds_read_b128 v[182:185], v153 offset:32768
	ds_read_b128 v[186:189], v153 offset:33792
	ds_read_b128 v[190:193], v153 offset:34816
	ds_read_b128 v[194:197], v153 offset:35840
	ds_read_b128 v[198:201], v153 offset:36864
	ds_read_b128 v[202:205], v153 offset:37888
	ds_read_b128 v[206:209], v153 offset:38912
	ds_read_b128 v[210:213], v153 offset:39936
	ds_read_b128 v[220:223], v153 offset:49152
	ds_read_b128 v[224:227], v153 offset:50176
	ds_read_b128 v[228:231], v153 offset:51200
	ds_read_b128 v[232:235], v153 offset:52224
	ds_read_b128 v[236:239], v153 offset:53248
	ds_read_b128 v[240:243], v153 offset:54272
	ds_read_b128 v[244:247], v153 offset:55296
	ds_read_b128 v[248:251], v153 offset:56320
	s_waitcnt lgkmcnt(0)
	s_barrier
	s_setprio 1
	v_mfma_f32_16x16x32_bf16 v[124:127], v[144:147], v[182:185], v[124:127]
	v_mfma_f32_16x16x32_bf16 v[120:123], v[158:161], v[182:185], v[120:123]
	v_mfma_f32_16x16x32_bf16 v[108:111], v[144:147], v[190:193], v[108:111]
	v_mfma_f32_16x16x32_bf16 v[104:107], v[158:161], v[190:193], v[104:107]
	v_mfma_f32_16x16x32_bf16 v[92:95], v[144:147], v[198:201], v[92:95]
	v_mfma_f32_16x16x32_bf16 v[88:91], v[158:161], v[198:201], v[88:91]
	v_mfma_f32_16x16x32_bf16 v[76:79], v[144:147], v[206:209], v[76:79]
	v_mfma_f32_16x16x32_bf16 v[72:75], v[158:161], v[206:209], v[72:75]
	v_mfma_f32_16x16x32_bf16 v[124:127], v[154:157], v[186:189], v[124:127]
	v_mfma_f32_16x16x32_bf16 v[120:123], v[162:165], v[186:189], v[120:123]
	v_mfma_f32_16x16x32_bf16 v[108:111], v[154:157], v[194:197], v[108:111]
	v_mfma_f32_16x16x32_bf16 v[104:107], v[162:165], v[194:197], v[104:107]
	v_mfma_f32_16x16x32_bf16 v[92:95], v[154:157], v[202:205], v[92:95]
	v_mfma_f32_16x16x32_bf16 v[88:91], v[162:165], v[202:205], v[88:91]
	v_mfma_f32_16x16x32_bf16 v[76:79], v[154:157], v[210:213], v[76:79]
	v_mfma_f32_16x16x32_bf16 v[72:75], v[162:165], v[210:213], v[72:75]
	s_setprio 0
	s_setprio 1
	v_mfma_f32_16x16x32_bf16 v[116:119], v[166:169], v[182:185], v[116:119]
	v_mfma_f32_16x16x32_bf16 v[112:115], v[174:177], v[182:185], v[112:115]
	v_mfma_f32_16x16x32_bf16 v[100:103], v[166:169], v[190:193], v[100:103]
	v_mfma_f32_16x16x32_bf16 v[96:99], v[174:177], v[190:193], v[96:99]
	v_mfma_f32_16x16x32_bf16 v[84:87], v[166:169], v[198:201], v[84:87]
	v_mfma_f32_16x16x32_bf16 v[80:83], v[174:177], v[198:201], v[80:83]
	v_mfma_f32_16x16x32_bf16 v[68:71], v[166:169], v[206:209], v[68:71]
	v_mfma_f32_16x16x32_bf16 v[64:67], v[174:177], v[206:209], v[64:67]
	v_mfma_f32_16x16x32_bf16 v[116:119], v[170:173], v[186:189], v[116:119]
	v_mfma_f32_16x16x32_bf16 v[112:115], v[178:181], v[186:189], v[112:115]
	v_mfma_f32_16x16x32_bf16 v[100:103], v[170:173], v[194:197], v[100:103]
	v_mfma_f32_16x16x32_bf16 v[96:99], v[178:181], v[194:197], v[96:99]
	v_mfma_f32_16x16x32_bf16 v[84:87], v[170:173], v[202:205], v[84:87]
	v_mfma_f32_16x16x32_bf16 v[80:83], v[178:181], v[202:205], v[80:83]
	v_mfma_f32_16x16x32_bf16 v[68:71], v[170:173], v[210:213], v[68:71]
	v_mfma_f32_16x16x32_bf16 v[64:67], v[178:181], v[210:213], v[64:67]
	s_setprio 0
	s_setprio 1
	v_mfma_f32_16x16x32_bf16 v[60:63], v[144:147], v[220:223], v[60:63]
	v_mfma_f32_16x16x32_bf16 v[56:59], v[158:161], v[220:223], v[56:59]
	v_mfma_f32_16x16x32_bf16 v[44:47], v[144:147], v[228:231], v[44:47]
	v_mfma_f32_16x16x32_bf16 v[40:43], v[158:161], v[228:231], v[40:43]
	v_mfma_f32_16x16x32_bf16 v[28:31], v[144:147], v[236:239], v[28:31]
	v_mfma_f32_16x16x32_bf16 v[24:27], v[158:161], v[236:239], v[24:27]
	v_mfma_f32_16x16x32_bf16 v[12:15], v[144:147], v[244:247], v[12:15]
	v_mfma_f32_16x16x32_bf16 v[8:11], v[158:161], v[244:247], v[8:11]
	v_mfma_f32_16x16x32_bf16 v[60:63], v[154:157], v[224:227], v[60:63]
	v_mfma_f32_16x16x32_bf16 v[56:59], v[162:165], v[224:227], v[56:59]
	v_mfma_f32_16x16x32_bf16 v[44:47], v[154:157], v[232:235], v[44:47]
	v_mfma_f32_16x16x32_bf16 v[40:43], v[162:165], v[232:235], v[40:43]
	v_mfma_f32_16x16x32_bf16 v[28:31], v[154:157], v[240:243], v[28:31]
	v_mfma_f32_16x16x32_bf16 v[24:27], v[162:165], v[240:243], v[24:27]
	v_mfma_f32_16x16x32_bf16 v[12:15], v[154:157], v[248:251], v[12:15]
	v_mfma_f32_16x16x32_bf16 v[8:11], v[162:165], v[248:251], v[8:11]
	s_setprio 0
	s_setprio 1
	v_mfma_f32_16x16x32_bf16 v[52:55], v[166:169], v[220:223], v[52:55]
	v_mfma_f32_16x16x32_bf16 v[48:51], v[174:177], v[220:223], v[48:51]
	v_mfma_f32_16x16x32_bf16 v[36:39], v[166:169], v[228:231], v[36:39]
	v_mfma_f32_16x16x32_bf16 v[32:35], v[174:177], v[228:231], v[32:35]
	v_mfma_f32_16x16x32_bf16 v[20:23], v[166:169], v[236:239], v[20:23]
	v_mfma_f32_16x16x32_bf16 v[16:19], v[174:177], v[236:239], v[16:19]
	v_mfma_f32_16x16x32_bf16 v[4:7], v[166:169], v[244:247], v[4:7]
	v_mfma_f32_16x16x32_bf16 v[0:3], v[174:177], v[244:247], v[0:3]
	v_mfma_f32_16x16x32_bf16 v[52:55], v[170:173], v[224:227], v[52:55]
	v_mfma_f32_16x16x32_bf16 v[48:51], v[178:181], v[224:227], v[48:51]
	v_mfma_f32_16x16x32_bf16 v[36:39], v[170:173], v[232:235], v[36:39]
	v_mfma_f32_16x16x32_bf16 v[32:35], v[178:181], v[232:235], v[32:35]
	v_mfma_f32_16x16x32_bf16 v[20:23], v[170:173], v[240:243], v[20:23]
	v_mfma_f32_16x16x32_bf16 v[16:19], v[178:181], v[240:243], v[16:19]
	v_mfma_f32_16x16x32_bf16 v[4:7], v[170:173], v[248:251], v[4:7]
	v_mfma_f32_16x16x32_bf16 v[0:3], v[178:181], v[248:251], v[0:3]
	s_setprio 0
	s_waitcnt vmcnt(0)
	s_barrier
	s_add_i32 s56, s56, 2
	s_add_u32 s12, s12, 0x100
	s_addc_u32 s13, s13, 0
	s_add_u32 s54, s54, 0x100
	s_addc_u32 s55, s55, 0
	s_cmp_gt_u32 s56, 13
	s_cbranch_scc0 .LBB0_686
	s_branch .Lk64_done_p4
.Lk64_trail_p4:
	s_sub_u32 vcc_lo, s12, 0x40000
	s_subb_u32 vcc_hi, s13, 0
	s_add_i32 m0, s36, 0xa000
	s_nop 0
	global_load_lds_dwordx4 v130, vcc
	s_add_u32 vcc_lo, vcc_lo, 0x10000
	s_addc_u32 vcc_hi, vcc_hi, 0
	s_add_i32 m0, s36, 0x9000
	s_nop 0
	global_load_lds_dwordx4 v134, vcc
	s_add_u32 vcc_lo, vcc_lo, 0x30000
	s_addc_u32 vcc_hi, vcc_hi, 0
	s_add_i32 m0, s36, 0xe000
	s_nop 0
	global_load_lds_dwordx4 v130, vcc
	s_add_u32 vcc_lo, vcc_lo, 0x10000
	s_addc_u32 vcc_hi, vcc_hi, 0
	s_add_i32 m0, s36, 0xd000
	s_nop 0
	global_load_lds_dwordx4 v134, vcc
	s_add_u32 vcc_lo, s34, 0x0
	s_addc_u32 vcc_hi, s35, 0
	s_mov_b32 m0, s36
	s_nop 0
	global_load_lds_dwordx4 v134, vcc
	s_sub_u32 vcc_lo, vcc_lo, 0x10000
	s_subb_u32 vcc_hi, vcc_hi, 0
	s_sub_i32 m0, s36, 0x1000
	s_nop 0
	global_load_lds_dwordx4 v134, vcc
	s_add_u32 vcc_lo, vcc_lo, 0x50000
	s_addc_u32 vcc_hi, vcc_hi, 0
	s_add_i32 m0, s36, 0x4000
	s_nop 0
	global_load_lds_dwordx4 v134, vcc
	s_sub_u32 vcc_lo, vcc_lo, 0x10000
	s_subb_u32 vcc_hi, vcc_hi, 0
	s_add_i32 m0, s36, 0x3000
	s_nop 0
	global_load_lds_dwordx4 v134, vcc
	ds_read_b128 v[144:147], v151 offset:0
	ds_read_b128 v[154:157], v151 offset:1024
	ds_read_b128 v[158:161], v151 offset:2048
	ds_read_b128 v[162:165], v151 offset:3072
	ds_read_b128 v[166:169], v152 offset:0
	ds_read_b128 v[170:173], v152 offset:1024
	ds_read_b128 v[174:177], v152 offset:2048
	ds_read_b128 v[178:181], v152 offset:3072
	ds_read_b128 v[182:185], v153 offset:0
	ds_read_b128 v[186:189], v153 offset:1024
	ds_read_b128 v[190:193], v153 offset:2048
	ds_read_b128 v[194:197], v153 offset:3072
	ds_read_b128 v[198:201], v153 offset:4096
	ds_read_b128 v[202:205], v153 offset:5120
	ds_read_b128 v[206:209], v153 offset:6144
	ds_read_b128 v[210:213], v153 offset:7168
	ds_read_b128 v[220:223], v153 offset:16384
	ds_read_b128 v[224:227], v153 offset:17408
	ds_read_b128 v[228:231], v153 offset:18432
	ds_read_b128 v[232:235], v153 offset:19456
	ds_read_b128 v[236:239], v153 offset:20480
	ds_read_b128 v[240:243], v153 offset:21504
	ds_read_b128 v[244:247], v153 offset:22528
	ds_read_b128 v[248:251], v153 offset:23552
	s_waitcnt lgkmcnt(0)
	s_barrier
	s_setprio 1
	v_mfma_f32_16x16x32_bf16 v[124:127], v[144:147], v[182:185], v[124:127]
	v_mfma_f32_16x16x32_bf16 v[120:123], v[158:161], v[182:185], v[120:123]
	v_mfma_f32_16x16x32_bf16 v[108:111], v[144:147], v[190:193], v[108:111]
	v_mfma_f32_16x16x32_bf16 v[104:107], v[158:161], v[190:193], v[104:107]
	v_mfma_f32_16x16x32_bf16 v[92:95], v[144:147], v[198:201], v[92:95]
	v_mfma_f32_16x16x32_bf16 v[88:91], v[158:161], v[198:201], v[88:91]
	v_mfma_f32_16x16x32_bf16 v[76:79], v[144:147], v[206:209], v[76:79]
	v_mfma_f32_16x16x32_bf16 v[72:75], v[158:161], v[206:209], v[72:75]
	v_mfma_f32_16x16x32_bf16 v[124:127], v[154:157], v[186:189], v[124:127]
	v_mfma_f32_16x16x32_bf16 v[120:123], v[162:165], v[186:189], v[120:123]
	v_mfma_f32_16x16x32_bf16 v[108:111], v[154:157], v[194:197], v[108:111]
	v_mfma_f32_16x16x32_bf16 v[104:107], v[162:165], v[194:197], v[104:107]
	v_mfma_f32_16x16x32_bf16 v[92:95], v[154:157], v[202:205], v[92:95]
	v_mfma_f32_16x16x32_bf16 v[88:91], v[162:165], v[202:205], v[88:91]
	v_mfma_f32_16x16x32_bf16 v[76:79], v[154:157], v[210:213], v[76:79]
	v_mfma_f32_16x16x32_bf16 v[72:75], v[162:165], v[210:213], v[72:75]
	s_setprio 0
	s_setprio 1
	v_mfma_f32_16x16x32_bf16 v[116:119], v[166:169], v[182:185], v[116:119]
	v_mfma_f32_16x16x32_bf16 v[112:115], v[174:177], v[182:185], v[112:115]
	v_mfma_f32_16x16x32_bf16 v[100:103], v[166:169], v[190:193], v[100:103]
	v_mfma_f32_16x16x32_bf16 v[96:99], v[174:177], v[190:193], v[96:99]
	v_mfma_f32_16x16x32_bf16 v[84:87], v[166:169], v[198:201], v[84:87]
	v_mfma_f32_16x16x32_bf16 v[80:83], v[174:177], v[198:201], v[80:83]
	v_mfma_f32_16x16x32_bf16 v[68:71], v[166:169], v[206:209], v[68:71]
	v_mfma_f32_16x16x32_bf16 v[64:67], v[174:177], v[206:209], v[64:67]
	v_mfma_f32_16x16x32_bf16 v[116:119], v[170:173], v[186:189], v[116:119]
	v_mfma_f32_16x16x32_bf16 v[112:115], v[178:181], v[186:189], v[112:115]
	v_mfma_f32_16x16x32_bf16 v[100:103], v[170:173], v[194:197], v[100:103]
	v_mfma_f32_16x16x32_bf16 v[96:99], v[178:181], v[194:197], v[96:99]
	v_mfma_f32_16x16x32_bf16 v[84:87], v[170:173], v[202:205], v[84:87]
	v_mfma_f32_16x16x32_bf16 v[80:83], v[178:181], v[202:205], v[80:83]
	v_mfma_f32_16x16x32_bf16 v[68:71], v[170:173], v[210:213], v[68:71]
	v_mfma_f32_16x16x32_bf16 v[64:67], v[178:181], v[210:213], v[64:67]
	s_setprio 0
	s_setprio 1
	v_mfma_f32_16x16x32_bf16 v[60:63], v[144:147], v[220:223], v[60:63]
	v_mfma_f32_16x16x32_bf16 v[56:59], v[158:161], v[220:223], v[56:59]
	v_mfma_f32_16x16x32_bf16 v[44:47], v[144:147], v[228:231], v[44:47]
	v_mfma_f32_16x16x32_bf16 v[40:43], v[158:161], v[228:231], v[40:43]
	v_mfma_f32_16x16x32_bf16 v[28:31], v[144:147], v[236:239], v[28:31]
	v_mfma_f32_16x16x32_bf16 v[24:27], v[158:161], v[236:239], v[24:27]
	v_mfma_f32_16x16x32_bf16 v[12:15], v[144:147], v[244:247], v[12:15]
	v_mfma_f32_16x16x32_bf16 v[8:11], v[158:161], v[244:247], v[8:11]
	v_mfma_f32_16x16x32_bf16 v[60:63], v[154:157], v[224:227], v[60:63]
	v_mfma_f32_16x16x32_bf16 v[56:59], v[162:165], v[224:227], v[56:59]
	v_mfma_f32_16x16x32_bf16 v[44:47], v[154:157], v[232:235], v[44:47]
	v_mfma_f32_16x16x32_bf16 v[40:43], v[162:165], v[232:235], v[40:43]
	v_mfma_f32_16x16x32_bf16 v[28:31], v[154:157], v[240:243], v[28:31]
	v_mfma_f32_16x16x32_bf16 v[24:27], v[162:165], v[240:243], v[24:27]
	v_mfma_f32_16x16x32_bf16 v[12:15], v[154:157], v[248:251], v[12:15]
	v_mfma_f32_16x16x32_bf16 v[8:11], v[162:165], v[248:251], v[8:11]
	s_setprio 0
	s_setprio 1
	v_mfma_f32_16x16x32_bf16 v[52:55], v[166:169], v[220:223], v[52:55]
	v_mfma_f32_16x16x32_bf16 v[48:51], v[174:177], v[220:223], v[48:51]
	v_mfma_f32_16x16x32_bf16 v[36:39], v[166:169], v[228:231], v[36:39]
	v_mfma_f32_16x16x32_bf16 v[32:35], v[174:177], v[228:231], v[32:35]
	v_mfma_f32_16x16x32_bf16 v[20:23], v[166:169], v[236:239], v[20:23]
	v_mfma_f32_16x16x32_bf16 v[16:19], v[174:177], v[236:239], v[16:19]
	v_mfma_f32_16x16x32_bf16 v[4:7], v[166:169], v[244:247], v[4:7]
	v_mfma_f32_16x16x32_bf16 v[0:3], v[174:177], v[244:247], v[0:3]
	v_mfma_f32_16x16x32_bf16 v[52:55], v[170:173], v[224:227], v[52:55]
	v_mfma_f32_16x16x32_bf16 v[48:51], v[178:181], v[224:227], v[48:51]
	v_mfma_f32_16x16x32_bf16 v[36:39], v[170:173], v[232:235], v[36:39]
	v_mfma_f32_16x16x32_bf16 v[32:35], v[178:181], v[232:235], v[32:35]
	v_mfma_f32_16x16x32_bf16 v[20:23], v[170:173], v[240:243], v[20:23]
	v_mfma_f32_16x16x32_bf16 v[16:19], v[178:181], v[240:243], v[16:19]
	v_mfma_f32_16x16x32_bf16 v[4:7], v[170:173], v[248:251], v[4:7]
	v_mfma_f32_16x16x32_bf16 v[0:3], v[178:181], v[248:251], v[0:3]
	s_setprio 0
	s_waitcnt vmcnt(0)
	s_barrier
	s_add_u32 vcc_lo, s34, 0x0
	s_addc_u32 vcc_hi, s35, 0
	s_add_i32 m0, s36, 0x2000
	s_nop 0
	global_load_lds_dwordx4 v130, vcc
	s_add_u32 vcc_lo, vcc_lo, 0x10000
	s_addc_u32 vcc_hi, vcc_hi, 0
	s_add_i32 m0, s36, 0x1000
	s_nop 0
	global_load_lds_dwordx4 v134, vcc
	s_add_u32 vcc_lo, vcc_lo, 0x30000
	s_addc_u32 vcc_hi, vcc_hi, 0
	s_add_i32 m0, s36, 0x6000
	s_nop 0
	global_load_lds_dwordx4 v130, vcc
	s_add_u32 vcc_lo, vcc_lo, 0x10000
	s_addc_u32 vcc_hi, vcc_hi, 0
	s_add_i32 m0, s36, 0x5000
	s_nop 0
	global_load_lds_dwordx4 v134, vcc
	s_add_u32 vcc_lo, s34, 0x80
	s_addc_u32 vcc_hi, s35, 0
	s_add_i32 m0, s36, 0x8000
	s_nop 0
	global_load_lds_dwordx4 v134, vcc
	s_sub_u32 vcc_lo, vcc_lo, 0x10000
	s_subb_u32 vcc_hi, vcc_hi, 0
	s_add_i32 m0, s36, 0x7000
	s_nop 0
	global_load_lds_dwordx4 v134, vcc
	s_add_u32 vcc_lo, vcc_lo, 0x50000
	s_addc_u32 vcc_hi, vcc_hi, 0
	s_add_i32 m0, s36, 0xc000
	s_nop 0
	global_load_lds_dwordx4 v134, vcc
	s_sub_u32 vcc_lo, vcc_lo, 0x10000
	s_subb_u32 vcc_hi, vcc_hi, 0
	s_add_i32 m0, s36, 0xb000
	s_nop 0
	global_load_lds_dwordx4 v134, vcc
	ds_read_b128 v[144:147], v151 offset:32768
	ds_read_b128 v[154:157], v151 offset:33792
	ds_read_b128 v[158:161], v151 offset:34816
	ds_read_b128 v[162:165], v151 offset:35840
	ds_read_b128 v[166:169], v152 offset:32768
	ds_read_b128 v[170:173], v152 offset:33792
	ds_read_b128 v[174:177], v152 offset:34816
	ds_read_b128 v[178:181], v152 offset:35840
	ds_read_b128 v[182:185], v153 offset:32768
	ds_read_b128 v[186:189], v153 offset:33792
	ds_read_b128 v[190:193], v153 offset:34816
	ds_read_b128 v[194:197], v153 offset:35840
	ds_read_b128 v[198:201], v153 offset:36864
	ds_read_b128 v[202:205], v153 offset:37888
	ds_read_b128 v[206:209], v153 offset:38912
	ds_read_b128 v[210:213], v153 offset:39936
	ds_read_b128 v[220:223], v153 offset:49152
	ds_read_b128 v[224:227], v153 offset:50176
	ds_read_b128 v[228:231], v153 offset:51200
	ds_read_b128 v[232:235], v153 offset:52224
	ds_read_b128 v[236:239], v153 offset:53248
	ds_read_b128 v[240:243], v153 offset:54272
	ds_read_b128 v[244:247], v153 offset:55296
	ds_read_b128 v[248:251], v153 offset:56320
	s_waitcnt lgkmcnt(0)
	s_barrier
	s_setprio 1
	v_mfma_f32_16x16x32_bf16 v[124:127], v[144:147], v[182:185], v[124:127]
	v_mfma_f32_16x16x32_bf16 v[120:123], v[158:161], v[182:185], v[120:123]
	v_mfma_f32_16x16x32_bf16 v[108:111], v[144:147], v[190:193], v[108:111]
	v_mfma_f32_16x16x32_bf16 v[104:107], v[158:161], v[190:193], v[104:107]
	v_mfma_f32_16x16x32_bf16 v[92:95], v[144:147], v[198:201], v[92:95]
	v_mfma_f32_16x16x32_bf16 v[88:91], v[158:161], v[198:201], v[88:91]
	v_mfma_f32_16x16x32_bf16 v[76:79], v[144:147], v[206:209], v[76:79]
	v_mfma_f32_16x16x32_bf16 v[72:75], v[158:161], v[206:209], v[72:75]
	v_mfma_f32_16x16x32_bf16 v[124:127], v[154:157], v[186:189], v[124:127]
	v_mfma_f32_16x16x32_bf16 v[120:123], v[162:165], v[186:189], v[120:123]
	v_mfma_f32_16x16x32_bf16 v[108:111], v[154:157], v[194:197], v[108:111]
	v_mfma_f32_16x16x32_bf16 v[104:107], v[162:165], v[194:197], v[104:107]
	v_mfma_f32_16x16x32_bf16 v[92:95], v[154:157], v[202:205], v[92:95]
	v_mfma_f32_16x16x32_bf16 v[88:91], v[162:165], v[202:205], v[88:91]
	v_mfma_f32_16x16x32_bf16 v[76:79], v[154:157], v[210:213], v[76:79]
	v_mfma_f32_16x16x32_bf16 v[72:75], v[162:165], v[210:213], v[72:75]
	s_setprio 0
	s_setprio 1
	v_mfma_f32_16x16x32_bf16 v[116:119], v[166:169], v[182:185], v[116:119]
	v_mfma_f32_16x16x32_bf16 v[112:115], v[174:177], v[182:185], v[112:115]
	v_mfma_f32_16x16x32_bf16 v[100:103], v[166:169], v[190:193], v[100:103]
	v_mfma_f32_16x16x32_bf16 v[96:99], v[174:177], v[190:193], v[96:99]
	v_mfma_f32_16x16x32_bf16 v[84:87], v[166:169], v[198:201], v[84:87]
	v_mfma_f32_16x16x32_bf16 v[80:83], v[174:177], v[198:201], v[80:83]
	v_mfma_f32_16x16x32_bf16 v[68:71], v[166:169], v[206:209], v[68:71]
	v_mfma_f32_16x16x32_bf16 v[64:67], v[174:177], v[206:209], v[64:67]
	v_mfma_f32_16x16x32_bf16 v[116:119], v[170:173], v[186:189], v[116:119]
	v_mfma_f32_16x16x32_bf16 v[112:115], v[178:181], v[186:189], v[112:115]
	v_mfma_f32_16x16x32_bf16 v[100:103], v[170:173], v[194:197], v[100:103]
	v_mfma_f32_16x16x32_bf16 v[96:99], v[178:181], v[194:197], v[96:99]
	v_mfma_f32_16x16x32_bf16 v[84:87], v[170:173], v[202:205], v[84:87]
	v_mfma_f32_16x16x32_bf16 v[80:83], v[178:181], v[202:205], v[80:83]
	v_mfma_f32_16x16x32_bf16 v[68:71], v[170:173], v[210:213], v[68:71]
	v_mfma_f32_16x16x32_bf16 v[64:67], v[178:181], v[210:213], v[64:67]
	s_setprio 0
	s_setprio 1
	v_mfma_f32_16x16x32_bf16 v[60:63], v[144:147], v[220:223], v[60:63]
	v_mfma_f32_16x16x32_bf16 v[56:59], v[158:161], v[220:223], v[56:59]
	v_mfma_f32_16x16x32_bf16 v[44:47], v[144:147], v[228:231], v[44:47]
	v_mfma_f32_16x16x32_bf16 v[40:43], v[158:161], v[228:231], v[40:43]
	v_mfma_f32_16x16x32_bf16 v[28:31], v[144:147], v[236:239], v[28:31]
	v_mfma_f32_16x16x32_bf16 v[24:27], v[158:161], v[236:239], v[24:27]
	v_mfma_f32_16x16x32_bf16 v[12:15], v[144:147], v[244:247], v[12:15]
	v_mfma_f32_16x16x32_bf16 v[8:11], v[158:161], v[244:247], v[8:11]
	v_mfma_f32_16x16x32_bf16 v[60:63], v[154:157], v[224:227], v[60:63]
	v_mfma_f32_16x16x32_bf16 v[56:59], v[162:165], v[224:227], v[56:59]
	v_mfma_f32_16x16x32_bf16 v[44:47], v[154:157], v[232:235], v[44:47]
	v_mfma_f32_16x16x32_bf16 v[40:43], v[162:165], v[232:235], v[40:43]
	v_mfma_f32_16x16x32_bf16 v[28:31], v[154:157], v[240:243], v[28:31]
	v_mfma_f32_16x16x32_bf16 v[24:27], v[162:165], v[240:243], v[24:27]
	v_mfma_f32_16x16x32_bf16 v[12:15], v[154:157], v[248:251], v[12:15]
	v_mfma_f32_16x16x32_bf16 v[8:11], v[162:165], v[248:251], v[8:11]
	s_setprio 0
	s_setprio 1
	v_mfma_f32_16x16x32_bf16 v[52:55], v[166:169], v[220:223], v[52:55]
	v_mfma_f32_16x16x32_bf16 v[48:51], v[174:177], v[220:223], v[48:51]
	v_mfma_f32_16x16x32_bf16 v[36:39], v[166:169], v[228:231], v[36:39]
	v_mfma_f32_16x16x32_bf16 v[32:35], v[174:177], v[228:231], v[32:35]
	v_mfma_f32_16x16x32_bf16 v[20:23], v[166:169], v[236:239], v[20:23]
	v_mfma_f32_16x16x32_bf16 v[16:19], v[174:177], v[236:239], v[16:19]
	v_mfma_f32_16x16x32_bf16 v[4:7], v[166:169], v[244:247], v[4:7]
	v_mfma_f32_16x16x32_bf16 v[0:3], v[174:177], v[244:247], v[0:3]
	v_mfma_f32_16x16x32_bf16 v[52:55], v[170:173], v[224:227], v[52:55]
	v_mfma_f32_16x16x32_bf16 v[48:51], v[178:181], v[224:227], v[48:51]
	v_mfma_f32_16x16x32_bf16 v[36:39], v[170:173], v[232:235], v[36:39]
	v_mfma_f32_16x16x32_bf16 v[32:35], v[178:181], v[232:235], v[32:35]
	v_mfma_f32_16x16x32_bf16 v[20:23], v[170:173], v[240:243], v[20:23]
	v_mfma_f32_16x16x32_bf16 v[16:19], v[178:181], v[240:243], v[16:19]
	v_mfma_f32_16x16x32_bf16 v[4:7], v[170:173], v[248:251], v[4:7]
	v_mfma_f32_16x16x32_bf16 v[0:3], v[178:181], v[248:251], v[0:3]
	s_setprio 0
	s_waitcnt vmcnt(0)
	s_barrier
	s_add_i32 s56, s56, 2
	s_add_u32 s12, s12, 0x100
	s_addc_u32 s13, s13, 0
	s_add_u32 s54, s54, 0x100
	s_addc_u32 s55, s55, 0
	s_cmp_gt_u32 s56, 13
	s_cbranch_scc0 .LBB0_686

.LBB0_761:
	s_add_u32 s36, s34, 0xfff80080
	s_addc_u32 s37, s35, -1
	s_cmp_eq_u32 s58, 28
	s_cselect_b32 s43, s23, s37
	s_cselect_b32 s42, s29, s36
	s_cselect_b32 s37, s13, s57
	s_cselect_b32 s36, s31, s56
	s_and_b64 vcc, exec, s[10:11]
	s_cbranch_vccz .Lk64_trail_p5
	s_sub_u32 vcc_lo, s56, 0x80
	s_subb_u32 vcc_hi, s57, 0
	s_add_i32 m0, s44, 0x18000
	s_nop 0
	global_load_lds_dwordx4 v130, vcc
	s_add_i32 m0, s44, 0x1a000
	s_nop 0
	global_load_lds_dwordx4 v134, vcc
	s_add_u32 vcc_lo, vcc_lo, 0x20000
	s_addc_u32 vcc_hi, vcc_hi, 0
	s_add_i32 m0, s44, 0x19000
	s_nop 0
	global_load_lds_dwordx4 v130, vcc
	s_add_i32 m0, s44, 0x1b000
	s_nop 0
	global_load_lds_dwordx4 v134, vcc
	s_add_u32 vcc_lo, vcc_lo, 0x60000
	s_addc_u32 vcc_hi, vcc_hi, 0
	s_add_i32 m0, s44, 0x1c000
	s_nop 0
	global_load_lds_dwordx4 v130, vcc
	s_add_i32 m0, s44, 0x1e000
	s_nop 0
	global_load_lds_dwordx4 v134, vcc
	s_add_u32 vcc_lo, vcc_lo, 0x20000
	s_addc_u32 vcc_hi, vcc_hi, 0
	s_add_i32 m0, s44, 0x1d000
	s_nop 0
	global_load_lds_dwordx4 v130, vcc
	s_add_i32 m0, s44, 0x1f000
	s_nop 0
	global_load_lds_dwordx4 v134, vcc
	ds_read_b128 v[144:147], v153 offset:0
	ds_read_b128 v[158:161], v153 offset:1024
	ds_read_b128 v[162:165], v153 offset:2048
	ds_read_b128 v[166:169], v153 offset:3072
	ds_read_b128 v[170:173], v154 offset:0
	ds_read_b128 v[174:177], v154 offset:1024
	ds_read_b128 v[178:181], v154 offset:2048
	ds_read_b128 v[182:185], v154 offset:3072
	ds_read_b128 v[186:189], v155 offset:0
	ds_read_b128 v[190:193], v155 offset:1024
	ds_read_b128 v[194:197], v155 offset:2048
	ds_read_b128 v[198:201], v155 offset:3072
	ds_read_b128 v[202:205], v155 offset:4096
	ds_read_b128 v[206:209], v155 offset:5120
	ds_read_b128 v[210:213], v155 offset:6144
	ds_read_b128 v[214:217], v155 offset:7168
	ds_read_b128 v[220:223], v155 offset:16384
	ds_read_b128 v[224:227], v155 offset:17408
	ds_read_b128 v[228:231], v155 offset:18432
	ds_read_b128 v[232:235], v155 offset:19456
	ds_read_b128 v[236:239], v155 offset:20480
	ds_read_b128 v[240:243], v155 offset:21504
	ds_read_b128 v[244:247], v155 offset:22528
	ds_read_b128 v[248:251], v155 offset:23552
	s_waitcnt lgkmcnt(0)
	s_barrier
	s_setprio 1
	v_mfma_f32_16x16x32_bf16 v[124:127], v[144:147], v[186:189], v[124:127]
	v_mfma_f32_16x16x32_bf16 v[120:123], v[162:165], v[186:189], v[120:123]
	v_mfma_f32_16x16x32_bf16 v[108:111], v[144:147], v[194:197], v[108:111]
	v_mfma_f32_16x16x32_bf16 v[104:107], v[162:165], v[194:197], v[104:107]
	v_mfma_f32_16x16x32_bf16 v[92:95], v[144:147], v[202:205], v[92:95]
	v_mfma_f32_16x16x32_bf16 v[88:91], v[162:165], v[202:205], v[88:91]
	v_mfma_f32_16x16x32_bf16 v[76:79], v[144:147], v[210:213], v[76:79]
	v_mfma_f32_16x16x32_bf16 v[72:75], v[162:165], v[210:213], v[72:75]
	v_mfma_f32_16x16x32_bf16 v[124:127], v[158:161], v[190:193], v[124:127]
	v_mfma_f32_16x16x32_bf16 v[120:123], v[166:169], v[190:193], v[120:123]
	v_mfma_f32_16x16x32_bf16 v[108:111], v[158:161], v[198:201], v[108:111]
	v_mfma_f32_16x16x32_bf16 v[104:107], v[166:169], v[198:201], v[104:107]
	v_mfma_f32_16x16x32_bf16 v[92:95], v[158:161], v[206:209], v[92:95]
	v_mfma_f32_16x16x32_bf16 v[88:91], v[166:169], v[206:209], v[88:91]
	v_mfma_f32_16x16x32_bf16 v[76:79], v[158:161], v[214:217], v[76:79]
	v_mfma_f32_16x16x32_bf16 v[72:75], v[166:169], v[214:217], v[72:75]
	s_setprio 0
	s_setprio 1
	v_mfma_f32_16x16x32_bf16 v[116:119], v[170:173], v[186:189], v[116:119]
	v_mfma_f32_16x16x32_bf16 v[112:115], v[178:181], v[186:189], v[112:115]
	v_mfma_f32_16x16x32_bf16 v[100:103], v[170:173], v[194:197], v[100:103]
	v_mfma_f32_16x16x32_bf16 v[96:99], v[178:181], v[194:197], v[96:99]
	v_mfma_f32_16x16x32_bf16 v[84:87], v[170:173], v[202:205], v[84:87]
	v_mfma_f32_16x16x32_bf16 v[80:83], v[178:181], v[202:205], v[80:83]
	v_mfma_f32_16x16x32_bf16 v[68:71], v[170:173], v[210:213], v[68:71]
	v_mfma_f32_16x16x32_bf16 v[64:67], v[178:181], v[210:213], v[64:67]
	v_mfma_f32_16x16x32_bf16 v[116:119], v[174:177], v[190:193], v[116:119]
	v_mfma_f32_16x16x32_bf16 v[112:115], v[182:185], v[190:193], v[112:115]
	v_mfma_f32_16x16x32_bf16 v[100:103], v[174:177], v[198:201], v[100:103]
	v_mfma_f32_16x16x32_bf16 v[96:99], v[182:185], v[198:201], v[96:99]
	v_mfma_f32_16x16x32_bf16 v[84:87], v[174:177], v[206:209], v[84:87]
	v_mfma_f32_16x16x32_bf16 v[80:83], v[182:185], v[206:209], v[80:83]
	v_mfma_f32_16x16x32_bf16 v[68:71], v[174:177], v[214:217], v[68:71]
	v_mfma_f32_16x16x32_bf16 v[64:67], v[182:185], v[214:217], v[64:67]
	s_setprio 0
	s_setprio 1
	v_mfma_f32_16x16x32_bf16 v[60:63], v[144:147], v[220:223], v[60:63]
	v_mfma_f32_16x16x32_bf16 v[56:59], v[162:165], v[220:223], v[56:59]
	v_mfma_f32_16x16x32_bf16 v[44:47], v[144:147], v[228:231], v[44:47]
	v_mfma_f32_16x16x32_bf16 v[40:43], v[162:165], v[228:231], v[40:43]
	v_mfma_f32_16x16x32_bf16 v[28:31], v[144:147], v[236:239], v[28:31]
	v_mfma_f32_16x16x32_bf16 v[24:27], v[162:165], v[236:239], v[24:27]
	v_mfma_f32_16x16x32_bf16 v[12:15], v[144:147], v[244:247], v[12:15]
	v_mfma_f32_16x16x32_bf16 v[8:11], v[162:165], v[244:247], v[8:11]
	v_mfma_f32_16x16x32_bf16 v[60:63], v[158:161], v[224:227], v[60:63]
	v_mfma_f32_16x16x32_bf16 v[56:59], v[166:169], v[224:227], v[56:59]
	v_mfma_f32_16x16x32_bf16 v[44:47], v[158:161], v[232:235], v[44:47]
	v_mfma_f32_16x16x32_bf16 v[40:43], v[166:169], v[232:235], v[40:43]
	v_mfma_f32_16x16x32_bf16 v[28:31], v[158:161], v[240:243], v[28:31]
	v_mfma_f32_16x16x32_bf16 v[24:27], v[166:169], v[240:243], v[24:27]
	v_mfma_f32_16x16x32_bf16 v[12:15], v[158:161], v[248:251], v[12:15]
	v_mfma_f32_16x16x32_bf16 v[8:11], v[166:169], v[248:251], v[8:11]
	s_setprio 0
	s_setprio 1
	v_mfma_f32_16x16x32_bf16 v[52:55], v[170:173], v[220:223], v[52:55]
	v_mfma_f32_16x16x32_bf16 v[48:51], v[178:181], v[220:223], v[48:51]
	v_mfma_f32_16x16x32_bf16 v[36:39], v[170:173], v[228:231], v[36:39]
	v_mfma_f32_16x16x32_bf16 v[32:35], v[178:181], v[228:231], v[32:35]
	v_mfma_f32_16x16x32_bf16 v[20:23], v[170:173], v[236:239], v[20:23]
	v_mfma_f32_16x16x32_bf16 v[16:19], v[178:181], v[236:239], v[16:19]
	v_mfma_f32_16x16x32_bf16 v[4:7], v[170:173], v[244:247], v[4:7]
	v_mfma_f32_16x16x32_bf16 v[0:3], v[178:181], v[244:247], v[0:3]
	v_mfma_f32_16x16x32_bf16 v[52:55], v[174:177], v[224:227], v[52:55]
	v_mfma_f32_16x16x32_bf16 v[48:51], v[182:185], v[224:227], v[48:51]
	v_mfma_f32_16x16x32_bf16 v[36:39], v[174:177], v[232:235], v[36:39]
	v_mfma_f32_16x16x32_bf16 v[32:35], v[182:185], v[232:235], v[32:35]
	v_mfma_f32_16x16x32_bf16 v[20:23], v[174:177], v[240:243], v[20:23]
	v_mfma_f32_16x16x32_bf16 v[16:19], v[182:185], v[240:243], v[16:19]
	v_mfma_f32_16x16x32_bf16 v[4:7], v[174:177], v[248:251], v[4:7]
	v_mfma_f32_16x16x32_bf16 v[0:3], v[182:185], v[248:251], v[0:3]
	s_setprio 0
	s_waitcnt vmcnt(0)
	s_barrier
	s_add_u32 vcc_lo, s36, 0x0
	s_addc_u32 vcc_hi, s37, 0
	s_add_i32 m0, s44, 0x10000
	s_nop 0
	global_load_lds_dwordx4 v130, vcc
	s_add_i32 m0, s44, 0x12000
	s_nop 0
	global_load_lds_dwordx4 v134, vcc
	s_add_u32 vcc_lo, vcc_lo, 0x20000
	s_addc_u32 vcc_hi, vcc_hi, 0
	s_add_i32 m0, s44, 0x11000
	s_nop 0
	global_load_lds_dwordx4 v130, vcc
	s_add_i32 m0, s44, 0x13000
	s_nop 0
	global_load_lds_dwordx4 v134, vcc
	s_add_u32 vcc_lo, vcc_lo, 0x60000
	s_addc_u32 vcc_hi, vcc_hi, 0
	s_add_i32 m0, s44, 0x14000
	s_nop 0
	global_load_lds_dwordx4 v130, vcc
	s_add_i32 m0, s44, 0x16000
	s_nop 0
	global_load_lds_dwordx4 v134, vcc
	s_add_u32 vcc_lo, vcc_lo, 0x20000
	s_addc_u32 vcc_hi, vcc_hi, 0
	s_add_i32 m0, s44, 0x15000
	s_nop 0
	global_load_lds_dwordx4 v130, vcc
	s_add_i32 m0, s44, 0x17000
	s_nop 0
	global_load_lds_dwordx4 v134, vcc
	ds_read_b128 v[144:147], v153 offset:32768
	ds_read_b128 v[158:161], v153 offset:33792
	ds_read_b128 v[162:165], v153 offset:34816
	ds_read_b128 v[166:169], v153 offset:35840
	ds_read_b128 v[170:173], v154 offset:32768
	ds_read_b128 v[174:177], v154 offset:33792
	ds_read_b128 v[178:181], v154 offset:34816
	ds_read_b128 v[182:185], v154 offset:35840
	ds_read_b128 v[186:189], v155 offset:32768
	ds_read_b128 v[190:193], v155 offset:33792
	ds_read_b128 v[194:197], v155 offset:34816
	ds_read_b128 v[198:201], v155 offset:35840
	ds_read_b128 v[202:205], v155 offset:36864
	ds_read_b128 v[206:209], v155 offset:37888
	ds_read_b128 v[210:213], v155 offset:38912
	ds_read_b128 v[214:217], v155 offset:39936
	ds_read_b128 v[220:223], v155 offset:49152
	ds_read_b128 v[224:227], v155 offset:50176
	ds_read_b128 v[228:231], v155 offset:51200
	ds_read_b128 v[232:235], v155 offset:52224
	ds_read_b128 v[236:239], v155 offset:53248
	ds_read_b128 v[240:243], v155 offset:54272
	ds_read_b128 v[244:247], v155 offset:55296
	ds_read_b128 v[248:251], v155 offset:56320
	s_waitcnt lgkmcnt(0)
	s_barrier
	s_setprio 1
	v_mfma_f32_16x16x32_bf16 v[124:127], v[144:147], v[186:189], v[124:127]
	v_mfma_f32_16x16x32_bf16 v[120:123], v[162:165], v[186:189], v[120:123]
	v_mfma_f32_16x16x32_bf16 v[108:111], v[144:147], v[194:197], v[108:111]
	v_mfma_f32_16x16x32_bf16 v[104:107], v[162:165], v[194:197], v[104:107]
	v_mfma_f32_16x16x32_bf16 v[92:95], v[144:147], v[202:205], v[92:95]
	v_mfma_f32_16x16x32_bf16 v[88:91], v[162:165], v[202:205], v[88:91]
	v_mfma_f32_16x16x32_bf16 v[76:79], v[144:147], v[210:213], v[76:79]
	v_mfma_f32_16x16x32_bf16 v[72:75], v[162:165], v[210:213], v[72:75]
	v_mfma_f32_16x16x32_bf16 v[124:127], v[158:161], v[190:193], v[124:127]
	v_mfma_f32_16x16x32_bf16 v[120:123], v[166:169], v[190:193], v[120:123]
	v_mfma_f32_16x16x32_bf16 v[108:111], v[158:161], v[198:201], v[108:111]
	v_mfma_f32_16x16x32_bf16 v[104:107], v[166:169], v[198:201], v[104:107]
	v_mfma_f32_16x16x32_bf16 v[92:95], v[158:161], v[206:209], v[92:95]
	v_mfma_f32_16x16x32_bf16 v[88:91], v[166:169], v[206:209], v[88:91]
	v_mfma_f32_16x16x32_bf16 v[76:79], v[158:161], v[214:217], v[76:79]
	v_mfma_f32_16x16x32_bf16 v[72:75], v[166:169], v[214:217], v[72:75]
	s_setprio 0
	s_setprio 1
	v_mfma_f32_16x16x32_bf16 v[116:119], v[170:173], v[186:189], v[116:119]
	v_mfma_f32_16x16x32_bf16 v[112:115], v[178:181], v[186:189], v[112:115]
	v_mfma_f32_16x16x32_bf16 v[100:103], v[170:173], v[194:197], v[100:103]
	v_mfma_f32_16x16x32_bf16 v[96:99], v[178:181], v[194:197], v[96:99]
	v_mfma_f32_16x16x32_bf16 v[84:87], v[170:173], v[202:205], v[84:87]
	v_mfma_f32_16x16x32_bf16 v[80:83], v[178:181], v[202:205], v[80:83]
	v_mfma_f32_16x16x32_bf16 v[68:71], v[170:173], v[210:213], v[68:71]
	v_mfma_f32_16x16x32_bf16 v[64:67], v[178:181], v[210:213], v[64:67]
	v_mfma_f32_16x16x32_bf16 v[116:119], v[174:177], v[190:193], v[116:119]
	v_mfma_f32_16x16x32_bf16 v[112:115], v[182:185], v[190:193], v[112:115]
	v_mfma_f32_16x16x32_bf16 v[100:103], v[174:177], v[198:201], v[100:103]
	v_mfma_f32_16x16x32_bf16 v[96:99], v[182:185], v[198:201], v[96:99]
	v_mfma_f32_16x16x32_bf16 v[84:87], v[174:177], v[206:209], v[84:87]
	v_mfma_f32_16x16x32_bf16 v[80:83], v[182:185], v[206:209], v[80:83]
	v_mfma_f32_16x16x32_bf16 v[68:71], v[174:177], v[214:217], v[68:71]
	v_mfma_f32_16x16x32_bf16 v[64:67], v[182:185], v[214:217], v[64:67]
	s_setprio 0
	s_setprio 1
	v_mfma_f32_16x16x32_bf16 v[60:63], v[144:147], v[220:223], v[60:63]
	v_mfma_f32_16x16x32_bf16 v[56:59], v[162:165], v[220:223], v[56:59]
	v_mfma_f32_16x16x32_bf16 v[44:47], v[144:147], v[228:231], v[44:47]
	v_mfma_f32_16x16x32_bf16 v[40:43], v[162:165], v[228:231], v[40:43]
	v_mfma_f32_16x16x32_bf16 v[28:31], v[144:147], v[236:239], v[28:31]
	v_mfma_f32_16x16x32_bf16 v[24:27], v[162:165], v[236:239], v[24:27]
	v_mfma_f32_16x16x32_bf16 v[12:15], v[144:147], v[244:247], v[12:15]
	v_mfma_f32_16x16x32_bf16 v[8:11], v[162:165], v[244:247], v[8:11]
	v_mfma_f32_16x16x32_bf16 v[60:63], v[158:161], v[224:227], v[60:63]
	v_mfma_f32_16x16x32_bf16 v[56:59], v[166:169], v[224:227], v[56:59]
	v_mfma_f32_16x16x32_bf16 v[44:47], v[158:161], v[232:235], v[44:47]
	v_mfma_f32_16x16x32_bf16 v[40:43], v[166:169], v[232:235], v[40:43]
	v_mfma_f32_16x16x32_bf16 v[28:31], v[158:161], v[240:243], v[28:31]
	v_mfma_f32_16x16x32_bf16 v[24:27], v[166:169], v[240:243], v[24:27]
	v_mfma_f32_16x16x32_bf16 v[12:15], v[158:161], v[248:251], v[12:15]
	v_mfma_f32_16x16x32_bf16 v[8:11], v[166:169], v[248:251], v[8:11]
	s_setprio 0
	s_setprio 1
	v_mfma_f32_16x16x32_bf16 v[52:55], v[170:173], v[220:223], v[52:55]
	v_mfma_f32_16x16x32_bf16 v[48:51], v[178:181], v[220:223], v[48:51]
	v_mfma_f32_16x16x32_bf16 v[36:39], v[170:173], v[228:231], v[36:39]
	v_mfma_f32_16x16x32_bf16 v[32:35], v[178:181], v[228:231], v[32:35]
	v_mfma_f32_16x16x32_bf16 v[20:23], v[170:173], v[236:239], v[20:23]
	v_mfma_f32_16x16x32_bf16 v[16:19], v[178:181], v[236:239], v[16:19]
	v_mfma_f32_16x16x32_bf16 v[4:7], v[170:173], v[244:247], v[4:7]
	v_mfma_f32_16x16x32_bf16 v[0:3], v[178:181], v[244:247], v[0:3]
	v_mfma_f32_16x16x32_bf16 v[52:55], v[174:177], v[224:227], v[52:55]
	v_mfma_f32_16x16x32_bf16 v[48:51], v[182:185], v[224:227], v[48:51]
	v_mfma_f32_16x16x32_bf16 v[36:39], v[174:177], v[232:235], v[36:39]
	v_mfma_f32_16x16x32_bf16 v[32:35], v[182:185], v[232:235], v[32:35]
	v_mfma_f32_16x16x32_bf16 v[20:23], v[174:177], v[240:243], v[20:23]
	v_mfma_f32_16x16x32_bf16 v[16:19], v[182:185], v[240:243], v[16:19]
	v_mfma_f32_16x16x32_bf16 v[4:7], v[174:177], v[248:251], v[4:7]
	v_mfma_f32_16x16x32_bf16 v[0:3], v[182:185], v[248:251], v[0:3]
	s_setprio 0
	s_waitcnt vmcnt(0)
	s_barrier
	s_add_i32 s58, s58, 2
	s_add_u32 s34, s34, 0x100
	s_addc_u32 s35, s35, 0
	s_add_u32 s56, s56, 0x100
	s_addc_u32 s57, s57, 0
	s_cmp_gt_u32 s58, 29
	s_cbranch_scc0 .LBB0_761
	s_branch .Lk64_done_p5
.Lk64_trail_p5:
	s_sub_u32 vcc_lo, s34, 0x80000
	s_subb_u32 vcc_hi, s35, 0
	s_add_i32 m0, s44, 0xa000
	s_nop 0
	global_load_lds_dwordx4 v132, vcc
	s_add_u32 vcc_lo, vcc_lo, 0x20000
	s_addc_u32 vcc_hi, vcc_hi, 0
	s_add_i32 m0, s44, 0x9000
	s_nop 0
	global_load_lds_dwordx4 v128, vcc
	s_add_u32 vcc_lo, vcc_lo, 0x60000
	s_addc_u32 vcc_hi, vcc_hi, 0
	s_add_i32 m0, s44, 0xe000
	s_nop 0
	global_load_lds_dwordx4 v132, vcc
	s_add_u32 vcc_lo, vcc_lo, 0x20000
	s_addc_u32 vcc_hi, vcc_hi, 0
	s_add_i32 m0, s44, 0xd000
	s_nop 0
	global_load_lds_dwordx4 v128, vcc
	s_add_u32 vcc_lo, s42, 0x0
	s_addc_u32 vcc_hi, s43, 0
	s_mov_b32 m0, s44
	s_nop 0
	global_load_lds_dwordx4 v128, vcc
	s_sub_u32 vcc_lo, vcc_lo, 0x20000
	s_subb_u32 vcc_hi, vcc_hi, 0
	s_sub_i32 m0, s44, 0x1000
	s_nop 0
	global_load_lds_dwordx4 v128, vcc
	s_add_u32 vcc_lo, vcc_lo, 0xa0000
	s_addc_u32 vcc_hi, vcc_hi, 0
	s_add_i32 m0, s44, 0x4000
	s_nop 0
	global_load_lds_dwordx4 v128, vcc
	s_sub_u32 vcc_lo, vcc_lo, 0x20000
	s_subb_u32 vcc_hi, vcc_hi, 0
	s_add_i32 m0, s44, 0x3000
	s_nop 0
	global_load_lds_dwordx4 v128, vcc
	ds_read_b128 v[144:147], v153 offset:0
	ds_read_b128 v[158:161], v153 offset:1024
	ds_read_b128 v[162:165], v153 offset:2048
	ds_read_b128 v[166:169], v153 offset:3072
	ds_read_b128 v[170:173], v154 offset:0
	ds_read_b128 v[174:177], v154 offset:1024
	ds_read_b128 v[178:181], v154 offset:2048
	ds_read_b128 v[182:185], v154 offset:3072
	ds_read_b128 v[186:189], v155 offset:0
	ds_read_b128 v[190:193], v155 offset:1024
	ds_read_b128 v[194:197], v155 offset:2048
	ds_read_b128 v[198:201], v155 offset:3072
	ds_read_b128 v[202:205], v155 offset:4096
	ds_read_b128 v[206:209], v155 offset:5120
	ds_read_b128 v[210:213], v155 offset:6144
	ds_read_b128 v[214:217], v155 offset:7168
	ds_read_b128 v[220:223], v155 offset:16384
	ds_read_b128 v[224:227], v155 offset:17408
	ds_read_b128 v[228:231], v155 offset:18432
	ds_read_b128 v[232:235], v155 offset:19456
	ds_read_b128 v[236:239], v155 offset:20480
	ds_read_b128 v[240:243], v155 offset:21504
	ds_read_b128 v[244:247], v155 offset:22528
	ds_read_b128 v[248:251], v155 offset:23552
	s_waitcnt lgkmcnt(0)
	s_barrier
	s_setprio 1
	v_mfma_f32_16x16x32_bf16 v[124:127], v[144:147], v[186:189], v[124:127]
	v_mfma_f32_16x16x32_bf16 v[120:123], v[162:165], v[186:189], v[120:123]
	v_mfma_f32_16x16x32_bf16 v[108:111], v[144:147], v[194:197], v[108:111]
	v_mfma_f32_16x16x32_bf16 v[104:107], v[162:165], v[194:197], v[104:107]
	v_mfma_f32_16x16x32_bf16 v[92:95], v[144:147], v[202:205], v[92:95]
	v_mfma_f32_16x16x32_bf16 v[88:91], v[162:165], v[202:205], v[88:91]
	v_mfma_f32_16x16x32_bf16 v[76:79], v[144:147], v[210:213], v[76:79]
	v_mfma_f32_16x16x32_bf16 v[72:75], v[162:165], v[210:213], v[72:75]
	v_mfma_f32_16x16x32_bf16 v[124:127], v[158:161], v[190:193], v[124:127]
	v_mfma_f32_16x16x32_bf16 v[120:123], v[166:169], v[190:193], v[120:123]
	v_mfma_f32_16x16x32_bf16 v[108:111], v[158:161], v[198:201], v[108:111]
	v_mfma_f32_16x16x32_bf16 v[104:107], v[166:169], v[198:201], v[104:107]
	v_mfma_f32_16x16x32_bf16 v[92:95], v[158:161], v[206:209], v[92:95]
	v_mfma_f32_16x16x32_bf16 v[88:91], v[166:169], v[206:209], v[88:91]
	v_mfma_f32_16x16x32_bf16 v[76:79], v[158:161], v[214:217], v[76:79]
	v_mfma_f32_16x16x32_bf16 v[72:75], v[166:169], v[214:217], v[72:75]
	s_setprio 0
	s_setprio 1
	v_mfma_f32_16x16x32_bf16 v[116:119], v[170:173], v[186:189], v[116:119]
	v_mfma_f32_16x16x32_bf16 v[112:115], v[178:181], v[186:189], v[112:115]
	v_mfma_f32_16x16x32_bf16 v[100:103], v[170:173], v[194:197], v[100:103]
	v_mfma_f32_16x16x32_bf16 v[96:99], v[178:181], v[194:197], v[96:99]
	v_mfma_f32_16x16x32_bf16 v[84:87], v[170:173], v[202:205], v[84:87]
	v_mfma_f32_16x16x32_bf16 v[80:83], v[178:181], v[202:205], v[80:83]
	v_mfma_f32_16x16x32_bf16 v[68:71], v[170:173], v[210:213], v[68:71]
	v_mfma_f32_16x16x32_bf16 v[64:67], v[178:181], v[210:213], v[64:67]
	v_mfma_f32_16x16x32_bf16 v[116:119], v[174:177], v[190:193], v[116:119]
	v_mfma_f32_16x16x32_bf16 v[112:115], v[182:185], v[190:193], v[112:115]
	v_mfma_f32_16x16x32_bf16 v[100:103], v[174:177], v[198:201], v[100:103]
	v_mfma_f32_16x16x32_bf16 v[96:99], v[182:185], v[198:201], v[96:99]
	v_mfma_f32_16x16x32_bf16 v[84:87], v[174:177], v[206:209], v[84:87]
	v_mfma_f32_16x16x32_bf16 v[80:83], v[182:185], v[206:209], v[80:83]
	v_mfma_f32_16x16x32_bf16 v[68:71], v[174:177], v[214:217], v[68:71]
	v_mfma_f32_16x16x32_bf16 v[64:67], v[182:185], v[214:217], v[64:67]
	s_setprio 0
	s_setprio 1
	v_mfma_f32_16x16x32_bf16 v[60:63], v[144:147], v[220:223], v[60:63]
	v_mfma_f32_16x16x32_bf16 v[56:59], v[162:165], v[220:223], v[56:59]
	v_mfma_f32_16x16x32_bf16 v[44:47], v[144:147], v[228:231], v[44:47]
	v_mfma_f32_16x16x32_bf16 v[40:43], v[162:165], v[228:231], v[40:43]
	v_mfma_f32_16x16x32_bf16 v[28:31], v[144:147], v[236:239], v[28:31]
	v_mfma_f32_16x16x32_bf16 v[24:27], v[162:165], v[236:239], v[24:27]
	v_mfma_f32_16x16x32_bf16 v[12:15], v[144:147], v[244:247], v[12:15]
	v_mfma_f32_16x16x32_bf16 v[8:11], v[162:165], v[244:247], v[8:11]
	v_mfma_f32_16x16x32_bf16 v[60:63], v[158:161], v[224:227], v[60:63]
	v_mfma_f32_16x16x32_bf16 v[56:59], v[166:169], v[224:227], v[56:59]
	v_mfma_f32_16x16x32_bf16 v[44:47], v[158:161], v[232:235], v[44:47]
	v_mfma_f32_16x16x32_bf16 v[40:43], v[166:169], v[232:235], v[40:43]
	v_mfma_f32_16x16x32_bf16 v[28:31], v[158:161], v[240:243], v[28:31]
	v_mfma_f32_16x16x32_bf16 v[24:27], v[166:169], v[240:243], v[24:27]
	v_mfma_f32_16x16x32_bf16 v[12:15], v[158:161], v[248:251], v[12:15]
	v_mfma_f32_16x16x32_bf16 v[8:11], v[166:169], v[248:251], v[8:11]
	s_setprio 0
	s_setprio 1
	v_mfma_f32_16x16x32_bf16 v[52:55], v[170:173], v[220:223], v[52:55]
	v_mfma_f32_16x16x32_bf16 v[48:51], v[178:181], v[220:223], v[48:51]
	v_mfma_f32_16x16x32_bf16 v[36:39], v[170:173], v[228:231], v[36:39]
	v_mfma_f32_16x16x32_bf16 v[32:35], v[178:181], v[228:231], v[32:35]
	v_mfma_f32_16x16x32_bf16 v[20:23], v[170:173], v[236:239], v[20:23]
	v_mfma_f32_16x16x32_bf16 v[16:19], v[178:181], v[236:239], v[16:19]
	v_mfma_f32_16x16x32_bf16 v[4:7], v[170:173], v[244:247], v[4:7]
	v_mfma_f32_16x16x32_bf16 v[0:3], v[178:181], v[244:247], v[0:3]
	v_mfma_f32_16x16x32_bf16 v[52:55], v[174:177], v[224:227], v[52:55]
	v_mfma_f32_16x16x32_bf16 v[48:51], v[182:185], v[224:227], v[48:51]
	v_mfma_f32_16x16x32_bf16 v[36:39], v[174:177], v[232:235], v[36:39]
	v_mfma_f32_16x16x32_bf16 v[32:35], v[182:185], v[232:235], v[32:35]
	v_mfma_f32_16x16x32_bf16 v[20:23], v[174:177], v[240:243], v[20:23]
	v_mfma_f32_16x16x32_bf16 v[16:19], v[182:185], v[240:243], v[16:19]
	v_mfma_f32_16x16x32_bf16 v[4:7], v[174:177], v[248:251], v[4:7]
	v_mfma_f32_16x16x32_bf16 v[0:3], v[182:185], v[248:251], v[0:3]
	s_setprio 0
	s_waitcnt vmcnt(0)
	s_barrier
	s_add_u32 vcc_lo, s42, 0x0
	s_addc_u32 vcc_hi, s43, 0
	s_add_i32 m0, s44, 0x2000
	s_nop 0
	global_load_lds_dwordx4 v132, vcc
	s_add_u32 vcc_lo, vcc_lo, 0x20000
	s_addc_u32 vcc_hi, vcc_hi, 0
	s_add_i32 m0, s44, 0x1000
	s_nop 0
	global_load_lds_dwordx4 v128, vcc
	s_add_u32 vcc_lo, vcc_lo, 0x60000
	s_addc_u32 vcc_hi, vcc_hi, 0
	s_add_i32 m0, s44, 0x6000
	s_nop 0
	global_load_lds_dwordx4 v132, vcc
	s_add_u32 vcc_lo, vcc_lo, 0x20000
	s_addc_u32 vcc_hi, vcc_hi, 0
	s_add_i32 m0, s44, 0x5000
	s_nop 0
	global_load_lds_dwordx4 v128, vcc
	s_add_u32 vcc_lo, s42, 0x80
	s_addc_u32 vcc_hi, s43, 0
	s_add_i32 m0, s44, 0x8000
	s_nop 0
	global_load_lds_dwordx4 v128, vcc
	s_sub_u32 vcc_lo, vcc_lo, 0x20000
	s_subb_u32 vcc_hi, vcc_hi, 0
	s_add_i32 m0, s44, 0x7000
	s_nop 0
	global_load_lds_dwordx4 v128, vcc
	s_add_u32 vcc_lo, vcc_lo, 0xa0000
	s_addc_u32 vcc_hi, vcc_hi, 0
	s_add_i32 m0, s44, 0xc000
	s_nop 0
	global_load_lds_dwordx4 v128, vcc
	s_sub_u32 vcc_lo, vcc_lo, 0x20000
	s_subb_u32 vcc_hi, vcc_hi, 0
	s_add_i32 m0, s44, 0xb000
	s_nop 0
	global_load_lds_dwordx4 v128, vcc
	ds_read_b128 v[144:147], v153 offset:32768
	ds_read_b128 v[158:161], v153 offset:33792
	ds_read_b128 v[162:165], v153 offset:34816
	ds_read_b128 v[166:169], v153 offset:35840
	ds_read_b128 v[170:173], v154 offset:32768
	ds_read_b128 v[174:177], v154 offset:33792
	ds_read_b128 v[178:181], v154 offset:34816
	ds_read_b128 v[182:185], v154 offset:35840
	ds_read_b128 v[186:189], v155 offset:32768
	ds_read_b128 v[190:193], v155 offset:33792
	ds_read_b128 v[194:197], v155 offset:34816
	ds_read_b128 v[198:201], v155 offset:35840
	ds_read_b128 v[202:205], v155 offset:36864
	ds_read_b128 v[206:209], v155 offset:37888
	ds_read_b128 v[210:213], v155 offset:38912
	ds_read_b128 v[214:217], v155 offset:39936
	ds_read_b128 v[220:223], v155 offset:49152
	ds_read_b128 v[224:227], v155 offset:50176
	ds_read_b128 v[228:231], v155 offset:51200
	ds_read_b128 v[232:235], v155 offset:52224
	ds_read_b128 v[236:239], v155 offset:53248
	ds_read_b128 v[240:243], v155 offset:54272
	ds_read_b128 v[244:247], v155 offset:55296
	ds_read_b128 v[248:251], v155 offset:56320
	s_waitcnt lgkmcnt(0)
	s_barrier
	s_setprio 1
	v_mfma_f32_16x16x32_bf16 v[124:127], v[144:147], v[186:189], v[124:127]
	v_mfma_f32_16x16x32_bf16 v[120:123], v[162:165], v[186:189], v[120:123]
	v_mfma_f32_16x16x32_bf16 v[108:111], v[144:147], v[194:197], v[108:111]
	v_mfma_f32_16x16x32_bf16 v[104:107], v[162:165], v[194:197], v[104:107]
	v_mfma_f32_16x16x32_bf16 v[92:95], v[144:147], v[202:205], v[92:95]
	v_mfma_f32_16x16x32_bf16 v[88:91], v[162:165], v[202:205], v[88:91]
	v_mfma_f32_16x16x32_bf16 v[76:79], v[144:147], v[210:213], v[76:79]
	v_mfma_f32_16x16x32_bf16 v[72:75], v[162:165], v[210:213], v[72:75]
	v_mfma_f32_16x16x32_bf16 v[124:127], v[158:161], v[190:193], v[124:127]
	v_mfma_f32_16x16x32_bf16 v[120:123], v[166:169], v[190:193], v[120:123]
	v_mfma_f32_16x16x32_bf16 v[108:111], v[158:161], v[198:201], v[108:111]
	v_mfma_f32_16x16x32_bf16 v[104:107], v[166:169], v[198:201], v[104:107]
	v_mfma_f32_16x16x32_bf16 v[92:95], v[158:161], v[206:209], v[92:95]
	v_mfma_f32_16x16x32_bf16 v[88:91], v[166:169], v[206:209], v[88:91]
	v_mfma_f32_16x16x32_bf16 v[76:79], v[158:161], v[214:217], v[76:79]
	v_mfma_f32_16x16x32_bf16 v[72:75], v[166:169], v[214:217], v[72:75]
	s_setprio 0
	s_setprio 1
	v_mfma_f32_16x16x32_bf16 v[116:119], v[170:173], v[186:189], v[116:119]
	v_mfma_f32_16x16x32_bf16 v[112:115], v[178:181], v[186:189], v[112:115]
	v_mfma_f32_16x16x32_bf16 v[100:103], v[170:173], v[194:197], v[100:103]
	v_mfma_f32_16x16x32_bf16 v[96:99], v[178:181], v[194:197], v[96:99]
	v_mfma_f32_16x16x32_bf16 v[84:87], v[170:173], v[202:205], v[84:87]
	v_mfma_f32_16x16x32_bf16 v[80:83], v[178:181], v[202:205], v[80:83]
	v_mfma_f32_16x16x32_bf16 v[68:71], v[170:173], v[210:213], v[68:71]
	v_mfma_f32_16x16x32_bf16 v[64:67], v[178:181], v[210:213], v[64:67]
	v_mfma_f32_16x16x32_bf16 v[116:119], v[174:177], v[190:193], v[116:119]
	v_mfma_f32_16x16x32_bf16 v[112:115], v[182:185], v[190:193], v[112:115]
	v_mfma_f32_16x16x32_bf16 v[100:103], v[174:177], v[198:201], v[100:103]
	v_mfma_f32_16x16x32_bf16 v[96:99], v[182:185], v[198:201], v[96:99]
	v_mfma_f32_16x16x32_bf16 v[84:87], v[174:177], v[206:209], v[84:87]
	v_mfma_f32_16x16x32_bf16 v[80:83], v[182:185], v[206:209], v[80:83]
	v_mfma_f32_16x16x32_bf16 v[68:71], v[174:177], v[214:217], v[68:71]
	v_mfma_f32_16x16x32_bf16 v[64:67], v[182:185], v[214:217], v[64:67]
	s_setprio 0
	s_setprio 1
	v_mfma_f32_16x16x32_bf16 v[60:63], v[144:147], v[220:223], v[60:63]
	v_mfma_f32_16x16x32_bf16 v[56:59], v[162:165], v[220:223], v[56:59]
	v_mfma_f32_16x16x32_bf16 v[44:47], v[144:147], v[228:231], v[44:47]
	v_mfma_f32_16x16x32_bf16 v[40:43], v[162:165], v[228:231], v[40:43]
	v_mfma_f32_16x16x32_bf16 v[28:31], v[144:147], v[236:239], v[28:31]
	v_mfma_f32_16x16x32_bf16 v[24:27], v[162:165], v[236:239], v[24:27]
	v_mfma_f32_16x16x32_bf16 v[12:15], v[144:147], v[244:247], v[12:15]
	v_mfma_f32_16x16x32_bf16 v[8:11], v[162:165], v[244:247], v[8:11]
	v_mfma_f32_16x16x32_bf16 v[60:63], v[158:161], v[224:227], v[60:63]
	v_mfma_f32_16x16x32_bf16 v[56:59], v[166:169], v[224:227], v[56:59]
	v_mfma_f32_16x16x32_bf16 v[44:47], v[158:161], v[232:235], v[44:47]
	v_mfma_f32_16x16x32_bf16 v[40:43], v[166:169], v[232:235], v[40:43]
	v_mfma_f32_16x16x32_bf16 v[28:31], v[158:161], v[240:243], v[28:31]
	v_mfma_f32_16x16x32_bf16 v[24:27], v[166:169], v[240:243], v[24:27]
	v_mfma_f32_16x16x32_bf16 v[12:15], v[158:161], v[248:251], v[12:15]
	v_mfma_f32_16x16x32_bf16 v[8:11], v[166:169], v[248:251], v[8:11]
	s_setprio 0
	s_setprio 1
	v_mfma_f32_16x16x32_bf16 v[52:55], v[170:173], v[220:223], v[52:55]
	v_mfma_f32_16x16x32_bf16 v[48:51], v[178:181], v[220:223], v[48:51]
	v_mfma_f32_16x16x32_bf16 v[36:39], v[170:173], v[228:231], v[36:39]
	v_mfma_f32_16x16x32_bf16 v[32:35], v[178:181], v[228:231], v[32:35]
	v_mfma_f32_16x16x32_bf16 v[20:23], v[170:173], v[236:239], v[20:23]
	v_mfma_f32_16x16x32_bf16 v[16:19], v[178:181], v[236:239], v[16:19]
	v_mfma_f32_16x16x32_bf16 v[4:7], v[170:173], v[244:247], v[4:7]
	v_mfma_f32_16x16x32_bf16 v[0:3], v[178:181], v[244:247], v[0:3]
	v_mfma_f32_16x16x32_bf16 v[52:55], v[174:177], v[224:227], v[52:55]
	v_mfma_f32_16x16x32_bf16 v[48:51], v[182:185], v[224:227], v[48:51]
	v_mfma_f32_16x16x32_bf16 v[36:39], v[174:177], v[232:235], v[36:39]
	v_mfma_f32_16x16x32_bf16 v[32:35], v[182:185], v[232:235], v[32:35]
	v_mfma_f32_16x16x32_bf16 v[20:23], v[174:177], v[240:243], v[20:23]
	v_mfma_f32_16x16x32_bf16 v[16:19], v[182:185], v[240:243], v[16:19]
	v_mfma_f32_16x16x32_bf16 v[4:7], v[174:177], v[248:251], v[4:7]
	v_mfma_f32_16x16x32_bf16 v[0:3], v[182:185], v[248:251], v[0:3]
	s_setprio 0
	s_waitcnt vmcnt(0)
	s_barrier
	s_add_i32 s58, s58, 2
	s_add_u32 s34, s34, 0x100
	s_addc_u32 s35, s35, 0
	s_add_u32 s56, s56, 0x100
	s_addc_u32 s57, s57, 0
	s_cmp_gt_u32 s58, 29
	s_cbranch_scc0 .LBB0_761

.Lk64_epd_p6_l:
	ds_read_b128 v[32:35], v169 offset:0
	ds_read_b128 v[36:39], v169 offset:1024
	ds_read_b128 v[40:43], v169 offset:2048
	ds_read_b128 v[44:47], v169 offset:3072
	ds_read_b128 v[162:165], v170 offset:0
	ds_read_b128 v[174:177], v170 offset:1024
	ds_read_b128 v[178:181], v170 offset:2048
	ds_read_b128 v[182:185], v170 offset:3072
	ds_read_b128 v[186:189], v171 offset:0
	ds_read_b128 v[190:193], v171 offset:1024
	ds_read_b128 v[194:197], v171 offset:2048
	ds_read_b128 v[198:201], v171 offset:3072
	ds_read_b128 v[202:205], v171 offset:4096
	ds_read_b128 v[206:209], v171 offset:5120
	ds_read_b128 v[210:213], v171 offset:6144
	ds_read_b128 v[214:217], v171 offset:7168
	ds_read_b128 v[220:223], v171 offset:16384
	ds_read_b128 v[224:227], v171 offset:17408
	ds_read_b128 v[228:231], v171 offset:18432
	ds_read_b128 v[232:235], v171 offset:19456
	ds_read_b128 v[236:239], v171 offset:20480
	ds_read_b128 v[240:243], v171 offset:21504
	ds_read_b128 v[244:247], v171 offset:22528
	ds_read_b128 v[248:251], v171 offset:23552
	s_waitcnt lgkmcnt(0)
	s_barrier
	s_setprio 1
	v_mfma_f32_16x16x32_bf16 v[140:143], v[32:35], v[186:189], v[140:143]
	v_mfma_f32_16x16x32_bf16 v[136:139], v[40:43], v[186:189], v[136:139]
	v_mfma_f32_16x16x32_bf16 v[124:127], v[32:35], v[194:197], v[124:127]
	v_mfma_f32_16x16x32_bf16 v[120:123], v[40:43], v[194:197], v[120:123]
	v_mfma_f32_16x16x32_bf16 v[108:111], v[32:35], v[202:205], v[108:111]
	v_mfma_f32_16x16x32_bf16 v[104:107], v[40:43], v[202:205], v[104:107]
	v_mfma_f32_16x16x32_bf16 v[92:95], v[32:35], v[210:213], v[92:95]
	v_mfma_f32_16x16x32_bf16 v[88:91], v[40:43], v[210:213], v[88:91]
	v_mfma_f32_16x16x32_bf16 v[140:143], v[36:39], v[190:193], v[140:143]
	v_mfma_f32_16x16x32_bf16 v[136:139], v[44:47], v[190:193], v[136:139]
	v_mfma_f32_16x16x32_bf16 v[124:127], v[36:39], v[198:201], v[124:127]
	v_mfma_f32_16x16x32_bf16 v[120:123], v[44:47], v[198:201], v[120:123]
	v_mfma_f32_16x16x32_bf16 v[108:111], v[36:39], v[206:209], v[108:111]
	v_mfma_f32_16x16x32_bf16 v[104:107], v[44:47], v[206:209], v[104:107]
	v_mfma_f32_16x16x32_bf16 v[92:95], v[36:39], v[214:217], v[92:95]
	v_mfma_f32_16x16x32_bf16 v[88:91], v[44:47], v[214:217], v[88:91]
	s_setprio 0
	s_setprio 1
	v_mfma_f32_16x16x32_bf16 v[132:135], v[162:165], v[186:189], v[132:135]
	v_mfma_f32_16x16x32_bf16 v[128:131], v[178:181], v[186:189], v[128:131]
	v_mfma_f32_16x16x32_bf16 v[116:119], v[162:165], v[194:197], v[116:119]
	v_mfma_f32_16x16x32_bf16 v[112:115], v[178:181], v[194:197], v[112:115]
	v_mfma_f32_16x16x32_bf16 v[100:103], v[162:165], v[202:205], v[100:103]
	v_mfma_f32_16x16x32_bf16 v[96:99], v[178:181], v[202:205], v[96:99]
	v_mfma_f32_16x16x32_bf16 v[84:87], v[162:165], v[210:213], v[84:87]
	v_mfma_f32_16x16x32_bf16 v[80:83], v[178:181], v[210:213], v[80:83]
	v_mfma_f32_16x16x32_bf16 v[132:135], v[174:177], v[190:193], v[132:135]
	v_mfma_f32_16x16x32_bf16 v[128:131], v[182:185], v[190:193], v[128:131]
	v_mfma_f32_16x16x32_bf16 v[116:119], v[174:177], v[198:201], v[116:119]
	v_mfma_f32_16x16x32_bf16 v[112:115], v[182:185], v[198:201], v[112:115]
	v_mfma_f32_16x16x32_bf16 v[100:103], v[174:177], v[206:209], v[100:103]
	v_mfma_f32_16x16x32_bf16 v[96:99], v[182:185], v[206:209], v[96:99]
	v_mfma_f32_16x16x32_bf16 v[84:87], v[174:177], v[214:217], v[84:87]
	v_mfma_f32_16x16x32_bf16 v[80:83], v[182:185], v[214:217], v[80:83]
	s_setprio 0
	s_setprio 1
	v_mfma_f32_16x16x32_bf16 v[76:79], v[32:35], v[220:223], v[76:79]
	v_mfma_f32_16x16x32_bf16 v[72:75], v[40:43], v[220:223], v[72:75]
	v_mfma_f32_16x16x32_bf16 v[60:63], v[32:35], v[228:231], v[60:63]
	v_mfma_f32_16x16x32_bf16 v[56:59], v[40:43], v[228:231], v[56:59]
	v_mfma_f32_16x16x32_bf16 v[28:31], v[32:35], v[236:239], v[28:31]
	v_mfma_f32_16x16x32_bf16 v[24:27], v[40:43], v[236:239], v[24:27]
	v_mfma_f32_16x16x32_bf16 v[12:15], v[32:35], v[244:247], v[12:15]
	v_mfma_f32_16x16x32_bf16 v[8:11], v[40:43], v[244:247], v[8:11]
	v_mfma_f32_16x16x32_bf16 v[76:79], v[36:39], v[224:227], v[76:79]
	v_mfma_f32_16x16x32_bf16 v[72:75], v[44:47], v[224:227], v[72:75]
	v_mfma_f32_16x16x32_bf16 v[60:63], v[36:39], v[232:235], v[60:63]
	v_mfma_f32_16x16x32_bf16 v[56:59], v[44:47], v[232:235], v[56:59]
	v_mfma_f32_16x16x32_bf16 v[28:31], v[36:39], v[240:243], v[28:31]
	v_mfma_f32_16x16x32_bf16 v[24:27], v[44:47], v[240:243], v[24:27]
	v_mfma_f32_16x16x32_bf16 v[12:15], v[36:39], v[248:251], v[12:15]
	v_mfma_f32_16x16x32_bf16 v[8:11], v[44:47], v[248:251], v[8:11]
	s_setprio 0
	s_setprio 1
	v_mfma_f32_16x16x32_bf16 v[68:71], v[162:165], v[220:223], v[68:71]
	v_mfma_f32_16x16x32_bf16 v[64:67], v[178:181], v[220:223], v[64:67]
	v_mfma_f32_16x16x32_bf16 v[52:55], v[162:165], v[228:231], v[52:55]
	v_mfma_f32_16x16x32_bf16 v[48:51], v[178:181], v[228:231], v[48:51]
	v_mfma_f32_16x16x32_bf16 v[20:23], v[162:165], v[236:239], v[20:23]
	v_mfma_f32_16x16x32_bf16 v[16:19], v[178:181], v[236:239], v[16:19]
	v_mfma_f32_16x16x32_bf16 v[4:7], v[162:165], v[244:247], v[4:7]
	v_mfma_f32_16x16x32_bf16 v[0:3], v[178:181], v[244:247], v[0:3]
	v_mfma_f32_16x16x32_bf16 v[68:71], v[174:177], v[224:227], v[68:71]
	v_mfma_f32_16x16x32_bf16 v[64:67], v[182:185], v[224:227], v[64:67]
	v_mfma_f32_16x16x32_bf16 v[52:55], v[174:177], v[232:235], v[52:55]
	v_mfma_f32_16x16x32_bf16 v[48:51], v[182:185], v[232:235], v[48:51]
	v_mfma_f32_16x16x32_bf16 v[20:23], v[174:177], v[240:243], v[20:23]
	v_mfma_f32_16x16x32_bf16 v[16:19], v[182:185], v[240:243], v[16:19]
	v_mfma_f32_16x16x32_bf16 v[4:7], v[174:177], v[248:251], v[4:7]
	v_mfma_f32_16x16x32_bf16 v[0:3], v[182:185], v[248:251], v[0:3]
	s_setprio 0
	s_waitcnt vmcnt(0)
	s_barrier
	s_add_u32 vcc_lo, s30, 0x0
	s_addc_u32 vcc_hi, s31, 0
	s_add_i32 m0, s37, 0x10000
	s_nop 0
	global_load_lds_dwordx4 v148, vcc
	s_add_i32 m0, s37, 0x12000
	s_nop 0
	global_load_lds_dwordx4 v144, vcc
	s_add_u32 vcc_lo, vcc_lo, 0x20000
	s_addc_u32 vcc_hi, vcc_hi, 0
	s_add_i32 m0, s37, 0x11000
	s_nop 0
	global_load_lds_dwordx4 v148, vcc
	s_add_i32 m0, s37, 0x13000
	s_nop 0
	global_load_lds_dwordx4 v144, vcc
	s_add_u32 vcc_lo, vcc_lo, 0x60000
	s_addc_u32 vcc_hi, vcc_hi, 0
	s_add_i32 m0, s37, 0x14000
	s_nop 0
	global_load_lds_dwordx4 v148, vcc
	s_add_i32 m0, s37, 0x16000
	s_nop 0
	global_load_lds_dwordx4 v144, vcc
	s_add_u32 vcc_lo, vcc_lo, 0x20000
	s_addc_u32 vcc_hi, vcc_hi, 0
	s_add_i32 m0, s37, 0x15000
	s_nop 0
	global_load_lds_dwordx4 v148, vcc
	s_add_i32 m0, s37, 0x17000
	s_nop 0
	global_load_lds_dwordx4 v144, vcc
	ds_read_b128 v[32:35], v169 offset:32768
	ds_read_b128 v[36:39], v169 offset:33792
	ds_read_b128 v[40:43], v169 offset:34816
	ds_read_b128 v[44:47], v169 offset:35840
	ds_read_b128 v[162:165], v170 offset:32768
	ds_read_b128 v[174:177], v170 offset:33792
	ds_read_b128 v[178:181], v170 offset:34816
	ds_read_b128 v[182:185], v170 offset:35840
	ds_read_b128 v[186:189], v171 offset:32768
	ds_read_b128 v[190:193], v171 offset:33792
	ds_read_b128 v[194:197], v171 offset:34816
	ds_read_b128 v[198:201], v171 offset:35840
	ds_read_b128 v[202:205], v171 offset:36864
	ds_read_b128 v[206:209], v171 offset:37888
	ds_read_b128 v[210:213], v171 offset:38912
	ds_read_b128 v[214:217], v171 offset:39936
	ds_read_b128 v[220:223], v171 offset:49152
	ds_read_b128 v[224:227], v171 offset:50176
	ds_read_b128 v[228:231], v171 offset:51200
	ds_read_b128 v[232:235], v171 offset:52224
	ds_read_b128 v[236:239], v171 offset:53248
	ds_read_b128 v[240:243], v171 offset:54272
	ds_read_b128 v[244:247], v171 offset:55296
	ds_read_b128 v[248:251], v171 offset:56320
	s_waitcnt lgkmcnt(0)
	s_barrier
	s_setprio 1
	v_mfma_f32_16x16x32_bf16 v[140:143], v[32:35], v[186:189], v[140:143]
	v_mfma_f32_16x16x32_bf16 v[136:139], v[40:43], v[186:189], v[136:139]
	v_mfma_f32_16x16x32_bf16 v[124:127], v[32:35], v[194:197], v[124:127]
	v_mfma_f32_16x16x32_bf16 v[120:123], v[40:43], v[194:197], v[120:123]
	v_mfma_f32_16x16x32_bf16 v[108:111], v[32:35], v[202:205], v[108:111]
	v_mfma_f32_16x16x32_bf16 v[104:107], v[40:43], v[202:205], v[104:107]
	v_mfma_f32_16x16x32_bf16 v[92:95], v[32:35], v[210:213], v[92:95]
	v_mfma_f32_16x16x32_bf16 v[88:91], v[40:43], v[210:213], v[88:91]
	v_mfma_f32_16x16x32_bf16 v[140:143], v[36:39], v[190:193], v[140:143]
	v_mfma_f32_16x16x32_bf16 v[136:139], v[44:47], v[190:193], v[136:139]
	v_mfma_f32_16x16x32_bf16 v[124:127], v[36:39], v[198:201], v[124:127]
	v_mfma_f32_16x16x32_bf16 v[120:123], v[44:47], v[198:201], v[120:123]
	v_mfma_f32_16x16x32_bf16 v[108:111], v[36:39], v[206:209], v[108:111]
	v_mfma_f32_16x16x32_bf16 v[104:107], v[44:47], v[206:209], v[104:107]
	v_mfma_f32_16x16x32_bf16 v[92:95], v[36:39], v[214:217], v[92:95]
	v_mfma_f32_16x16x32_bf16 v[88:91], v[44:47], v[214:217], v[88:91]
	s_setprio 0
	s_setprio 1
	v_mfma_f32_16x16x32_bf16 v[132:135], v[162:165], v[186:189], v[132:135]
	v_mfma_f32_16x16x32_bf16 v[128:131], v[178:181], v[186:189], v[128:131]
	v_mfma_f32_16x16x32_bf16 v[116:119], v[162:165], v[194:197], v[116:119]
	v_mfma_f32_16x16x32_bf16 v[112:115], v[178:181], v[194:197], v[112:115]
	v_mfma_f32_16x16x32_bf16 v[100:103], v[162:165], v[202:205], v[100:103]
	v_mfma_f32_16x16x32_bf16 v[96:99], v[178:181], v[202:205], v[96:99]
	v_mfma_f32_16x16x32_bf16 v[84:87], v[162:165], v[210:213], v[84:87]
	v_mfma_f32_16x16x32_bf16 v[80:83], v[178:181], v[210:213], v[80:83]
	v_mfma_f32_16x16x32_bf16 v[132:135], v[174:177], v[190:193], v[132:135]
	v_mfma_f32_16x16x32_bf16 v[128:131], v[182:185], v[190:193], v[128:131]
	v_mfma_f32_16x16x32_bf16 v[116:119], v[174:177], v[198:201], v[116:119]
	v_mfma_f32_16x16x32_bf16 v[112:115], v[182:185], v[198:201], v[112:115]
	v_mfma_f32_16x16x32_bf16 v[100:103], v[174:177], v[206:209], v[100:103]
	v_mfma_f32_16x16x32_bf16 v[96:99], v[182:185], v[206:209], v[96:99]
	v_mfma_f32_16x16x32_bf16 v[84:87], v[174:177], v[214:217], v[84:87]
	v_mfma_f32_16x16x32_bf16 v[80:83], v[182:185], v[214:217], v[80:83]
	s_setprio 0
	s_setprio 1
	v_mfma_f32_16x16x32_bf16 v[76:79], v[32:35], v[220:223], v[76:79]
	v_mfma_f32_16x16x32_bf16 v[72:75], v[40:43], v[220:223], v[72:75]
	v_mfma_f32_16x16x32_bf16 v[60:63], v[32:35], v[228:231], v[60:63]
	v_mfma_f32_16x16x32_bf16 v[56:59], v[40:43], v[228:231], v[56:59]
	v_mfma_f32_16x16x32_bf16 v[28:31], v[32:35], v[236:239], v[28:31]
	v_mfma_f32_16x16x32_bf16 v[24:27], v[40:43], v[236:239], v[24:27]
	v_mfma_f32_16x16x32_bf16 v[12:15], v[32:35], v[244:247], v[12:15]
	v_mfma_f32_16x16x32_bf16 v[8:11], v[40:43], v[244:247], v[8:11]
	v_mfma_f32_16x16x32_bf16 v[76:79], v[36:39], v[224:227], v[76:79]
	v_mfma_f32_16x16x32_bf16 v[72:75], v[44:47], v[224:227], v[72:75]
	v_mfma_f32_16x16x32_bf16 v[60:63], v[36:39], v[232:235], v[60:63]
	v_mfma_f32_16x16x32_bf16 v[56:59], v[44:47], v[232:235], v[56:59]
	v_mfma_f32_16x16x32_bf16 v[28:31], v[36:39], v[240:243], v[28:31]
	v_mfma_f32_16x16x32_bf16 v[24:27], v[44:47], v[240:243], v[24:27]
	v_mfma_f32_16x16x32_bf16 v[12:15], v[36:39], v[248:251], v[12:15]
	v_mfma_f32_16x16x32_bf16 v[8:11], v[44:47], v[248:251], v[8:11]
	s_setprio 0
	s_setprio 1
	v_mfma_f32_16x16x32_bf16 v[68:71], v[162:165], v[220:223], v[68:71]
	v_mfma_f32_16x16x32_bf16 v[64:67], v[178:181], v[220:223], v[64:67]
	v_mfma_f32_16x16x32_bf16 v[52:55], v[162:165], v[228:231], v[52:55]
	v_mfma_f32_16x16x32_bf16 v[48:51], v[178:181], v[228:231], v[48:51]
	v_mfma_f32_16x16x32_bf16 v[20:23], v[162:165], v[236:239], v[20:23]
	v_mfma_f32_16x16x32_bf16 v[16:19], v[178:181], v[236:239], v[16:19]
	v_mfma_f32_16x16x32_bf16 v[4:7], v[162:165], v[244:247], v[4:7]
	v_mfma_f32_16x16x32_bf16 v[0:3], v[178:181], v[244:247], v[0:3]
	v_mfma_f32_16x16x32_bf16 v[68:71], v[174:177], v[224:227], v[68:71]
	v_mfma_f32_16x16x32_bf16 v[64:67], v[182:185], v[224:227], v[64:67]
	v_mfma_f32_16x16x32_bf16 v[52:55], v[174:177], v[232:235], v[52:55]
	v_mfma_f32_16x16x32_bf16 v[48:51], v[182:185], v[232:235], v[48:51]
	v_mfma_f32_16x16x32_bf16 v[20:23], v[174:177], v[240:243], v[20:23]
	v_mfma_f32_16x16x32_bf16 v[16:19], v[182:185], v[240:243], v[16:19]
	v_mfma_f32_16x16x32_bf16 v[4:7], v[174:177], v[248:251], v[4:7]
	v_mfma_f32_16x16x32_bf16 v[0:3], v[182:185], v[248:251], v[0:3]
	s_setprio 0
	s_waitcnt vmcnt(0)
	s_barrier
	s_add_i32 s56, s56, 2
	s_add_u32 s12, s12, 0x100
	s_addc_u32 s13, s13, 0
	s_add_u32 s54, s54, 0x100
	s_addc_u32 s55, s55, 0
	s_cmp_gt_u32 s56, 29
	s_cbranch_scc0 .LBB0_846
	s_branch .Lk64_done_p6

.Lk64_epd_p6_t:
	ds_read_b128 v[32:35], v169 offset:0
	ds_read_b128 v[36:39], v169 offset:1024
	ds_read_b128 v[40:43], v169 offset:2048
	ds_read_b128 v[44:47], v169 offset:3072
	ds_read_b128 v[162:165], v170 offset:0
	ds_read_b128 v[174:177], v170 offset:1024
	ds_read_b128 v[178:181], v170 offset:2048
	ds_read_b128 v[182:185], v170 offset:3072
	ds_read_b128 v[186:189], v171 offset:0
	ds_read_b128 v[190:193], v171 offset:1024
	ds_read_b128 v[194:197], v171 offset:2048
	ds_read_b128 v[198:201], v171 offset:3072
	ds_read_b128 v[202:205], v171 offset:4096
	ds_read_b128 v[206:209], v171 offset:5120
	ds_read_b128 v[210:213], v171 offset:6144
	ds_read_b128 v[214:217], v171 offset:7168
	ds_read_b128 v[220:223], v171 offset:16384
	ds_read_b128 v[224:227], v171 offset:17408
	ds_read_b128 v[228:231], v171 offset:18432
	ds_read_b128 v[232:235], v171 offset:19456
	ds_read_b128 v[236:239], v171 offset:20480
	ds_read_b128 v[240:243], v171 offset:21504
	ds_read_b128 v[244:247], v171 offset:22528
	ds_read_b128 v[248:251], v171 offset:23552
	s_waitcnt lgkmcnt(0)
	s_barrier
	s_setprio 1
	v_mfma_f32_16x16x32_bf16 v[140:143], v[32:35], v[186:189], v[140:143]
	v_mfma_f32_16x16x32_bf16 v[136:139], v[40:43], v[186:189], v[136:139]
	v_mfma_f32_16x16x32_bf16 v[124:127], v[32:35], v[194:197], v[124:127]
	v_mfma_f32_16x16x32_bf16 v[120:123], v[40:43], v[194:197], v[120:123]
	v_mfma_f32_16x16x32_bf16 v[108:111], v[32:35], v[202:205], v[108:111]
	v_mfma_f32_16x16x32_bf16 v[104:107], v[40:43], v[202:205], v[104:107]
	v_mfma_f32_16x16x32_bf16 v[92:95], v[32:35], v[210:213], v[92:95]
	v_mfma_f32_16x16x32_bf16 v[88:91], v[40:43], v[210:213], v[88:91]
	v_mfma_f32_16x16x32_bf16 v[140:143], v[36:39], v[190:193], v[140:143]
	v_mfma_f32_16x16x32_bf16 v[136:139], v[44:47], v[190:193], v[136:139]
	v_mfma_f32_16x16x32_bf16 v[124:127], v[36:39], v[198:201], v[124:127]
	v_mfma_f32_16x16x32_bf16 v[120:123], v[44:47], v[198:201], v[120:123]
	v_mfma_f32_16x16x32_bf16 v[108:111], v[36:39], v[206:209], v[108:111]
	v_mfma_f32_16x16x32_bf16 v[104:107], v[44:47], v[206:209], v[104:107]
	v_mfma_f32_16x16x32_bf16 v[92:95], v[36:39], v[214:217], v[92:95]
	v_mfma_f32_16x16x32_bf16 v[88:91], v[44:47], v[214:217], v[88:91]
	s_setprio 0
	s_setprio 1
	v_mfma_f32_16x16x32_bf16 v[132:135], v[162:165], v[186:189], v[132:135]
	v_mfma_f32_16x16x32_bf16 v[128:131], v[178:181], v[186:189], v[128:131]
	v_mfma_f32_16x16x32_bf16 v[116:119], v[162:165], v[194:197], v[116:119]
	v_mfma_f32_16x16x32_bf16 v[112:115], v[178:181], v[194:197], v[112:115]
	v_mfma_f32_16x16x32_bf16 v[100:103], v[162:165], v[202:205], v[100:103]
	v_mfma_f32_16x16x32_bf16 v[96:99], v[178:181], v[202:205], v[96:99]
	v_mfma_f32_16x16x32_bf16 v[84:87], v[162:165], v[210:213], v[84:87]
	v_mfma_f32_16x16x32_bf16 v[80:83], v[178:181], v[210:213], v[80:83]
	v_mfma_f32_16x16x32_bf16 v[132:135], v[174:177], v[190:193], v[132:135]
	v_mfma_f32_16x16x32_bf16 v[128:131], v[182:185], v[190:193], v[128:131]
	v_mfma_f32_16x16x32_bf16 v[116:119], v[174:177], v[198:201], v[116:119]
	v_mfma_f32_16x16x32_bf16 v[112:115], v[182:185], v[198:201], v[112:115]
	v_mfma_f32_16x16x32_bf16 v[100:103], v[174:177], v[206:209], v[100:103]
	v_mfma_f32_16x16x32_bf16 v[96:99], v[182:185], v[206:209], v[96:99]
	v_mfma_f32_16x16x32_bf16 v[84:87], v[174:177], v[214:217], v[84:87]
	v_mfma_f32_16x16x32_bf16 v[80:83], v[182:185], v[214:217], v[80:83]
	s_setprio 0
	s_setprio 1
	v_mfma_f32_16x16x32_bf16 v[76:79], v[32:35], v[220:223], v[76:79]
	v_mfma_f32_16x16x32_bf16 v[72:75], v[40:43], v[220:223], v[72:75]
	v_mfma_f32_16x16x32_bf16 v[60:63], v[32:35], v[228:231], v[60:63]
	v_mfma_f32_16x16x32_bf16 v[56:59], v[40:43], v[228:231], v[56:59]
	v_mfma_f32_16x16x32_bf16 v[28:31], v[32:35], v[236:239], v[28:31]
	v_mfma_f32_16x16x32_bf16 v[24:27], v[40:43], v[236:239], v[24:27]
	v_mfma_f32_16x16x32_bf16 v[12:15], v[32:35], v[244:247], v[12:15]
	v_mfma_f32_16x16x32_bf16 v[8:11], v[40:43], v[244:247], v[8:11]
	v_mfma_f32_16x16x32_bf16 v[76:79], v[36:39], v[224:227], v[76:79]
	v_mfma_f32_16x16x32_bf16 v[72:75], v[44:47], v[224:227], v[72:75]
	v_mfma_f32_16x16x32_bf16 v[60:63], v[36:39], v[232:235], v[60:63]
	v_mfma_f32_16x16x32_bf16 v[56:59], v[44:47], v[232:235], v[56:59]
	v_mfma_f32_16x16x32_bf16 v[28:31], v[36:39], v[240:243], v[28:31]
	v_mfma_f32_16x16x32_bf16 v[24:27], v[44:47], v[240:243], v[24:27]
	v_mfma_f32_16x16x32_bf16 v[12:15], v[36:39], v[248:251], v[12:15]
	v_mfma_f32_16x16x32_bf16 v[8:11], v[44:47], v[248:251], v[8:11]
	s_setprio 0
	s_setprio 1
	v_mfma_f32_16x16x32_bf16 v[68:71], v[162:165], v[220:223], v[68:71]
	v_mfma_f32_16x16x32_bf16 v[64:67], v[178:181], v[220:223], v[64:67]
	v_mfma_f32_16x16x32_bf16 v[52:55], v[162:165], v[228:231], v[52:55]
	v_mfma_f32_16x16x32_bf16 v[48:51], v[178:181], v[228:231], v[48:51]
	v_mfma_f32_16x16x32_bf16 v[20:23], v[162:165], v[236:239], v[20:23]
	v_mfma_f32_16x16x32_bf16 v[16:19], v[178:181], v[236:239], v[16:19]
	v_mfma_f32_16x16x32_bf16 v[4:7], v[162:165], v[244:247], v[4:7]
	v_mfma_f32_16x16x32_bf16 v[0:3], v[178:181], v[244:247], v[0:3]
	v_mfma_f32_16x16x32_bf16 v[68:71], v[174:177], v[224:227], v[68:71]
	v_mfma_f32_16x16x32_bf16 v[64:67], v[182:185], v[224:227], v[64:67]
	v_mfma_f32_16x16x32_bf16 v[52:55], v[174:177], v[232:235], v[52:55]
	v_mfma_f32_16x16x32_bf16 v[48:51], v[182:185], v[232:235], v[48:51]
	v_mfma_f32_16x16x32_bf16 v[20:23], v[174:177], v[240:243], v[20:23]
	v_mfma_f32_16x16x32_bf16 v[16:19], v[182:185], v[240:243], v[16:19]
	v_mfma_f32_16x16x32_bf16 v[4:7], v[174:177], v[248:251], v[4:7]
	v_mfma_f32_16x16x32_bf16 v[0:3], v[182:185], v[248:251], v[0:3]
	s_setprio 0
	s_waitcnt vmcnt(0)
	s_barrier
	s_add_u32 vcc_lo, s34, 0x0
	s_addc_u32 vcc_hi, s35, 0
	s_add_i32 m0, s37, 0x2000
	s_nop 0
	global_load_lds_dwordx4 v146, vcc
	s_add_u32 vcc_lo, vcc_lo, 0x20000
	s_addc_u32 vcc_hi, vcc_hi, 0
	s_add_i32 m0, s37, 0x1000
	s_nop 0
	global_load_lds_dwordx4 v150, vcc
	s_add_u32 vcc_lo, vcc_lo, 0x60000
	s_addc_u32 vcc_hi, vcc_hi, 0
	s_add_i32 m0, s37, 0x6000
	s_nop 0
	global_load_lds_dwordx4 v146, vcc
	s_add_u32 vcc_lo, vcc_lo, 0x20000
	s_addc_u32 vcc_hi, vcc_hi, 0
	s_add_i32 m0, s37, 0x5000
	s_nop 0
	global_load_lds_dwordx4 v150, vcc
	s_add_u32 vcc_lo, s34, 0x80
	s_addc_u32 vcc_hi, s35, 0
	s_add_i32 m0, s37, 0x8000
	s_nop 0
	global_load_lds_dwordx4 v150, vcc
	s_sub_u32 vcc_lo, vcc_lo, 0x20000
	s_subb_u32 vcc_hi, vcc_hi, 0
	s_add_i32 m0, s37, 0x7000
	s_nop 0
	global_load_lds_dwordx4 v150, vcc
	s_add_u32 vcc_lo, vcc_lo, 0xa0000
	s_addc_u32 vcc_hi, vcc_hi, 0
	s_add_i32 m0, s37, 0xc000
	s_nop 0
	global_load_lds_dwordx4 v150, vcc
	s_sub_u32 vcc_lo, vcc_lo, 0x20000
	s_subb_u32 vcc_hi, vcc_hi, 0
	s_add_i32 m0, s37, 0xb000
	s_nop 0
	global_load_lds_dwordx4 v150, vcc
	ds_read_b128 v[32:35], v169 offset:32768
	ds_read_b128 v[36:39], v169 offset:33792
	ds_read_b128 v[40:43], v169 offset:34816
	ds_read_b128 v[44:47], v169 offset:35840
	ds_read_b128 v[162:165], v170 offset:32768
	ds_read_b128 v[174:177], v170 offset:33792
	ds_read_b128 v[178:181], v170 offset:34816
	ds_read_b128 v[182:185], v170 offset:35840
	ds_read_b128 v[186:189], v171 offset:32768
	ds_read_b128 v[190:193], v171 offset:33792
	ds_read_b128 v[194:197], v171 offset:34816
	ds_read_b128 v[198:201], v171 offset:35840
	ds_read_b128 v[202:205], v171 offset:36864
	ds_read_b128 v[206:209], v171 offset:37888
	ds_read_b128 v[210:213], v171 offset:38912
	ds_read_b128 v[214:217], v171 offset:39936
	ds_read_b128 v[220:223], v171 offset:49152
	ds_read_b128 v[224:227], v171 offset:50176
	ds_read_b128 v[228:231], v171 offset:51200
	ds_read_b128 v[232:235], v171 offset:52224
	ds_read_b128 v[236:239], v171 offset:53248
	ds_read_b128 v[240:243], v171 offset:54272
	ds_read_b128 v[244:247], v171 offset:55296
	ds_read_b128 v[248:251], v171 offset:56320
	s_waitcnt lgkmcnt(0)
	s_barrier
	s_setprio 1
	v_mfma_f32_16x16x32_bf16 v[140:143], v[32:35], v[186:189], v[140:143]
	v_mfma_f32_16x16x32_bf16 v[136:139], v[40:43], v[186:189], v[136:139]
	v_mfma_f32_16x16x32_bf16 v[124:127], v[32:35], v[194:197], v[124:127]
	v_mfma_f32_16x16x32_bf16 v[120:123], v[40:43], v[194:197], v[120:123]
	v_mfma_f32_16x16x32_bf16 v[108:111], v[32:35], v[202:205], v[108:111]
	v_mfma_f32_16x16x32_bf16 v[104:107], v[40:43], v[202:205], v[104:107]
	v_mfma_f32_16x16x32_bf16 v[92:95], v[32:35], v[210:213], v[92:95]
	v_mfma_f32_16x16x32_bf16 v[88:91], v[40:43], v[210:213], v[88:91]
	v_mfma_f32_16x16x32_bf16 v[140:143], v[36:39], v[190:193], v[140:143]
	v_mfma_f32_16x16x32_bf16 v[136:139], v[44:47], v[190:193], v[136:139]
	v_mfma_f32_16x16x32_bf16 v[124:127], v[36:39], v[198:201], v[124:127]
	v_mfma_f32_16x16x32_bf16 v[120:123], v[44:47], v[198:201], v[120:123]
	v_mfma_f32_16x16x32_bf16 v[108:111], v[36:39], v[206:209], v[108:111]
	v_mfma_f32_16x16x32_bf16 v[104:107], v[44:47], v[206:209], v[104:107]
	v_mfma_f32_16x16x32_bf16 v[92:95], v[36:39], v[214:217], v[92:95]
	v_mfma_f32_16x16x32_bf16 v[88:91], v[44:47], v[214:217], v[88:91]
	s_setprio 0
	s_setprio 1
	v_mfma_f32_16x16x32_bf16 v[132:135], v[162:165], v[186:189], v[132:135]
	v_mfma_f32_16x16x32_bf16 v[128:131], v[178:181], v[186:189], v[128:131]
	v_mfma_f32_16x16x32_bf16 v[116:119], v[162:165], v[194:197], v[116:119]
	v_mfma_f32_16x16x32_bf16 v[112:115], v[178:181], v[194:197], v[112:115]
	v_mfma_f32_16x16x32_bf16 v[100:103], v[162:165], v[202:205], v[100:103]
	v_mfma_f32_16x16x32_bf16 v[96:99], v[178:181], v[202:205], v[96:99]
	v_mfma_f32_16x16x32_bf16 v[84:87], v[162:165], v[210:213], v[84:87]
	v_mfma_f32_16x16x32_bf16 v[80:83], v[178:181], v[210:213], v[80:83]
	v_mfma_f32_16x16x32_bf16 v[132:135], v[174:177], v[190:193], v[132:135]
	v_mfma_f32_16x16x32_bf16 v[128:131], v[182:185], v[190:193], v[128:131]
	v_mfma_f32_16x16x32_bf16 v[116:119], v[174:177], v[198:201], v[116:119]
	v_mfma_f32_16x16x32_bf16 v[112:115], v[182:185], v[198:201], v[112:115]
	v_mfma_f32_16x16x32_bf16 v[100:103], v[174:177], v[206:209], v[100:103]
	v_mfma_f32_16x16x32_bf16 v[96:99], v[182:185], v[206:209], v[96:99]
	v_mfma_f32_16x16x32_bf16 v[84:87], v[174:177], v[214:217], v[84:87]
	v_mfma_f32_16x16x32_bf16 v[80:83], v[182:185], v[214:217], v[80:83]
	s_setprio 0
	s_setprio 1
	v_mfma_f32_16x16x32_bf16 v[76:79], v[32:35], v[220:223], v[76:79]
	v_mfma_f32_16x16x32_bf16 v[72:75], v[40:43], v[220:223], v[72:75]
	v_mfma_f32_16x16x32_bf16 v[60:63], v[32:35], v[228:231], v[60:63]
	v_mfma_f32_16x16x32_bf16 v[56:59], v[40:43], v[228:231], v[56:59]
	v_mfma_f32_16x16x32_bf16 v[28:31], v[32:35], v[236:239], v[28:31]
	v_mfma_f32_16x16x32_bf16 v[24:27], v[40:43], v[236:239], v[24:27]
	v_mfma_f32_16x16x32_bf16 v[12:15], v[32:35], v[244:247], v[12:15]
	v_mfma_f32_16x16x32_bf16 v[8:11], v[40:43], v[244:247], v[8:11]
	v_mfma_f32_16x16x32_bf16 v[76:79], v[36:39], v[224:227], v[76:79]
	v_mfma_f32_16x16x32_bf16 v[72:75], v[44:47], v[224:227], v[72:75]
	v_mfma_f32_16x16x32_bf16 v[60:63], v[36:39], v[232:235], v[60:63]
	v_mfma_f32_16x16x32_bf16 v[56:59], v[44:47], v[232:235], v[56:59]
	v_mfma_f32_16x16x32_bf16 v[28:31], v[36:39], v[240:243], v[28:31]
	v_mfma_f32_16x16x32_bf16 v[24:27], v[44:47], v[240:243], v[24:27]
	v_mfma_f32_16x16x32_bf16 v[12:15], v[36:39], v[248:251], v[12:15]
	v_mfma_f32_16x16x32_bf16 v[8:11], v[44:47], v[248:251], v[8:11]
	s_setprio 0
	s_setprio 1
	v_mfma_f32_16x16x32_bf16 v[68:71], v[162:165], v[220:223], v[68:71]
	v_mfma_f32_16x16x32_bf16 v[64:67], v[178:181], v[220:223], v[64:67]
	v_mfma_f32_16x16x32_bf16 v[52:55], v[162:165], v[228:231], v[52:55]
	v_mfma_f32_16x16x32_bf16 v[48:51], v[178:181], v[228:231], v[48:51]
	v_mfma_f32_16x16x32_bf16 v[20:23], v[162:165], v[236:239], v[20:23]
	v_mfma_f32_16x16x32_bf16 v[16:19], v[178:181], v[236:239], v[16:19]
	v_mfma_f32_16x16x32_bf16 v[4:7], v[162:165], v[244:247], v[4:7]
	v_mfma_f32_16x16x32_bf16 v[0:3], v[178:181], v[244:247], v[0:3]
	v_mfma_f32_16x16x32_bf16 v[68:71], v[174:177], v[224:227], v[68:71]
	v_mfma_f32_16x16x32_bf16 v[64:67], v[182:185], v[224:227], v[64:67]
	v_mfma_f32_16x16x32_bf16 v[52:55], v[174:177], v[232:235], v[52:55]
	v_mfma_f32_16x16x32_bf16 v[48:51], v[182:185], v[232:235], v[48:51]
	v_mfma_f32_16x16x32_bf16 v[20:23], v[174:177], v[240:243], v[20:23]
	v_mfma_f32_16x16x32_bf16 v[16:19], v[182:185], v[240:243], v[16:19]
	v_mfma_f32_16x16x32_bf16 v[4:7], v[174:177], v[248:251], v[4:7]
	v_mfma_f32_16x16x32_bf16 v[0:3], v[182:185], v[248:251], v[0:3]
	s_setprio 0
	s_waitcnt vmcnt(0)
	s_barrier
	s_add_i32 s56, s56, 2
	s_add_u32 s12, s12, 0x100
	s_addc_u32 s13, s13, 0
	s_add_u32 s54, s54, 0x100
	s_addc_u32 s55, s55, 0
	s_cmp_gt_u32 s56, 29
	s_cbranch_scc0 .LBB0_846

.LBB0_940:
	s_add_u32 s24, s22, 0x100
	s_addc_u32 s25, s23, 0
	s_cmpk_eq_i32 s56, 0x54
	s_cselect_b32 s29, s19, s25
	s_cselect_b32 s28, s18, s24
	s_cselect_b32 s27, s21, s47
	s_cselect_b32 s26, s20, s46
	s_and_b64 vcc, exec, s[12:13]
	s_cbranch_vccz .Lk64_trail_p7
	s_sub_u32 vcc_lo, s46, 0x80
	s_subb_u32 vcc_hi, s47, 0
	s_add_i32 m0, s30, 0x18000
	s_nop 0
	global_load_lds_dwordx4 v130, vcc
	s_add_i32 m0, s30, 0x1a000
	s_nop 0
	global_load_lds_dwordx4 v134, vcc
	s_add_u32 vcc_lo, vcc_lo, 0x58000
	s_addc_u32 vcc_hi, vcc_hi, 0
	s_add_i32 m0, s30, 0x19000
	s_nop 0
	global_load_lds_dwordx4 v130, vcc
	s_add_i32 m0, s30, 0x1b000
	s_nop 0
	global_load_lds_dwordx4 v134, vcc
	s_add_u32 vcc_lo, vcc_lo, 0x108000
	s_addc_u32 vcc_hi, vcc_hi, 0
	s_add_i32 m0, s30, 0x1c000
	s_nop 0
	global_load_lds_dwordx4 v130, vcc
	s_add_i32 m0, s30, 0x1e000
	s_nop 0
	global_load_lds_dwordx4 v134, vcc
	s_add_u32 vcc_lo, vcc_lo, 0x58000
	s_addc_u32 vcc_hi, vcc_hi, 0
	s_add_i32 m0, s30, 0x1d000
	s_nop 0
	global_load_lds_dwordx4 v130, vcc
	s_add_i32 m0, s30, 0x1f000
	s_nop 0
	global_load_lds_dwordx4 v134, vcc
	ds_read_b128 v[144:147], v185 offset:0
	ds_read_b128 v[148:151], v185 offset:1024
	ds_read_b128 v[152:155], v185 offset:2048
	ds_read_b128 v[156:159], v185 offset:3072
	ds_read_b128 v[160:163], v186 offset:0
	ds_read_b128 v[164:167], v186 offset:1024
	ds_read_b128 v[168:171], v186 offset:2048
	ds_read_b128 v[172:175], v186 offset:3072
	ds_read_b128 v[176:179], v187 offset:0
	ds_read_b128 v[190:193], v187 offset:1024
	ds_read_b128 v[194:197], v187 offset:2048
	ds_read_b128 v[198:201], v187 offset:3072
	ds_read_b128 v[202:205], v187 offset:4096
	ds_read_b128 v[206:209], v187 offset:5120
	ds_read_b128 v[210:213], v187 offset:6144
	ds_read_b128 v[214:217], v187 offset:7168
	ds_read_b128 v[220:223], v187 offset:16384
	ds_read_b128 v[224:227], v187 offset:17408
	ds_read_b128 v[228:231], v187 offset:18432
	ds_read_b128 v[232:235], v187 offset:19456
	ds_read_b128 v[236:239], v187 offset:20480
	ds_read_b128 v[240:243], v187 offset:21504
	ds_read_b128 v[244:247], v187 offset:22528
	ds_read_b128 v[248:251], v187 offset:23552
	s_waitcnt lgkmcnt(0)
	s_barrier
	s_setprio 1
	v_mfma_f32_16x16x32_bf16 v[72:75], v[144:147], v[176:179], v[72:75]
	v_mfma_f32_16x16x32_bf16 v[76:79], v[152:155], v[176:179], v[76:79]
	v_mfma_f32_16x16x32_bf16 v[96:99], v[144:147], v[194:197], v[96:99]
	v_mfma_f32_16x16x32_bf16 v[100:103], v[152:155], v[194:197], v[100:103]
	v_mfma_f32_16x16x32_bf16 v[120:123], v[144:147], v[202:205], v[120:123]
	v_mfma_f32_16x16x32_bf16 v[124:127], v[152:155], v[202:205], v[124:127]
	v_mfma_f32_16x16x32_bf16 v[92:95], v[144:147], v[210:213], v[92:95]
	v_mfma_f32_16x16x32_bf16 v[84:87], v[152:155], v[210:213], v[84:87]
	v_mfma_f32_16x16x32_bf16 v[72:75], v[148:151], v[190:193], v[72:75]
	v_mfma_f32_16x16x32_bf16 v[76:79], v[156:159], v[190:193], v[76:79]
	v_mfma_f32_16x16x32_bf16 v[96:99], v[148:151], v[198:201], v[96:99]
	v_mfma_f32_16x16x32_bf16 v[100:103], v[156:159], v[198:201], v[100:103]
	v_mfma_f32_16x16x32_bf16 v[120:123], v[148:151], v[206:209], v[120:123]
	v_mfma_f32_16x16x32_bf16 v[124:127], v[156:159], v[206:209], v[124:127]
	v_mfma_f32_16x16x32_bf16 v[92:95], v[148:151], v[214:217], v[92:95]
	v_mfma_f32_16x16x32_bf16 v[84:87], v[156:159], v[214:217], v[84:87]
	s_setprio 0
	s_setprio 1
	v_mfma_f32_16x16x32_bf16 v[80:83], v[160:163], v[176:179], v[80:83]
	v_mfma_f32_16x16x32_bf16 v[88:91], v[168:171], v[176:179], v[88:91]
	v_mfma_f32_16x16x32_bf16 v[108:111], v[160:163], v[194:197], v[108:111]
	v_mfma_f32_16x16x32_bf16 v[112:115], v[168:171], v[194:197], v[112:115]
	v_mfma_f32_16x16x32_bf16 v[116:119], v[160:163], v[202:205], v[116:119]
	v_mfma_f32_16x16x32_bf16 v[104:107], v[168:171], v[202:205], v[104:107]
	v_mfma_f32_16x16x32_bf16 v[68:71], v[160:163], v[210:213], v[68:71]
	v_mfma_f32_16x16x32_bf16 v[64:67], v[168:171], v[210:213], v[64:67]
	v_mfma_f32_16x16x32_bf16 v[80:83], v[164:167], v[190:193], v[80:83]
	v_mfma_f32_16x16x32_bf16 v[88:91], v[172:175], v[190:193], v[88:91]
	v_mfma_f32_16x16x32_bf16 v[108:111], v[164:167], v[198:201], v[108:111]
	v_mfma_f32_16x16x32_bf16 v[112:115], v[172:175], v[198:201], v[112:115]
	v_mfma_f32_16x16x32_bf16 v[116:119], v[164:167], v[206:209], v[116:119]
	v_mfma_f32_16x16x32_bf16 v[104:107], v[172:175], v[206:209], v[104:107]
	v_mfma_f32_16x16x32_bf16 v[68:71], v[164:167], v[214:217], v[68:71]
	v_mfma_f32_16x16x32_bf16 v[64:67], v[172:175], v[214:217], v[64:67]
	s_setprio 0
	s_setprio 1
	v_mfma_f32_16x16x32_bf16 v[60:63], v[144:147], v[220:223], v[60:63]
	v_mfma_f32_16x16x32_bf16 v[56:59], v[152:155], v[220:223], v[56:59]
	v_mfma_f32_16x16x32_bf16 v[44:47], v[144:147], v[228:231], v[44:47]
	v_mfma_f32_16x16x32_bf16 v[40:43], v[152:155], v[228:231], v[40:43]
	v_mfma_f32_16x16x32_bf16 v[28:31], v[144:147], v[236:239], v[28:31]
	v_mfma_f32_16x16x32_bf16 v[24:27], v[152:155], v[236:239], v[24:27]
	v_mfma_f32_16x16x32_bf16 v[12:15], v[144:147], v[244:247], v[12:15]
	v_mfma_f32_16x16x32_bf16 v[8:11], v[152:155], v[244:247], v[8:11]
	v_mfma_f32_16x16x32_bf16 v[60:63], v[148:151], v[224:227], v[60:63]
	v_mfma_f32_16x16x32_bf16 v[56:59], v[156:159], v[224:227], v[56:59]
	v_mfma_f32_16x16x32_bf16 v[44:47], v[148:151], v[232:235], v[44:47]
	v_mfma_f32_16x16x32_bf16 v[40:43], v[156:159], v[232:235], v[40:43]
	v_mfma_f32_16x16x32_bf16 v[28:31], v[148:151], v[240:243], v[28:31]
	v_mfma_f32_16x16x32_bf16 v[24:27], v[156:159], v[240:243], v[24:27]
	v_mfma_f32_16x16x32_bf16 v[12:15], v[148:151], v[248:251], v[12:15]
	v_mfma_f32_16x16x32_bf16 v[8:11], v[156:159], v[248:251], v[8:11]
	s_setprio 0
	s_setprio 1
	v_mfma_f32_16x16x32_bf16 v[52:55], v[160:163], v[220:223], v[52:55]
	v_mfma_f32_16x16x32_bf16 v[48:51], v[168:171], v[220:223], v[48:51]
	v_mfma_f32_16x16x32_bf16 v[36:39], v[160:163], v[228:231], v[36:39]
	v_mfma_f32_16x16x32_bf16 v[32:35], v[168:171], v[228:231], v[32:35]
	v_mfma_f32_16x16x32_bf16 v[20:23], v[160:163], v[236:239], v[20:23]
	v_mfma_f32_16x16x32_bf16 v[16:19], v[168:171], v[236:239], v[16:19]
	v_mfma_f32_16x16x32_bf16 v[4:7], v[160:163], v[244:247], v[4:7]
	v_mfma_f32_16x16x32_bf16 v[0:3], v[168:171], v[244:247], v[0:3]
	v_mfma_f32_16x16x32_bf16 v[52:55], v[164:167], v[224:227], v[52:55]
	v_mfma_f32_16x16x32_bf16 v[48:51], v[172:175], v[224:227], v[48:51]
	v_mfma_f32_16x16x32_bf16 v[36:39], v[164:167], v[232:235], v[36:39]
	v_mfma_f32_16x16x32_bf16 v[32:35], v[172:175], v[232:235], v[32:35]
	v_mfma_f32_16x16x32_bf16 v[20:23], v[164:167], v[240:243], v[20:23]
	v_mfma_f32_16x16x32_bf16 v[16:19], v[172:175], v[240:243], v[16:19]
	v_mfma_f32_16x16x32_bf16 v[4:7], v[164:167], v[248:251], v[4:7]
	v_mfma_f32_16x16x32_bf16 v[0:3], v[172:175], v[248:251], v[0:3]
	s_setprio 0
	s_waitcnt vmcnt(0)
	s_barrier
	s_add_u32 vcc_lo, s26, 0x0
	s_addc_u32 vcc_hi, s27, 0
	s_add_i32 m0, s30, 0x10000
	s_nop 0
	global_load_lds_dwordx4 v130, vcc
	s_add_i32 m0, s30, 0x12000
	s_nop 0
	global_load_lds_dwordx4 v134, vcc
	s_add_u32 vcc_lo, vcc_lo, 0x58000
	s_addc_u32 vcc_hi, vcc_hi, 0
	s_add_i32 m0, s30, 0x11000
	s_nop 0
	global_load_lds_dwordx4 v130, vcc
	s_add_i32 m0, s30, 0x13000
	s_nop 0
	global_load_lds_dwordx4 v134, vcc
	s_add_u32 vcc_lo, vcc_lo, 0x108000
	s_addc_u32 vcc_hi, vcc_hi, 0
	s_add_i32 m0, s30, 0x14000
	s_nop 0
	global_load_lds_dwordx4 v130, vcc
	s_add_i32 m0, s30, 0x16000
	s_nop 0
	global_load_lds_dwordx4 v134, vcc
	s_add_u32 vcc_lo, vcc_lo, 0x58000
	s_addc_u32 vcc_hi, vcc_hi, 0
	s_add_i32 m0, s30, 0x15000
	s_nop 0
	global_load_lds_dwordx4 v130, vcc
	s_add_i32 m0, s30, 0x17000
	s_nop 0
	global_load_lds_dwordx4 v134, vcc
	ds_read_b128 v[144:147], v185 offset:32768
	ds_read_b128 v[148:151], v185 offset:33792
	ds_read_b128 v[152:155], v185 offset:34816
	ds_read_b128 v[156:159], v185 offset:35840
	ds_read_b128 v[160:163], v186 offset:32768
	ds_read_b128 v[164:167], v186 offset:33792
	ds_read_b128 v[168:171], v186 offset:34816
	ds_read_b128 v[172:175], v186 offset:35840
	ds_read_b128 v[176:179], v187 offset:32768
	ds_read_b128 v[190:193], v187 offset:33792
	ds_read_b128 v[194:197], v187 offset:34816
	ds_read_b128 v[198:201], v187 offset:35840
	ds_read_b128 v[202:205], v187 offset:36864
	ds_read_b128 v[206:209], v187 offset:37888
	ds_read_b128 v[210:213], v187 offset:38912
	ds_read_b128 v[214:217], v187 offset:39936
	ds_read_b128 v[220:223], v187 offset:49152
	ds_read_b128 v[224:227], v187 offset:50176
	ds_read_b128 v[228:231], v187 offset:51200
	ds_read_b128 v[232:235], v187 offset:52224
	ds_read_b128 v[236:239], v187 offset:53248
	ds_read_b128 v[240:243], v187 offset:54272
	ds_read_b128 v[244:247], v187 offset:55296
	ds_read_b128 v[248:251], v187 offset:56320
	s_waitcnt lgkmcnt(0)
	s_barrier
	s_setprio 1
	v_mfma_f32_16x16x32_bf16 v[72:75], v[144:147], v[176:179], v[72:75]
	v_mfma_f32_16x16x32_bf16 v[76:79], v[152:155], v[176:179], v[76:79]
	v_mfma_f32_16x16x32_bf16 v[96:99], v[144:147], v[194:197], v[96:99]
	v_mfma_f32_16x16x32_bf16 v[100:103], v[152:155], v[194:197], v[100:103]
	v_mfma_f32_16x16x32_bf16 v[120:123], v[144:147], v[202:205], v[120:123]
	v_mfma_f32_16x16x32_bf16 v[124:127], v[152:155], v[202:205], v[124:127]
	v_mfma_f32_16x16x32_bf16 v[92:95], v[144:147], v[210:213], v[92:95]
	v_mfma_f32_16x16x32_bf16 v[84:87], v[152:155], v[210:213], v[84:87]
	v_mfma_f32_16x16x32_bf16 v[72:75], v[148:151], v[190:193], v[72:75]
	v_mfma_f32_16x16x32_bf16 v[76:79], v[156:159], v[190:193], v[76:79]
	v_mfma_f32_16x16x32_bf16 v[96:99], v[148:151], v[198:201], v[96:99]
	v_mfma_f32_16x16x32_bf16 v[100:103], v[156:159], v[198:201], v[100:103]
	v_mfma_f32_16x16x32_bf16 v[120:123], v[148:151], v[206:209], v[120:123]
	v_mfma_f32_16x16x32_bf16 v[124:127], v[156:159], v[206:209], v[124:127]
	v_mfma_f32_16x16x32_bf16 v[92:95], v[148:151], v[214:217], v[92:95]
	v_mfma_f32_16x16x32_bf16 v[84:87], v[156:159], v[214:217], v[84:87]
	s_setprio 0
	s_setprio 1
	v_mfma_f32_16x16x32_bf16 v[80:83], v[160:163], v[176:179], v[80:83]
	v_mfma_f32_16x16x32_bf16 v[88:91], v[168:171], v[176:179], v[88:91]
	v_mfma_f32_16x16x32_bf16 v[108:111], v[160:163], v[194:197], v[108:111]
	v_mfma_f32_16x16x32_bf16 v[112:115], v[168:171], v[194:197], v[112:115]
	v_mfma_f32_16x16x32_bf16 v[116:119], v[160:163], v[202:205], v[116:119]
	v_mfma_f32_16x16x32_bf16 v[104:107], v[168:171], v[202:205], v[104:107]
	v_mfma_f32_16x16x32_bf16 v[68:71], v[160:163], v[210:213], v[68:71]
	v_mfma_f32_16x16x32_bf16 v[64:67], v[168:171], v[210:213], v[64:67]
	v_mfma_f32_16x16x32_bf16 v[80:83], v[164:167], v[190:193], v[80:83]
	v_mfma_f32_16x16x32_bf16 v[88:91], v[172:175], v[190:193], v[88:91]
	v_mfma_f32_16x16x32_bf16 v[108:111], v[164:167], v[198:201], v[108:111]
	v_mfma_f32_16x16x32_bf16 v[112:115], v[172:175], v[198:201], v[112:115]
	v_mfma_f32_16x16x32_bf16 v[116:119], v[164:167], v[206:209], v[116:119]
	v_mfma_f32_16x16x32_bf16 v[104:107], v[172:175], v[206:209], v[104:107]
	v_mfma_f32_16x16x32_bf16 v[68:71], v[164:167], v[214:217], v[68:71]
	v_mfma_f32_16x16x32_bf16 v[64:67], v[172:175], v[214:217], v[64:67]
	s_setprio 0
	s_setprio 1
	v_mfma_f32_16x16x32_bf16 v[60:63], v[144:147], v[220:223], v[60:63]
	v_mfma_f32_16x16x32_bf16 v[56:59], v[152:155], v[220:223], v[56:59]
	v_mfma_f32_16x16x32_bf16 v[44:47], v[144:147], v[228:231], v[44:47]
	v_mfma_f32_16x16x32_bf16 v[40:43], v[152:155], v[228:231], v[40:43]
	v_mfma_f32_16x16x32_bf16 v[28:31], v[144:147], v[236:239], v[28:31]
	v_mfma_f32_16x16x32_bf16 v[24:27], v[152:155], v[236:239], v[24:27]
	v_mfma_f32_16x16x32_bf16 v[12:15], v[144:147], v[244:247], v[12:15]
	v_mfma_f32_16x16x32_bf16 v[8:11], v[152:155], v[244:247], v[8:11]
	v_mfma_f32_16x16x32_bf16 v[60:63], v[148:151], v[224:227], v[60:63]
	v_mfma_f32_16x16x32_bf16 v[56:59], v[156:159], v[224:227], v[56:59]
	v_mfma_f32_16x16x32_bf16 v[44:47], v[148:151], v[232:235], v[44:47]
	v_mfma_f32_16x16x32_bf16 v[40:43], v[156:159], v[232:235], v[40:43]
	v_mfma_f32_16x16x32_bf16 v[28:31], v[148:151], v[240:243], v[28:31]
	v_mfma_f32_16x16x32_bf16 v[24:27], v[156:159], v[240:243], v[24:27]
	v_mfma_f32_16x16x32_bf16 v[12:15], v[148:151], v[248:251], v[12:15]
	v_mfma_f32_16x16x32_bf16 v[8:11], v[156:159], v[248:251], v[8:11]
	s_setprio 0
	s_setprio 1
	v_mfma_f32_16x16x32_bf16 v[52:55], v[160:163], v[220:223], v[52:55]
	v_mfma_f32_16x16x32_bf16 v[48:51], v[168:171], v[220:223], v[48:51]
	v_mfma_f32_16x16x32_bf16 v[36:39], v[160:163], v[228:231], v[36:39]
	v_mfma_f32_16x16x32_bf16 v[32:35], v[168:171], v[228:231], v[32:35]
	v_mfma_f32_16x16x32_bf16 v[20:23], v[160:163], v[236:239], v[20:23]
	v_mfma_f32_16x16x32_bf16 v[16:19], v[168:171], v[236:239], v[16:19]
	v_mfma_f32_16x16x32_bf16 v[4:7], v[160:163], v[244:247], v[4:7]
	v_mfma_f32_16x16x32_bf16 v[0:3], v[168:171], v[244:247], v[0:3]
	v_mfma_f32_16x16x32_bf16 v[52:55], v[164:167], v[224:227], v[52:55]
	v_mfma_f32_16x16x32_bf16 v[48:51], v[172:175], v[224:227], v[48:51]
	v_mfma_f32_16x16x32_bf16 v[36:39], v[164:167], v[232:235], v[36:39]
	v_mfma_f32_16x16x32_bf16 v[32:35], v[172:175], v[232:235], v[32:35]
	v_mfma_f32_16x16x32_bf16 v[20:23], v[164:167], v[240:243], v[20:23]
	v_mfma_f32_16x16x32_bf16 v[16:19], v[172:175], v[240:243], v[16:19]
	v_mfma_f32_16x16x32_bf16 v[4:7], v[164:167], v[248:251], v[4:7]
	v_mfma_f32_16x16x32_bf16 v[0:3], v[172:175], v[248:251], v[0:3]
	s_setprio 0
	s_waitcnt vmcnt(0)
	s_barrier
	s_add_i32 s56, s56, 2
	s_add_u32 s46, s46, 0x100
	s_addc_u32 s47, s47, 0
	s_cmpk_gt_u32 s56, 0x55
	s_mov_b64 s[22:23], s[24:25]
	s_cbranch_scc0 .LBB0_940
	s_branch .Lk64_done_p7
.Lk64_trail_p7:
	s_add_u32 vcc_lo, s22, 0x80
	s_addc_u32 vcc_hi, s23, 0
	s_add_i32 m0, s30, 0xa000
	s_nop 0
	global_load_lds_dwordx4 v132, vcc
	s_add_u32 vcc_lo, vcc_lo, 0x58000
	s_addc_u32 vcc_hi, vcc_hi, 0
	s_add_i32 m0, s30, 0x9000
	s_nop 0
	global_load_lds_dwordx4 v128, vcc
	s_add_u32 vcc_lo, vcc_lo, 0x108000
	s_addc_u32 vcc_hi, vcc_hi, 0
	s_add_i32 m0, s30, 0xe000
	s_nop 0
	global_load_lds_dwordx4 v132, vcc
	s_add_u32 vcc_lo, vcc_lo, 0x58000
	s_addc_u32 vcc_hi, vcc_hi, 0
	s_add_i32 m0, s30, 0xd000
	s_nop 0
	global_load_lds_dwordx4 v128, vcc
	s_add_u32 vcc_lo, s28, 0x0
	s_addc_u32 vcc_hi, s29, 0
	s_mov_b32 m0, s30
	s_nop 0
	global_load_lds_dwordx4 v128, vcc
	s_sub_u32 vcc_lo, vcc_lo, 0x58000
	s_subb_u32 vcc_hi, vcc_hi, 0
	s_sub_i32 m0, s30, 0x1000
	s_nop 0
	global_load_lds_dwordx4 v128, vcc
	s_add_u32 vcc_lo, vcc_lo, 0x1b8000
	s_addc_u32 vcc_hi, vcc_hi, 0
	s_add_i32 m0, s30, 0x4000
	s_nop 0
	global_load_lds_dwordx4 v128, vcc
	s_sub_u32 vcc_lo, vcc_lo, 0x58000
	s_subb_u32 vcc_hi, vcc_hi, 0
	s_add_i32 m0, s30, 0x3000
	s_nop 0
	global_load_lds_dwordx4 v128, vcc
	ds_read_b128 v[144:147], v185 offset:0
	ds_read_b128 v[148:151], v185 offset:1024
	ds_read_b128 v[152:155], v185 offset:2048
	ds_read_b128 v[156:159], v185 offset:3072
	ds_read_b128 v[160:163], v186 offset:0
	ds_read_b128 v[164:167], v186 offset:1024
	ds_read_b128 v[168:171], v186 offset:2048
	ds_read_b128 v[172:175], v186 offset:3072
	ds_read_b128 v[176:179], v187 offset:0
	ds_read_b128 v[190:193], v187 offset:1024
	ds_read_b128 v[194:197], v187 offset:2048
	ds_read_b128 v[198:201], v187 offset:3072
	ds_read_b128 v[202:205], v187 offset:4096
	ds_read_b128 v[206:209], v187 offset:5120
	ds_read_b128 v[210:213], v187 offset:6144
	ds_read_b128 v[214:217], v187 offset:7168
	ds_read_b128 v[220:223], v187 offset:16384
	ds_read_b128 v[224:227], v187 offset:17408
	ds_read_b128 v[228:231], v187 offset:18432
	ds_read_b128 v[232:235], v187 offset:19456
	ds_read_b128 v[236:239], v187 offset:20480
	ds_read_b128 v[240:243], v187 offset:21504
	ds_read_b128 v[244:247], v187 offset:22528
	ds_read_b128 v[248:251], v187 offset:23552
	s_waitcnt lgkmcnt(0)
	s_barrier
	s_setprio 1
	v_mfma_f32_16x16x32_bf16 v[72:75], v[144:147], v[176:179], v[72:75]
	v_mfma_f32_16x16x32_bf16 v[76:79], v[152:155], v[176:179], v[76:79]
	v_mfma_f32_16x16x32_bf16 v[96:99], v[144:147], v[194:197], v[96:99]
	v_mfma_f32_16x16x32_bf16 v[100:103], v[152:155], v[194:197], v[100:103]
	v_mfma_f32_16x16x32_bf16 v[120:123], v[144:147], v[202:205], v[120:123]
	v_mfma_f32_16x16x32_bf16 v[124:127], v[152:155], v[202:205], v[124:127]
	v_mfma_f32_16x16x32_bf16 v[92:95], v[144:147], v[210:213], v[92:95]
	v_mfma_f32_16x16x32_bf16 v[84:87], v[152:155], v[210:213], v[84:87]
	v_mfma_f32_16x16x32_bf16 v[72:75], v[148:151], v[190:193], v[72:75]
	v_mfma_f32_16x16x32_bf16 v[76:79], v[156:159], v[190:193], v[76:79]
	v_mfma_f32_16x16x32_bf16 v[96:99], v[148:151], v[198:201], v[96:99]
	v_mfma_f32_16x16x32_bf16 v[100:103], v[156:159], v[198:201], v[100:103]
	v_mfma_f32_16x16x32_bf16 v[120:123], v[148:151], v[206:209], v[120:123]
	v_mfma_f32_16x16x32_bf16 v[124:127], v[156:159], v[206:209], v[124:127]
	v_mfma_f32_16x16x32_bf16 v[92:95], v[148:151], v[214:217], v[92:95]
	v_mfma_f32_16x16x32_bf16 v[84:87], v[156:159], v[214:217], v[84:87]
	s_setprio 0
	s_setprio 1
	v_mfma_f32_16x16x32_bf16 v[80:83], v[160:163], v[176:179], v[80:83]
	v_mfma_f32_16x16x32_bf16 v[88:91], v[168:171], v[176:179], v[88:91]
	v_mfma_f32_16x16x32_bf16 v[108:111], v[160:163], v[194:197], v[108:111]
	v_mfma_f32_16x16x32_bf16 v[112:115], v[168:171], v[194:197], v[112:115]
	v_mfma_f32_16x16x32_bf16 v[116:119], v[160:163], v[202:205], v[116:119]
	v_mfma_f32_16x16x32_bf16 v[104:107], v[168:171], v[202:205], v[104:107]
	v_mfma_f32_16x16x32_bf16 v[68:71], v[160:163], v[210:213], v[68:71]
	v_mfma_f32_16x16x32_bf16 v[64:67], v[168:171], v[210:213], v[64:67]
	v_mfma_f32_16x16x32_bf16 v[80:83], v[164:167], v[190:193], v[80:83]
	v_mfma_f32_16x16x32_bf16 v[88:91], v[172:175], v[190:193], v[88:91]
	v_mfma_f32_16x16x32_bf16 v[108:111], v[164:167], v[198:201], v[108:111]
	v_mfma_f32_16x16x32_bf16 v[112:115], v[172:175], v[198:201], v[112:115]
	v_mfma_f32_16x16x32_bf16 v[116:119], v[164:167], v[206:209], v[116:119]
	v_mfma_f32_16x16x32_bf16 v[104:107], v[172:175], v[206:209], v[104:107]
	v_mfma_f32_16x16x32_bf16 v[68:71], v[164:167], v[214:217], v[68:71]
	v_mfma_f32_16x16x32_bf16 v[64:67], v[172:175], v[214:217], v[64:67]
	s_setprio 0
	s_setprio 1
	v_mfma_f32_16x16x32_bf16 v[60:63], v[144:147], v[220:223], v[60:63]
	v_mfma_f32_16x16x32_bf16 v[56:59], v[152:155], v[220:223], v[56:59]
	v_mfma_f32_16x16x32_bf16 v[44:47], v[144:147], v[228:231], v[44:47]
	v_mfma_f32_16x16x32_bf16 v[40:43], v[152:155], v[228:231], v[40:43]
	v_mfma_f32_16x16x32_bf16 v[28:31], v[144:147], v[236:239], v[28:31]
	v_mfma_f32_16x16x32_bf16 v[24:27], v[152:155], v[236:239], v[24:27]
	v_mfma_f32_16x16x32_bf16 v[12:15], v[144:147], v[244:247], v[12:15]
	v_mfma_f32_16x16x32_bf16 v[8:11], v[152:155], v[244:247], v[8:11]
	v_mfma_f32_16x16x32_bf16 v[60:63], v[148:151], v[224:227], v[60:63]
	v_mfma_f32_16x16x32_bf16 v[56:59], v[156:159], v[224:227], v[56:59]
	v_mfma_f32_16x16x32_bf16 v[44:47], v[148:151], v[232:235], v[44:47]
	v_mfma_f32_16x16x32_bf16 v[40:43], v[156:159], v[232:235], v[40:43]
	v_mfma_f32_16x16x32_bf16 v[28:31], v[148:151], v[240:243], v[28:31]
	v_mfma_f32_16x16x32_bf16 v[24:27], v[156:159], v[240:243], v[24:27]
	v_mfma_f32_16x16x32_bf16 v[12:15], v[148:151], v[248:251], v[12:15]
	v_mfma_f32_16x16x32_bf16 v[8:11], v[156:159], v[248:251], v[8:11]
	s_setprio 0
	s_setprio 1
	v_mfma_f32_16x16x32_bf16 v[52:55], v[160:163], v[220:223], v[52:55]
	v_mfma_f32_16x16x32_bf16 v[48:51], v[168:171], v[220:223], v[48:51]
	v_mfma_f32_16x16x32_bf16 v[36:39], v[160:163], v[228:231], v[36:39]
	v_mfma_f32_16x16x32_bf16 v[32:35], v[168:171], v[228:231], v[32:35]
	v_mfma_f32_16x16x32_bf16 v[20:23], v[160:163], v[236:239], v[20:23]
	v_mfma_f32_16x16x32_bf16 v[16:19], v[168:171], v[236:239], v[16:19]
	v_mfma_f32_16x16x32_bf16 v[4:7], v[160:163], v[244:247], v[4:7]
	v_mfma_f32_16x16x32_bf16 v[0:3], v[168:171], v[244:247], v[0:3]
	v_mfma_f32_16x16x32_bf16 v[52:55], v[164:167], v[224:227], v[52:55]
	v_mfma_f32_16x16x32_bf16 v[48:51], v[172:175], v[224:227], v[48:51]
	v_mfma_f32_16x16x32_bf16 v[36:39], v[164:167], v[232:235], v[36:39]
	v_mfma_f32_16x16x32_bf16 v[32:35], v[172:175], v[232:235], v[32:35]
	v_mfma_f32_16x16x32_bf16 v[20:23], v[164:167], v[240:243], v[20:23]
	v_mfma_f32_16x16x32_bf16 v[16:19], v[172:175], v[240:243], v[16:19]
	v_mfma_f32_16x16x32_bf16 v[4:7], v[164:167], v[248:251], v[4:7]
	v_mfma_f32_16x16x32_bf16 v[0:3], v[172:175], v[248:251], v[0:3]
	s_setprio 0
	s_waitcnt vmcnt(0)
	s_barrier
	s_add_u32 vcc_lo, s28, 0x0
	s_addc_u32 vcc_hi, s29, 0
	s_add_i32 m0, s30, 0x2000
	s_nop 0
	global_load_lds_dwordx4 v132, vcc
	s_add_u32 vcc_lo, vcc_lo, 0x58000
	s_addc_u32 vcc_hi, vcc_hi, 0
	s_add_i32 m0, s30, 0x1000
	s_nop 0
	global_load_lds_dwordx4 v128, vcc
	s_add_u32 vcc_lo, vcc_lo, 0x108000
	s_addc_u32 vcc_hi, vcc_hi, 0
	s_add_i32 m0, s30, 0x6000
	s_nop 0
	global_load_lds_dwordx4 v132, vcc
	s_add_u32 vcc_lo, vcc_lo, 0x58000
	s_addc_u32 vcc_hi, vcc_hi, 0
	s_add_i32 m0, s30, 0x5000
	s_nop 0
	global_load_lds_dwordx4 v128, vcc
	s_add_u32 vcc_lo, s28, 0x80
	s_addc_u32 vcc_hi, s29, 0
	s_add_i32 m0, s30, 0x8000
	s_nop 0
	global_load_lds_dwordx4 v128, vcc
	s_sub_u32 vcc_lo, vcc_lo, 0x58000
	s_subb_u32 vcc_hi, vcc_hi, 0
	s_add_i32 m0, s30, 0x7000
	s_nop 0
	global_load_lds_dwordx4 v128, vcc
	s_add_u32 vcc_lo, vcc_lo, 0x1b8000
	s_addc_u32 vcc_hi, vcc_hi, 0
	s_add_i32 m0, s30, 0xc000
	s_nop 0
	global_load_lds_dwordx4 v128, vcc
	s_sub_u32 vcc_lo, vcc_lo, 0x58000
	s_subb_u32 vcc_hi, vcc_hi, 0
	s_add_i32 m0, s30, 0xb000
	s_nop 0
	global_load_lds_dwordx4 v128, vcc
	ds_read_b128 v[144:147], v185 offset:32768
	ds_read_b128 v[148:151], v185 offset:33792
	ds_read_b128 v[152:155], v185 offset:34816
	ds_read_b128 v[156:159], v185 offset:35840
	ds_read_b128 v[160:163], v186 offset:32768
	ds_read_b128 v[164:167], v186 offset:33792
	ds_read_b128 v[168:171], v186 offset:34816
	ds_read_b128 v[172:175], v186 offset:35840
	ds_read_b128 v[176:179], v187 offset:32768
	ds_read_b128 v[190:193], v187 offset:33792
	ds_read_b128 v[194:197], v187 offset:34816
	ds_read_b128 v[198:201], v187 offset:35840
	ds_read_b128 v[202:205], v187 offset:36864
	ds_read_b128 v[206:209], v187 offset:37888
	ds_read_b128 v[210:213], v187 offset:38912
	ds_read_b128 v[214:217], v187 offset:39936
	ds_read_b128 v[220:223], v187 offset:49152
	ds_read_b128 v[224:227], v187 offset:50176
	ds_read_b128 v[228:231], v187 offset:51200
	ds_read_b128 v[232:235], v187 offset:52224
	ds_read_b128 v[236:239], v187 offset:53248
	ds_read_b128 v[240:243], v187 offset:54272
	ds_read_b128 v[244:247], v187 offset:55296
	ds_read_b128 v[248:251], v187 offset:56320
	s_waitcnt lgkmcnt(0)
	s_barrier
	s_setprio 1
	v_mfma_f32_16x16x32_bf16 v[72:75], v[144:147], v[176:179], v[72:75]
	v_mfma_f32_16x16x32_bf16 v[76:79], v[152:155], v[176:179], v[76:79]
	v_mfma_f32_16x16x32_bf16 v[96:99], v[144:147], v[194:197], v[96:99]
	v_mfma_f32_16x16x32_bf16 v[100:103], v[152:155], v[194:197], v[100:103]
	v_mfma_f32_16x16x32_bf16 v[120:123], v[144:147], v[202:205], v[120:123]
	v_mfma_f32_16x16x32_bf16 v[124:127], v[152:155], v[202:205], v[124:127]
	v_mfma_f32_16x16x32_bf16 v[92:95], v[144:147], v[210:213], v[92:95]
	v_mfma_f32_16x16x32_bf16 v[84:87], v[152:155], v[210:213], v[84:87]
	v_mfma_f32_16x16x32_bf16 v[72:75], v[148:151], v[190:193], v[72:75]
	v_mfma_f32_16x16x32_bf16 v[76:79], v[156:159], v[190:193], v[76:79]
	v_mfma_f32_16x16x32_bf16 v[96:99], v[148:151], v[198:201], v[96:99]
	v_mfma_f32_16x16x32_bf16 v[100:103], v[156:159], v[198:201], v[100:103]
	v_mfma_f32_16x16x32_bf16 v[120:123], v[148:151], v[206:209], v[120:123]
	v_mfma_f32_16x16x32_bf16 v[124:127], v[156:159], v[206:209], v[124:127]
	v_mfma_f32_16x16x32_bf16 v[92:95], v[148:151], v[214:217], v[92:95]
	v_mfma_f32_16x16x32_bf16 v[84:87], v[156:159], v[214:217], v[84:87]
	s_setprio 0
	s_setprio 1
	v_mfma_f32_16x16x32_bf16 v[80:83], v[160:163], v[176:179], v[80:83]
	v_mfma_f32_16x16x32_bf16 v[88:91], v[168:171], v[176:179], v[88:91]
	v_mfma_f32_16x16x32_bf16 v[108:111], v[160:163], v[194:197], v[108:111]
	v_mfma_f32_16x16x32_bf16 v[112:115], v[168:171], v[194:197], v[112:115]
	v_mfma_f32_16x16x32_bf16 v[116:119], v[160:163], v[202:205], v[116:119]
	v_mfma_f32_16x16x32_bf16 v[104:107], v[168:171], v[202:205], v[104:107]
	v_mfma_f32_16x16x32_bf16 v[68:71], v[160:163], v[210:213], v[68:71]
	v_mfma_f32_16x16x32_bf16 v[64:67], v[168:171], v[210:213], v[64:67]
	v_mfma_f32_16x16x32_bf16 v[80:83], v[164:167], v[190:193], v[80:83]
	v_mfma_f32_16x16x32_bf16 v[88:91], v[172:175], v[190:193], v[88:91]
	v_mfma_f32_16x16x32_bf16 v[108:111], v[164:167], v[198:201], v[108:111]
	v_mfma_f32_16x16x32_bf16 v[112:115], v[172:175], v[198:201], v[112:115]
	v_mfma_f32_16x16x32_bf16 v[116:119], v[164:167], v[206:209], v[116:119]
	v_mfma_f32_16x16x32_bf16 v[104:107], v[172:175], v[206:209], v[104:107]
	v_mfma_f32_16x16x32_bf16 v[68:71], v[164:167], v[214:217], v[68:71]
	v_mfma_f32_16x16x32_bf16 v[64:67], v[172:175], v[214:217], v[64:67]
	s_setprio 0
	s_setprio 1
	v_mfma_f32_16x16x32_bf16 v[60:63], v[144:147], v[220:223], v[60:63]
	v_mfma_f32_16x16x32_bf16 v[56:59], v[152:155], v[220:223], v[56:59]
	v_mfma_f32_16x16x32_bf16 v[44:47], v[144:147], v[228:231], v[44:47]
	v_mfma_f32_16x16x32_bf16 v[40:43], v[152:155], v[228:231], v[40:43]
	v_mfma_f32_16x16x32_bf16 v[28:31], v[144:147], v[236:239], v[28:31]
	v_mfma_f32_16x16x32_bf16 v[24:27], v[152:155], v[236:239], v[24:27]
	v_mfma_f32_16x16x32_bf16 v[12:15], v[144:147], v[244:247], v[12:15]
	v_mfma_f32_16x16x32_bf16 v[8:11], v[152:155], v[244:247], v[8:11]
	v_mfma_f32_16x16x32_bf16 v[60:63], v[148:151], v[224:227], v[60:63]
	v_mfma_f32_16x16x32_bf16 v[56:59], v[156:159], v[224:227], v[56:59]
	v_mfma_f32_16x16x32_bf16 v[44:47], v[148:151], v[232:235], v[44:47]
	v_mfma_f32_16x16x32_bf16 v[40:43], v[156:159], v[232:235], v[40:43]
	v_mfma_f32_16x16x32_bf16 v[28:31], v[148:151], v[240:243], v[28:31]
	v_mfma_f32_16x16x32_bf16 v[24:27], v[156:159], v[240:243], v[24:27]
	v_mfma_f32_16x16x32_bf16 v[12:15], v[148:151], v[248:251], v[12:15]
	v_mfma_f32_16x16x32_bf16 v[8:11], v[156:159], v[248:251], v[8:11]
	s_setprio 0
	s_setprio 1
	v_mfma_f32_16x16x32_bf16 v[52:55], v[160:163], v[220:223], v[52:55]
	v_mfma_f32_16x16x32_bf16 v[48:51], v[168:171], v[220:223], v[48:51]
	v_mfma_f32_16x16x32_bf16 v[36:39], v[160:163], v[228:231], v[36:39]
	v_mfma_f32_16x16x32_bf16 v[32:35], v[168:171], v[228:231], v[32:35]
	v_mfma_f32_16x16x32_bf16 v[20:23], v[160:163], v[236:239], v[20:23]
	v_mfma_f32_16x16x32_bf16 v[16:19], v[168:171], v[236:239], v[16:19]
	v_mfma_f32_16x16x32_bf16 v[4:7], v[160:163], v[244:247], v[4:7]
	v_mfma_f32_16x16x32_bf16 v[0:3], v[168:171], v[244:247], v[0:3]
	v_mfma_f32_16x16x32_bf16 v[52:55], v[164:167], v[224:227], v[52:55]
	v_mfma_f32_16x16x32_bf16 v[48:51], v[172:175], v[224:227], v[48:51]
	v_mfma_f32_16x16x32_bf16 v[36:39], v[164:167], v[232:235], v[36:39]
	v_mfma_f32_16x16x32_bf16 v[32:35], v[172:175], v[232:235], v[32:35]
	v_mfma_f32_16x16x32_bf16 v[20:23], v[164:167], v[240:243], v[20:23]
	v_mfma_f32_16x16x32_bf16 v[16:19], v[172:175], v[240:243], v[16:19]
	v_mfma_f32_16x16x32_bf16 v[4:7], v[164:167], v[248:251], v[4:7]
	v_mfma_f32_16x16x32_bf16 v[0:3], v[172:175], v[248:251], v[0:3]
	s_setprio 0
	s_waitcnt vmcnt(0)
	s_barrier
	s_add_i32 s56, s56, 2
	s_add_u32 s46, s46, 0x100
	s_addc_u32 s47, s47, 0
	s_cmpk_gt_u32 s56, 0x55
	s_mov_b64 s[22:23], s[24:25]
	s_cbranch_scc0 .LBB0_940
